# strategy 4: one static s_setprio 1 for waves 4-7 before each GEMM K-loop, per-segment flips removed
# speedup vs baseline: 1.0953x; 1.0037x over previous
; #define PG8_STAGEA(bufoff, gbase, voff) do { _Pragma("unroll") for (int _i = 0; _i < 2; ++_i) \
;         __builtin_amdgcn_global_load_lds((const unsigned*)((const char*)(gbase) + (voff)[_i]), (PG8_LAS unsigned*)(lds + (bufoff) + ldsw + _i * 8192), 16, 0, AUXA); } while (0)
; #define PG8_LDA(dst, b, h) do { _Pragma("unroll") for (int m = 0; m < 4; ++m) _Pragma("unroll") for (int k = 0; k < 2; ++k) dst[m][k] = *(const PG8_LAS bf16x8*)(lds + PG8_SA(b, h) + aoff + m * 2048 + k * 1024); } while (0)
; #define PG8_LDB(dst, b, h) do { _Pragma("unroll") for (int n = 0; n < 2; ++n) _Pragma("unroll") for (int k = 0; k < 2; ++k) dst[n][k] = *(const PG8_LAS bf16x8*)(lds + PG8_SB(b, h) + boff + n * 2048 + k * 1024); } while (0)
; #define PG8_MMA(ai, bj, At, Bt) do { __builtin_amdgcn_s_setprio(1); _Pragma("unroll") for (int m = 0; m < 4; ++m) _Pragma("unroll") for (int n = 0; n < 2; ++n) _Pragma("unroll") for (int k = 0; k < 2; ++k) \
;         acc[ai][bj][m][n] = __builtin_amdgcn_mfma_f32_16x16x32_bf16(Bt[n][k], At[m][k], acc[ai][bj][m][n], 0, 0, 0); __builtin_amdgcn_s_setprio(0); } while (0)
; #define PG8_WAIT_V(n) asm volatile("s_waitcnt vmcnt(" #n ")" ::: "memory")
; #define PG8_WAIT_L(n) asm volatile("s_waitcnt lgkmcnt(" #n ")" ::: "memory")
; #define PG8_BAR __builtin_amdgcn_s_barrier()
; #define PG8_SCHED __builtin_amdgcn_sched_barrier(0)
;     ...
;     f32x4 acc[2][2][4][2];
; #pragma unroll
;     for (int a = 0; a < 2; ++a)
; #pragma unroll
;         for (int b = 0; b < 2; ++b)
; #pragma unroll
;             for (int m = 0; m < 4; ++m)
; #pragma unroll
;                 for (int n = 0; n < 2; ++n) acc[a][b][m][n] = (f32x4){0.f, 0.f, 0.f, 0.f};
;     bf16x8 At[4][2], B0[2][2], B1[2][2];
;     const char* cA = (const char*)g.A + (size_t)cur.pm * tstep + (size_t)cur.k0 * (BK * 2); const char* cB = (const char*)g.Bt + (size_t)cur.pn * tstep + (size_t)cur.k0 * (BK * 2);
;     ...
;             PG8_LDB(B0, 0, 0); PG8_LDB(B1, 0, 1); PG8_SCHED; PG8_LDA(At, 0, 0); PG8_STAGEA(PG8_SA(1, 1), a1 + hstep, voffA);
;             PG8_WAIT_V(8); PG8_WAIT_L(0); PG8_BAR; PG8_MMA(0, 0, At, B0); PG8_MMA(0, 1, At, B1); PG8_BAR; PG8_SCHED;
.LBB0_118:
	s_ashr_i32 s29, s28, 31
	s_lshl_b64 s[30:31], s[28:29], 19
	s_add_u32 s30, s52, s30
	s_addc_u32 s31, s53, s31
	s_and_b64 s[34:35], s[0:1], exec
	s_cselect_b32 s5, s31, s9
	s_cselect_b32 s7, s30, s8
	s_ashr_i32 s27, s26, 31
	s_lshl_b64 s[34:35], s[26:27], 19
	s_add_u32 s34, s77, s34
	s_addc_u32 s35, s84, s35
	s_and_b64 s[38:39], s[0:1], exec
	s_cselect_b32 s27, s35, s37
	s_cselect_b32 s29, s34, s36
	s_add_u32 s8, s8, 0x40080
	s_addc_u32 s9, s9, 0
	s_add_u32 s58, s36, 0x100
	v_mov_b32_e32 v0, 0
	s_addc_u32 s59, s37, 0
	s_mov_b32 s78, -2
	v_mov_b32_e32 v1, v0
	v_mov_b32_e32 v2, v0
	v_mov_b32_e32 v3, v0
	v_mov_b32_e32 v4, v0
	v_mov_b32_e32 v5, v0
	v_mov_b32_e32 v6, v0
	v_mov_b32_e32 v7, v0
	v_mov_b32_e32 v16, v0
	v_mov_b32_e32 v17, v0
	v_mov_b32_e32 v18, v0
	v_mov_b32_e32 v19, v0
	v_mov_b32_e32 v20, v0
	v_mov_b32_e32 v21, v0
	v_mov_b32_e32 v22, v0
	v_mov_b32_e32 v23, v0
	v_mov_b32_e32 v32, v0
	v_mov_b32_e32 v33, v0
	v_mov_b32_e32 v34, v0
	v_mov_b32_e32 v35, v0
	v_mov_b32_e32 v36, v0
	v_mov_b32_e32 v37, v0
	v_mov_b32_e32 v38, v0
	v_mov_b32_e32 v39, v0
	v_mov_b32_e32 v56, v0
	v_mov_b32_e32 v57, v0
	v_mov_b32_e32 v58, v0
	v_mov_b32_e32 v59, v0
	v_mov_b32_e32 v60, v0
	v_mov_b32_e32 v61, v0
	v_mov_b32_e32 v62, v0
	v_mov_b32_e32 v63, v0
	v_mov_b32_e32 v8, v0
	v_mov_b32_e32 v9, v0
	v_mov_b32_e32 v10, v0
	v_mov_b32_e32 v11, v0
	v_mov_b32_e32 v12, v0
	v_mov_b32_e32 v13, v0
	v_mov_b32_e32 v14, v0
	v_mov_b32_e32 v15, v0
	v_mov_b32_e32 v24, v0
	v_mov_b32_e32 v25, v0
	v_mov_b32_e32 v26, v0
	v_mov_b32_e32 v27, v0
	v_mov_b32_e32 v28, v0
	v_mov_b32_e32 v29, v0
	v_mov_b32_e32 v30, v0
	v_mov_b32_e32 v31, v0
	v_mov_b32_e32 v40, v0
	v_mov_b32_e32 v41, v0
	v_mov_b32_e32 v42, v0
	v_mov_b32_e32 v43, v0
	v_mov_b32_e32 v44, v0
	v_mov_b32_e32 v45, v0
	v_mov_b32_e32 v46, v0
	v_mov_b32_e32 v47, v0
	v_mov_b32_e32 v64, v0
	v_mov_b32_e32 v65, v0
	v_mov_b32_e32 v66, v0
	v_mov_b32_e32 v67, v0
	v_mov_b32_e32 v68, v0
	v_mov_b32_e32 v69, v0
	v_mov_b32_e32 v70, v0
	v_mov_b32_e32 v71, v0
	v_mov_b32_e32 v80, v0
	v_mov_b32_e32 v81, v0
	v_mov_b32_e32 v82, v0
	v_mov_b32_e32 v83, v0
	v_mov_b32_e32 v84, v0
	v_mov_b32_e32 v85, v0
	v_mov_b32_e32 v86, v0
	v_mov_b32_e32 v87, v0
	v_mov_b32_e32 v96, v0
	v_mov_b32_e32 v97, v0
	v_mov_b32_e32 v98, v0
	v_mov_b32_e32 v99, v0
	v_mov_b32_e32 v100, v0
	v_mov_b32_e32 v101, v0
	v_mov_b32_e32 v102, v0
	v_mov_b32_e32 v103, v0
	v_mov_b32_e32 v112, v0
	v_mov_b32_e32 v113, v0
	v_mov_b32_e32 v114, v0
	v_mov_b32_e32 v115, v0
	v_mov_b32_e32 v116, v0
	v_mov_b32_e32 v117, v0
	v_mov_b32_e32 v118, v0
	v_mov_b32_e32 v119, v0
	v_mov_b32_e32 v48, v0
	v_mov_b32_e32 v49, v0
	v_mov_b32_e32 v50, v0
	v_mov_b32_e32 v51, v0
	v_mov_b32_e32 v52, v0
	v_mov_b32_e32 v53, v0
	v_mov_b32_e32 v54, v0
	v_mov_b32_e32 v55, v0
	v_mov_b32_e32 v88, v0
	v_mov_b32_e32 v89, v0
	v_mov_b32_e32 v90, v0
	v_mov_b32_e32 v91, v0
	v_mov_b32_e32 v92, v0
	v_mov_b32_e32 v93, v0
	v_mov_b32_e32 v94, v0
	v_mov_b32_e32 v95, v0
	v_mov_b32_e32 v104, v0
	v_mov_b32_e32 v105, v0
	v_mov_b32_e32 v106, v0
	v_mov_b32_e32 v107, v0
	v_mov_b32_e32 v108, v0
	v_mov_b32_e32 v109, v0
	v_mov_b32_e32 v110, v0
	v_mov_b32_e32 v111, v0
	v_mov_b32_e32 v120, v0
	v_mov_b32_e32 v121, v0
	v_mov_b32_e32 v122, v0
	v_mov_b32_e32 v123, v0
	v_mov_b32_e32 v124, v0
	v_mov_b32_e32 v125, v0
	v_mov_b32_e32 v126, v0
	v_mov_b32_e32 v127, v0
	v_mov_b32_e32 v72, v0
	v_mov_b32_e32 v73, v0
	v_mov_b32_e32 v74, v0
	v_mov_b32_e32 v75, v0
	v_mov_b32_e32 v76, v0
	v_mov_b32_e32 v77, v0
	v_mov_b32_e32 v78, v0
	v_mov_b32_e32 v79, v0
	v_readlane_b32 s98, v255, 17
	s_cmp_lg_u32 s98, 1
	s_cbranch_scc1 .Lsprio_0
	s_setprio 1
.Lsprio_0:
.LBB0_119:
	ds_read_b128 v[128:131], v229
	ds_read_b128 v[132:135], v229 offset:1024
	ds_read_b128 v[136:139], v229 offset:2048
	ds_read_b128 v[140:143], v229 offset:3072
	ds_read_b128 v[176:179], v230
	ds_read_b128 v[180:183], v230 offset:1024
	ds_read_b128 v[184:187], v230 offset:2048
	ds_read_b128 v[188:191], v230 offset:3072
	s_add_u32 s36, s8, 0xfffc0080
	s_addc_u32 s37, s9, -1
	s_cmp_eq_u32 s78, 12
	s_cselect_b32 s39, s5, s37
	s_cselect_b32 s38, s7, s36
	s_cselect_b32 s37, s27, s59
	s_cselect_b32 s36, s29, s58
	v_lshl_add_u64 v[172:173], s[8:9], 0, v[164:165]
	s_add_i32 m0, s85, 0xc000
	ds_read_b128 v[192:195], v231
	ds_read_b128 v[196:199], v231 offset:1024
	ds_read_b128 v[238:241], v231 offset:2048
	ds_read_b128 v[242:245], v231 offset:3072
	ds_read_b128 v[246:249], v231 offset:4096
	ds_read_b128 v[250:253], v231 offset:5120
	ds_read_b128 v[210:213], v231 offset:6144
	ds_read_b128 v[214:217], v231 offset:7168
	global_load_lds_dwordx4 v[172:173], off
	v_lshl_add_u64 v[172:173], s[8:9], 0, v[166:167]
	s_add_i32 m0, s85, 0xe000
	s_nop 0
	global_load_lds_dwordx4 v[172:173], off
	s_waitcnt vmcnt(8)
	s_waitcnt lgkmcnt(0)
	s_barrier
; #define PG8_STAGE(bufoff, gbase, voff) do { _Pragma("unroll") for (int _i = 0; _i < 2; ++_i) \
;         __builtin_amdgcn_global_load_lds((const unsigned*)((const char*)(gbase) + (voff)[_i]), (PG8_LAS unsigned*)(lds + (bufoff) + ldsw + _i * 8192), 16, 0, 0); } while (0)
; #define PG8_STAGEA(bufoff, gbase, voff) do { _Pragma("unroll") for (int _i = 0; _i < 2; ++_i) \
;         __builtin_amdgcn_global_load_lds((const unsigned*)((const char*)(gbase) + (voff)[_i]), (PG8_LAS unsigned*)(lds + (bufoff) + ldsw + _i * 8192), 16, 0, AUXA); } while (0)
; #define PG8_LDA(dst, b, h) do { _Pragma("unroll") for (int m = 0; m < 4; ++m) _Pragma("unroll") for (int k = 0; k < 2; ++k) dst[m][k] = *(const PG8_LAS bf16x8*)(lds + PG8_SA(b, h) + aoff + m * 2048 + k * 1024); } while (0)
; #define PG8_MMA(ai, bj, At, Bt) do { __builtin_amdgcn_s_setprio(1); _Pragma("unroll") for (int m = 0; m < 4; ++m) _Pragma("unroll") for (int n = 0; n < 2; ++n) _Pragma("unroll") for (int k = 0; k < 2; ++k) \
;         acc[ai][bj][m][n] = __builtin_amdgcn_mfma_f32_16x16x32_bf16(Bt[n][k], At[m][k], acc[ai][bj][m][n], 0, 0, 0); __builtin_amdgcn_s_setprio(0); } while (0)
; #define PG8_WAIT_V(n) asm volatile("s_waitcnt vmcnt(" #n ")" ::: "memory")
; #define PG8_WAIT_L(n) asm volatile("s_waitcnt lgkmcnt(" #n ")" ::: "memory")
; #define PG8_BAR __builtin_amdgcn_s_barrier()
; #define PG8_SCHED __builtin_amdgcn_sched_barrier(0)
;     ...
;             PG8_WAIT_V(8); PG8_WAIT_L(0); PG8_BAR; PG8_MMA(0, 0, At, B0); PG8_MMA(0, 1, At, B1); PG8_BAR; PG8_SCHED;
;             PG8_LDA(At, 0, 1); PG8_STAGE(PG8_SB(0, 0), b2, voffB); PG8_STAGE(PG8_SB(0, 1), b2 + hstepB, voffB); PG8_STAGEA(PG8_SA(0, 0), a2, voffA);
;             PG8_WAIT_V(8); PG8_WAIT_L(0); PG8_BAR; PG8_MMA(1, 0, At, B0); PG8_MMA(1, 1, At, B1); PG8_BAR; PG8_SCHED;
	s_waitcnt lgkmcnt(0)
	v_mfma_f32_16x16x32_bf16 v[76:79], v[128:131], v[192:195], v[76:79]
	v_mfma_f32_16x16x32_bf16 v[72:75], v[136:139], v[192:195], v[72:75]
	v_mfma_f32_16x16x32_bf16 v[124:127], v[128:131], v[238:241], v[124:127]
	v_mfma_f32_16x16x32_bf16 v[120:123], v[136:139], v[238:241], v[120:123]
	v_mfma_f32_16x16x32_bf16 v[108:111], v[128:131], v[246:249], v[108:111]
	v_mfma_f32_16x16x32_bf16 v[104:107], v[136:139], v[246:249], v[104:107]
	v_mfma_f32_16x16x32_bf16 v[92:95], v[128:131], v[210:213], v[92:95]
	v_mfma_f32_16x16x32_bf16 v[88:91], v[136:139], v[210:213], v[88:91]
	v_mfma_f32_16x16x32_bf16 v[76:79], v[132:135], v[196:199], v[76:79]
	v_mfma_f32_16x16x32_bf16 v[72:75], v[140:143], v[196:199], v[72:75]
	v_mfma_f32_16x16x32_bf16 v[124:127], v[132:135], v[242:245], v[124:127]
	v_mfma_f32_16x16x32_bf16 v[120:123], v[140:143], v[242:245], v[120:123]
	v_mfma_f32_16x16x32_bf16 v[108:111], v[132:135], v[250:253], v[108:111]
	v_mfma_f32_16x16x32_bf16 v[104:107], v[140:143], v[250:253], v[104:107]
	v_mfma_f32_16x16x32_bf16 v[92:95], v[132:135], v[214:217], v[92:95]
	v_mfma_f32_16x16x32_bf16 v[88:91], v[140:143], v[214:217], v[88:91]
	v_mfma_f32_16x16x32_bf16 v[52:55], v[176:179], v[192:195], v[52:55]
	v_mfma_f32_16x16x32_bf16 v[48:51], v[184:187], v[192:195], v[48:51]
	v_mfma_f32_16x16x32_bf16 v[116:119], v[176:179], v[238:241], v[116:119]
	v_mfma_f32_16x16x32_bf16 v[112:115], v[184:187], v[238:241], v[112:115]
	v_mfma_f32_16x16x32_bf16 v[100:103], v[176:179], v[246:249], v[100:103]
	v_mfma_f32_16x16x32_bf16 v[96:99], v[184:187], v[246:249], v[96:99]
	v_mfma_f32_16x16x32_bf16 v[84:87], v[176:179], v[210:213], v[84:87]
	v_mfma_f32_16x16x32_bf16 v[80:83], v[184:187], v[210:213], v[80:83]
	v_mfma_f32_16x16x32_bf16 v[52:55], v[180:183], v[196:199], v[52:55]
	v_mfma_f32_16x16x32_bf16 v[48:51], v[188:191], v[196:199], v[48:51]
	v_mfma_f32_16x16x32_bf16 v[116:119], v[180:183], v[242:245], v[116:119]
	v_mfma_f32_16x16x32_bf16 v[112:115], v[188:191], v[242:245], v[112:115]
	v_mfma_f32_16x16x32_bf16 v[100:103], v[180:183], v[250:253], v[100:103]
	v_mfma_f32_16x16x32_bf16 v[96:99], v[188:191], v[250:253], v[96:99]
	v_mfma_f32_16x16x32_bf16 v[84:87], v[180:183], v[214:217], v[84:87]
	v_mfma_f32_16x16x32_bf16 v[80:83], v[188:191], v[214:217], v[80:83]
	s_barrier
	s_add_i32 s79, s73, s67
	v_lshl_add_u64 v[172:173], s[36:37], 0, v[146:147]
	s_mov_b32 m0, s79
	ds_read_b128 v[192:195], v231 offset:16384
	ds_read_b128 v[196:199], v231 offset:17408
	ds_read_b128 v[210:213], v231 offset:18432
	ds_read_b128 v[214:217], v231 offset:19456
	ds_read_b128 v[238:241], v231 offset:20480
	ds_read_b128 v[242:245], v231 offset:21504
	ds_read_b128 v[246:249], v231 offset:22528
	ds_read_b128 v[250:253], v231 offset:23552
	global_load_lds_dwordx4 v[172:173], off
	s_add_i32 m0, s79, 0x2000
	s_add_u32 s80, s36, 0x10000
	v_lshl_add_u64 v[202:203], s[36:37], 0, v[150:151]
	s_addc_u32 s81, s37, 0
	s_add_i32 s79, s46, s67
	global_load_lds_dwordx4 v[202:203], off
	v_lshl_add_u64 v[204:205], s[80:81], 0, v[146:147]
	s_mov_b32 m0, s79
	v_lshl_add_u64 v[206:207], s[38:39], 0, v[148:149]
	global_load_lds_dwordx4 v[204:205], off
	v_lshl_add_u64 v[204:205], s[80:81], 0, v[150:151]
	s_add_i32 m0, s79, 0x2000
	s_nop 0
	global_load_lds_dwordx4 v[204:205], off
	v_lshl_add_u64 v[204:205], s[38:39], 0, v[144:145]
	s_mov_b32 m0, s85
	s_nop 0
	global_load_lds_dwordx4 v[204:205], off
	s_mov_b32 m0, s86
	s_nop 0
	global_load_lds_dwordx4 v[206:207], off
	s_waitcnt vmcnt(8)
	s_waitcnt lgkmcnt(0)
	s_barrier
	s_waitcnt lgkmcnt(0)
	v_mfma_f32_16x16x32_bf16 v[68:71], v[128:131], v[192:195], v[68:71]
	v_mfma_f32_16x16x32_bf16 v[64:67], v[136:139], v[192:195], v[64:67]
	v_mfma_f32_16x16x32_bf16 v[44:47], v[128:131], v[210:213], v[44:47]
	v_mfma_f32_16x16x32_bf16 v[40:43], v[136:139], v[210:213], v[40:43]
	v_mfma_f32_16x16x32_bf16 v[28:31], v[128:131], v[238:241], v[28:31]
	v_mfma_f32_16x16x32_bf16 v[24:27], v[136:139], v[238:241], v[24:27]
	v_mfma_f32_16x16x32_bf16 v[12:15], v[128:131], v[246:249], v[12:15]
	v_mfma_f32_16x16x32_bf16 v[8:11], v[136:139], v[246:249], v[8:11]
	v_mfma_f32_16x16x32_bf16 v[68:71], v[132:135], v[196:199], v[68:71]
	v_mfma_f32_16x16x32_bf16 v[64:67], v[140:143], v[196:199], v[64:67]
	v_mfma_f32_16x16x32_bf16 v[44:47], v[132:135], v[214:217], v[44:47]
	v_mfma_f32_16x16x32_bf16 v[40:43], v[140:143], v[214:217], v[40:43]
	v_mfma_f32_16x16x32_bf16 v[28:31], v[132:135], v[242:245], v[28:31]
	v_mfma_f32_16x16x32_bf16 v[24:27], v[140:143], v[242:245], v[24:27]
	v_mfma_f32_16x16x32_bf16 v[12:15], v[132:135], v[250:253], v[12:15]
	v_mfma_f32_16x16x32_bf16 v[8:11], v[140:143], v[250:253], v[8:11]
	v_mfma_f32_16x16x32_bf16 v[60:63], v[176:179], v[192:195], v[60:63]
	v_mfma_f32_16x16x32_bf16 v[56:59], v[184:187], v[192:195], v[56:59]
	v_mfma_f32_16x16x32_bf16 v[36:39], v[176:179], v[210:213], v[36:39]
	v_mfma_f32_16x16x32_bf16 v[32:35], v[184:187], v[210:213], v[32:35]
	v_mfma_f32_16x16x32_bf16 v[20:23], v[176:179], v[238:241], v[20:23]
	v_mfma_f32_16x16x32_bf16 v[16:19], v[184:187], v[238:241], v[16:19]
	v_mfma_f32_16x16x32_bf16 v[4:7], v[176:179], v[246:249], v[4:7]
	v_mfma_f32_16x16x32_bf16 v[0:3], v[184:187], v[246:249], v[0:3]
	v_mfma_f32_16x16x32_bf16 v[60:63], v[180:183], v[196:199], v[60:63]
	v_mfma_f32_16x16x32_bf16 v[56:59], v[188:191], v[196:199], v[56:59]
	v_mfma_f32_16x16x32_bf16 v[36:39], v[180:183], v[214:217], v[36:39]
	v_mfma_f32_16x16x32_bf16 v[32:35], v[188:191], v[214:217], v[32:35]
	v_mfma_f32_16x16x32_bf16 v[20:23], v[180:183], v[242:245], v[20:23]
	v_mfma_f32_16x16x32_bf16 v[16:19], v[188:191], v[242:245], v[16:19]
	v_mfma_f32_16x16x32_bf16 v[4:7], v[180:183], v[250:253], v[4:7]
	v_mfma_f32_16x16x32_bf16 v[0:3], v[188:191], v[250:253], v[0:3]
	s_barrier
; #define PG8_STAGEA(bufoff, gbase, voff) do { _Pragma("unroll") for (int _i = 0; _i < 2; ++_i) \
;         __builtin_amdgcn_global_load_lds((const unsigned*)((const char*)(gbase) + (voff)[_i]), (PG8_LAS unsigned*)(lds + (bufoff) + ldsw + _i * 8192), 16, 0, AUXA); } while (0)
; #define PG8_LDA(dst, b, h) do { _Pragma("unroll") for (int m = 0; m < 4; ++m) _Pragma("unroll") for (int k = 0; k < 2; ++k) dst[m][k] = *(const PG8_LAS bf16x8*)(lds + PG8_SA(b, h) + aoff + m * 2048 + k * 1024); } while (0)
; #define PG8_LDB(dst, b, h) do { _Pragma("unroll") for (int n = 0; n < 2; ++n) _Pragma("unroll") for (int k = 0; k < 2; ++k) dst[n][k] = *(const PG8_LAS bf16x8*)(lds + PG8_SB(b, h) + boff + n * 2048 + k * 1024); } while (0)
; #define PG8_MMA(ai, bj, At, Bt) do { __builtin_amdgcn_s_setprio(1); _Pragma("unroll") for (int m = 0; m < 4; ++m) _Pragma("unroll") for (int n = 0; n < 2; ++n) _Pragma("unroll") for (int k = 0; k < 2; ++k) \
;         acc[ai][bj][m][n] = __builtin_amdgcn_mfma_f32_16x16x32_bf16(Bt[n][k], At[m][k], acc[ai][bj][m][n], 0, 0, 0); __builtin_amdgcn_s_setprio(0); } while (0)
; #define PG8_WAIT_V(n) asm volatile("s_waitcnt vmcnt(" #n ")" ::: "memory")
; #define PG8_WAIT_L(n) asm volatile("s_waitcnt lgkmcnt(" #n ")" ::: "memory")
; #define PG8_BAR __builtin_amdgcn_s_barrier()
; #define PG8_SCHED __builtin_amdgcn_sched_barrier(0)
;     ...
;             PG8_LDB(B0, 1, 0); PG8_LDB(B1, 1, 1); PG8_SCHED; PG8_LDA(At, 1, 0); PG8_STAGEA(PG8_SA(0, 1), a2 + hstep, voffA);
;             PG8_WAIT_V(8); PG8_WAIT_L(0); PG8_BAR; PG8_MMA(0, 0, At, B0); PG8_MMA(0, 1, At, B1); PG8_BAR; PG8_SCHED;
	s_add_i32 s79, 0, 0x18000
	s_add_i32 s80, 0, 0x1c000
	v_add_u32_e32 v140, s79, v226
	v_add_u32_e32 v152, s80, v226
	ds_read_b128 v[128:131], v140
	ds_read_b128 v[132:135], v140 offset:1024
	ds_read_b128 v[136:139], v140 offset:2048
	ds_read_b128 v[140:143], v140 offset:3072
	ds_read_b128 v[176:179], v152
	ds_read_b128 v[180:183], v152 offset:1024
	ds_read_b128 v[184:187], v152 offset:2048
	ds_read_b128 v[188:191], v152 offset:3072
	s_add_u32 s38, s38, 0x40000
	s_addc_u32 s39, s39, 0
	s_mov_b32 m0, s87
	v_lshl_add_u64 v[218:219], s[38:39], 0, v[144:145]
	ds_read_b128 v[192:195], v231 offset:32768
	ds_read_b128 v[196:199], v231 offset:33792
	ds_read_b128 v[210:213], v231 offset:34816
	ds_read_b128 v[214:217], v231 offset:35840
	ds_read_b128 v[238:241], v231 offset:36864
	ds_read_b128 v[242:245], v231 offset:37888
	ds_read_b128 v[246:249], v231 offset:38912
	ds_read_b128 v[250:253], v231 offset:39936
	global_load_lds_dwordx4 v[218:219], off
	v_lshl_add_u64 v[218:219], s[38:39], 0, v[148:149]
	s_mov_b32 m0, s88
	s_nop 0
	global_load_lds_dwordx4 v[218:219], off
	s_waitcnt vmcnt(8)
	s_waitcnt lgkmcnt(0)
	s_barrier
	s_waitcnt lgkmcnt(0)
	v_mfma_f32_16x16x32_bf16 v[76:79], v[128:131], v[192:195], v[76:79]
	v_mfma_f32_16x16x32_bf16 v[72:75], v[136:139], v[192:195], v[72:75]
	v_mfma_f32_16x16x32_bf16 v[124:127], v[128:131], v[210:213], v[124:127]
	v_mfma_f32_16x16x32_bf16 v[120:123], v[136:139], v[210:213], v[120:123]
	v_mfma_f32_16x16x32_bf16 v[108:111], v[128:131], v[238:241], v[108:111]
	v_mfma_f32_16x16x32_bf16 v[104:107], v[136:139], v[238:241], v[104:107]
	v_mfma_f32_16x16x32_bf16 v[92:95], v[128:131], v[246:249], v[92:95]
	v_mfma_f32_16x16x32_bf16 v[88:91], v[136:139], v[246:249], v[88:91]
	v_mfma_f32_16x16x32_bf16 v[76:79], v[132:135], v[196:199], v[76:79]
	v_mfma_f32_16x16x32_bf16 v[72:75], v[140:143], v[196:199], v[72:75]
	v_mfma_f32_16x16x32_bf16 v[124:127], v[132:135], v[214:217], v[124:127]
	v_mfma_f32_16x16x32_bf16 v[120:123], v[140:143], v[214:217], v[120:123]
	v_mfma_f32_16x16x32_bf16 v[108:111], v[132:135], v[242:245], v[108:111]
	v_mfma_f32_16x16x32_bf16 v[104:107], v[140:143], v[242:245], v[104:107]
	v_mfma_f32_16x16x32_bf16 v[92:95], v[132:135], v[250:253], v[92:95]
	v_mfma_f32_16x16x32_bf16 v[88:91], v[140:143], v[250:253], v[88:91]
	v_mfma_f32_16x16x32_bf16 v[52:55], v[176:179], v[192:195], v[52:55]
	v_mfma_f32_16x16x32_bf16 v[48:51], v[184:187], v[192:195], v[48:51]
	v_mfma_f32_16x16x32_bf16 v[116:119], v[176:179], v[210:213], v[116:119]
	v_mfma_f32_16x16x32_bf16 v[112:115], v[184:187], v[210:213], v[112:115]
	v_mfma_f32_16x16x32_bf16 v[100:103], v[176:179], v[238:241], v[100:103]
	v_mfma_f32_16x16x32_bf16 v[96:99], v[184:187], v[238:241], v[96:99]
	v_mfma_f32_16x16x32_bf16 v[84:87], v[176:179], v[246:249], v[84:87]
	v_mfma_f32_16x16x32_bf16 v[80:83], v[184:187], v[246:249], v[80:83]
	v_mfma_f32_16x16x32_bf16 v[52:55], v[180:183], v[196:199], v[52:55]
	v_mfma_f32_16x16x32_bf16 v[48:51], v[188:191], v[196:199], v[48:51]
	v_mfma_f32_16x16x32_bf16 v[116:119], v[180:183], v[214:217], v[116:119]
	v_mfma_f32_16x16x32_bf16 v[112:115], v[188:191], v[214:217], v[112:115]
	v_mfma_f32_16x16x32_bf16 v[100:103], v[180:183], v[242:245], v[100:103]
	v_mfma_f32_16x16x32_bf16 v[96:99], v[188:191], v[242:245], v[96:99]
	v_mfma_f32_16x16x32_bf16 v[84:87], v[180:183], v[250:253], v[84:87]
	v_mfma_f32_16x16x32_bf16 v[80:83], v[188:191], v[250:253], v[80:83]
	s_barrier
; #define PG8_STAGE(bufoff, gbase, voff) do { _Pragma("unroll") for (int _i = 0; _i < 2; ++_i) \
;         __builtin_amdgcn_global_load_lds((const unsigned*)((const char*)(gbase) + (voff)[_i]), (PG8_LAS unsigned*)(lds + (bufoff) + ldsw + _i * 8192), 16, 0, 0); } while (0)
; #define PG8_STAGEA(bufoff, gbase, voff) do { _Pragma("unroll") for (int _i = 0; _i < 2; ++_i) \
;         __builtin_amdgcn_global_load_lds((const unsigned*)((const char*)(gbase) + (voff)[_i]), (PG8_LAS unsigned*)(lds + (bufoff) + ldsw + _i * 8192), 16, 0, AUXA); } while (0)
; #define PG8_LDA(dst, b, h) do { _Pragma("unroll") for (int m = 0; m < 4; ++m) _Pragma("unroll") for (int k = 0; k < 2; ++k) dst[m][k] = *(const PG8_LAS bf16x8*)(lds + PG8_SA(b, h) + aoff + m * 2048 + k * 1024); } while (0)
; #define PG8_MMA(ai, bj, At, Bt) do { __builtin_amdgcn_s_setprio(1); _Pragma("unroll") for (int m = 0; m < 4; ++m) _Pragma("unroll") for (int n = 0; n < 2; ++n) _Pragma("unroll") for (int k = 0; k < 2; ++k) \
;         acc[ai][bj][m][n] = __builtin_amdgcn_mfma_f32_16x16x32_bf16(Bt[n][k], At[m][k], acc[ai][bj][m][n], 0, 0, 0); __builtin_amdgcn_s_setprio(0); } while (0)
; #define PG8_WAIT_V(n) asm volatile("s_waitcnt vmcnt(" #n ")" ::: "memory")
; #define PG8_WAIT_L(n) asm volatile("s_waitcnt lgkmcnt(" #n ")" ::: "memory")
; #define PG8_BAR __builtin_amdgcn_s_barrier()
; #define PG8_SCHED __builtin_amdgcn_sched_barrier(0)
;     ...
;         for (int t = 0; t < nt; t += 2) {
;     ...
;             PG8_LDA(At, 1, 1); PG8_STAGE(PG8_SB(1, 0), b3, voffB); PG8_STAGE(PG8_SB(1, 1), b3 + hstepB, voffB); PG8_STAGEA(PG8_SA(1, 0), a3, voffA);
;             PG8_WAIT_V(8); PG8_WAIT_L(0); PG8_BAR; PG8_MMA(1, 0, At, B0); PG8_MMA(1, 1, At, B1); PG8_BAR; PG8_SCHED;
	s_add_i32 s38, s79, s67
	v_lshl_add_u64 v[172:173], v[172:173], 0, s[16:17]
	s_mov_b32 m0, s38
	ds_read_b128 v[192:195], v231 offset:49152
	ds_read_b128 v[196:199], v231 offset:50176
	ds_read_b128 v[210:213], v231 offset:51200
	ds_read_b128 v[214:217], v231 offset:52224
	ds_read_b128 v[238:241], v231 offset:53248
	ds_read_b128 v[242:245], v231 offset:54272
	ds_read_b128 v[246:249], v231 offset:55296
	ds_read_b128 v[250:253], v231 offset:56320
	global_load_lds_dwordx4 v[172:173], off
	s_add_i32 m0, s38, 0x2000
	s_add_u32 s36, s36, 0x10080
	v_lshl_add_u64 v[172:173], v[202:203], 0, s[16:17]
	s_addc_u32 s37, s37, 0
	s_add_i32 s38, s80, s67
	global_load_lds_dwordx4 v[172:173], off
	v_lshl_add_u64 v[172:173], s[36:37], 0, v[146:147]
	s_mov_b32 m0, s38
	s_nop 0
	global_load_lds_dwordx4 v[172:173], off
	v_lshl_add_u64 v[172:173], s[36:37], 0, v[150:151]
	s_add_i32 m0, s38, 0x2000
	s_nop 0
	global_load_lds_dwordx4 v[172:173], off
	v_lshl_add_u64 v[172:173], v[204:205], 0, s[16:17]
	s_mov_b32 m0, s89
	s_nop 0
	global_load_lds_dwordx4 v[172:173], off
	v_lshl_add_u64 v[172:173], v[206:207], 0, s[16:17]
	s_mov_b32 m0, s90
	s_nop 0
	global_load_lds_dwordx4 v[172:173], off
	s_waitcnt vmcnt(8)
	s_waitcnt lgkmcnt(0)
	s_barrier
	s_waitcnt lgkmcnt(0)
	v_mfma_f32_16x16x32_bf16 v[68:71], v[128:131], v[192:195], v[68:71]
	v_mfma_f32_16x16x32_bf16 v[64:67], v[136:139], v[192:195], v[64:67]
	v_mfma_f32_16x16x32_bf16 v[44:47], v[128:131], v[210:213], v[44:47]
	v_mfma_f32_16x16x32_bf16 v[40:43], v[136:139], v[210:213], v[40:43]
	v_mfma_f32_16x16x32_bf16 v[28:31], v[128:131], v[238:241], v[28:31]
	v_mfma_f32_16x16x32_bf16 v[24:27], v[136:139], v[238:241], v[24:27]
	v_mfma_f32_16x16x32_bf16 v[12:15], v[128:131], v[246:249], v[12:15]
	v_mfma_f32_16x16x32_bf16 v[8:11], v[136:139], v[246:249], v[8:11]
	v_mfma_f32_16x16x32_bf16 v[68:71], v[132:135], v[196:199], v[68:71]
	v_mfma_f32_16x16x32_bf16 v[64:67], v[140:143], v[196:199], v[64:67]
	v_mfma_f32_16x16x32_bf16 v[44:47], v[132:135], v[214:217], v[44:47]
	v_mfma_f32_16x16x32_bf16 v[40:43], v[140:143], v[214:217], v[40:43]
	v_mfma_f32_16x16x32_bf16 v[28:31], v[132:135], v[242:245], v[28:31]
	v_mfma_f32_16x16x32_bf16 v[24:27], v[140:143], v[242:245], v[24:27]
	v_mfma_f32_16x16x32_bf16 v[12:15], v[132:135], v[250:253], v[12:15]
	v_mfma_f32_16x16x32_bf16 v[8:11], v[140:143], v[250:253], v[8:11]
	v_mfma_f32_16x16x32_bf16 v[60:63], v[176:179], v[192:195], v[60:63]
	v_mfma_f32_16x16x32_bf16 v[56:59], v[184:187], v[192:195], v[56:59]
	v_mfma_f32_16x16x32_bf16 v[36:39], v[176:179], v[210:213], v[36:39]
	v_mfma_f32_16x16x32_bf16 v[32:35], v[184:187], v[210:213], v[32:35]
	v_mfma_f32_16x16x32_bf16 v[20:23], v[176:179], v[238:241], v[20:23]
	v_mfma_f32_16x16x32_bf16 v[16:19], v[184:187], v[238:241], v[16:19]
	v_mfma_f32_16x16x32_bf16 v[4:7], v[176:179], v[246:249], v[4:7]
	v_mfma_f32_16x16x32_bf16 v[0:3], v[184:187], v[246:249], v[0:3]
	v_mfma_f32_16x16x32_bf16 v[60:63], v[180:183], v[196:199], v[60:63]
	v_mfma_f32_16x16x32_bf16 v[56:59], v[188:191], v[196:199], v[56:59]
	v_mfma_f32_16x16x32_bf16 v[36:39], v[180:183], v[214:217], v[36:39]
	v_mfma_f32_16x16x32_bf16 v[32:35], v[188:191], v[214:217], v[32:35]
	v_mfma_f32_16x16x32_bf16 v[20:23], v[180:183], v[242:245], v[20:23]
	v_mfma_f32_16x16x32_bf16 v[16:19], v[188:191], v[242:245], v[16:19]
	v_mfma_f32_16x16x32_bf16 v[4:7], v[180:183], v[250:253], v[4:7]
	v_mfma_f32_16x16x32_bf16 v[0:3], v[188:191], v[250:253], v[0:3]
	s_barrier
	s_add_i32 s78, s78, 2
	s_add_u32 s8, s8, 0x100
	s_addc_u32 s9, s9, 0
	s_add_u32 s58, s58, 0x100
	s_addc_u32 s59, s59, 0
	s_cmp_gt_u32 s78, 13
	s_cbranch_scc0 .LBB0_119
	s_setprio 0
	s_and_b64 vcc, exec, s[18:19]
	s_cbranch_vccz .LBB0_122
	s_barrier

; #define PG8_STAGE(bufoff, gbase, voff) do { _Pragma("unroll") for (int _i = 0; _i < 2; ++_i) \
;         __builtin_amdgcn_global_load_lds((const unsigned*)((const char*)(gbase) + (voff)[_i]), (PG8_LAS unsigned*)(lds + (bufoff) + ldsw + _i * 8192), 16, 0, 0); } while (0)
; #define PG8_STAGEA(bufoff, gbase, voff) do { _Pragma("unroll") for (int _i = 0; _i < 2; ++_i) \
;         __builtin_amdgcn_global_load_lds((const unsigned*)((const char*)(gbase) + (voff)[_i]), (PG8_LAS unsigned*)(lds + (bufoff) + ldsw + _i * 8192), 16, 0, AUXA); } while (0)
; #define PG8_WAIT_V(n) asm volatile("s_waitcnt vmcnt(" #n ")" ::: "memory")
; #define PG8_BAR __builtin_amdgcn_s_barrier()
;     ...
;     f32x4 acc[2][2][4][2];
; #pragma unroll
;     for (int a = 0; a < 2; ++a)
; #pragma unroll
;         for (int b = 0; b < 2; ++b)
; #pragma unroll
;             for (int m = 0; m < 4; ++m)
; #pragma unroll
;                 for (int n = 0; n < 2; ++n) acc[a][b][m][n] = (f32x4){0.f, 0.f, 0.f, 0.f};
;     bf16x8 At[4][2], B0[2][2], B1[2][2];
;     const char* cA = (const char*)g.A + (size_t)cur.pm * tstep + (size_t)cur.k0 * (BK * 2); const char* cB = (const char*)g.Bt + (size_t)cur.pn * tstep + (size_t)cur.k0 * (BK * 2);
;     S.a_ready(cur);
;     if constexpr (SP2) {
;         PG8_STAGE(PG8_SB(0, 0), cB, voffB); PG8_STAGE(PG8_SB(0, 1), cB + hstepB, voffB); PG8_STAGEA(PG8_SA(0, 0), cA, voffA); PG8_STAGEA(PG8_SA(0, 1), cA + hstep, voffA);
;         if (wr == 1) PG8_BAR;
;         PG8_WAIT_V(2); PG8_BAR;
;         PG8_STAGE(PG8_SB(1, 0), cB + kstep, voffB); PG8_STAGEA(PG8_SA(1, 0), cA + kstep, voffA); PG8_STAGE(PG8_SB(1, 1), cB + hstepB + kstep, voffB);
;         PG8_WAIT_V(6); PG8_BAR;
.LBB0_443:
	v_and_b32_e32 v14, 15, v141
	v_or_b32_e32 v140, s72, v14
	v_lshlrev_b32_e32 v15, 6, v140
	v_and_b32_e32 v16, 48, v141
	s_movk_i32 s10, 0x3c0
	v_lshlrev_b32_e32 v17, 2, v140
	v_and_or_b32 v15, v15, s10, v16
	v_and_b32_e32 v17, 32, v17
	v_readlane_b32 s10, v255, 18
	v_lshl_or_b32 v14, v14, 6, v16
	v_lshlrev_b32_e32 v16, 2, v141
	v_bitop3_b32 v15, v15, s10, v17 bitop3:0xde
	v_and_b32_e32 v16, 32, v16
	v_readlane_b32 s10, v255, 19
	s_add_i32 m0, s1, 0x18000
	s_waitcnt vmcnt(2)
	s_barrier
	v_bitop3_b32 v14, v14, s10, v16 bitop3:0xde
	s_mov_b64 s[10:11], 0x80
	v_lshl_add_u64 v[6:7], v[6:7], 0, s[10:11]
	global_load_lds_dwordx4 v[6:7], off
	v_lshl_add_u64 v[4:5], v[4:5], 0, s[10:11]
	s_add_i32 m0, s1, 0x1a000
	s_add_i32 s20, s1, 0x8000
	s_add_i32 s21, s1, 0xa000
	global_load_lds_dwordx4 v[4:5], off
	v_lshl_add_u64 v[0:1], v[0:1], 0, s[10:11]
	s_mov_b32 m0, s20
	s_add_u32 s14, s6, 0x10080
	global_load_lds_dwordx4 v[0:1], off
	v_lshl_add_u64 v[0:1], v[2:3], 0, s[10:11]
	s_mov_b32 m0, s21
	s_addc_u32 s15, s7, 0
	global_load_lds_dwordx4 v[0:1], off
	s_add_i32 m0, s1, 0x1c000
	v_lshl_add_u64 v[0:1], s[14:15], 0, v[132:133]
	global_load_lds_dwordx4 v[0:1], off
	v_lshl_add_u64 v[0:1], s[14:15], 0, v[128:129]
	s_add_i32 m0, s1, 0x1e000
	s_ashr_i32 s13, s12, 31
	global_load_lds_dwordx4 v[0:1], off
	v_lshlrev_b32_e32 v0, 14, v12
	v_and_b32_e32 v0, 0xffff8000, v0
	s_lshl_b64 s[12:13], s[12:13], 19
	v_lshl_add_u32 v0, v11, 11, v0
	v_and_b32_e32 v1, 1, v12
	v_lshl_or_b32 v0, v1, 6, v0
	s_add_u32 s12, s68, s12
	v_lshl_add_u32 v0, v13, 1, v0
	v_mov_b32_e32 v1, v133
	s_addc_u32 s13, s69, s13
	v_lshl_add_u64 v[136:137], s[12:13], 0, v[0:1]
	v_lshlrev_b32_e32 v0, 14, v8
	v_and_b32_e32 v0, 0xffff8000, v0
	v_lshl_add_u32 v0, v9, 11, v0
	v_and_b32_e32 v1, 1, v8
	s_waitcnt vmcnt(6)
	v_lshl_or_b32 v0, v1, 6, v0
	s_add_i32 s25, 0, 0x10000
	s_add_i32 s27, 0, 0x14000
	s_add_i32 s29, 0, 0x18000
	s_add_i32 s31, 0, 0x1c000
	v_lshl_add_u32 v0, v10, 1, v0
	v_mov_b32_e32 v1, v133
	v_add_u32_e32 v142, s25, v14
	v_add_u32_e32 v143, s27, v14
	s_add_i32 s25, s25, s67
	s_add_i32 s27, s27, s67
	v_add_u32_e32 v145, s29, v14
	v_add_u32_e32 v146, s31, v14
	s_add_i32 s29, s29, s67
	s_add_i32 s31, s31, s67
	v_lshl_add_u64 v[138:139], s[12:13], 0, v[0:1]
	s_mov_b32 s22, -2
	s_mov_b64 s[12:13], 0xda40080
	v_add_u32_e32 v144, 0, v15
	s_add_i32 s23, s1, 0xc000
	s_add_i32 s24, s1, 0xe000
	s_add_i32 s26, s25, 0x2000
	s_add_i32 s28, s27, 0x2000
	s_add_i32 s30, s29, 0x2000
	s_add_i32 s34, s31, 0x2000
	v_mov_b32_e32 v0, v133
	v_mov_b32_e32 v2, v133
	v_mov_b32_e32 v3, v133
	v_mov_b32_e32 v4, v133
	v_mov_b32_e32 v5, v133
	v_mov_b32_e32 v6, v133
	v_mov_b32_e32 v7, v133
	v_mov_b32_e32 v16, v133
	v_mov_b32_e32 v17, v133
	v_mov_b32_e32 v18, v133
	v_mov_b32_e32 v19, v133
	v_mov_b32_e32 v20, v133
	v_mov_b32_e32 v21, v133
	v_mov_b32_e32 v22, v133
	v_mov_b32_e32 v23, v133
	v_mov_b32_e32 v32, v133
	v_mov_b32_e32 v33, v133
	v_mov_b32_e32 v34, v133
	v_mov_b32_e32 v35, v133
	v_mov_b32_e32 v36, v133
	v_mov_b32_e32 v37, v133
	v_mov_b32_e32 v38, v133
	v_mov_b32_e32 v39, v133
	v_mov_b32_e32 v48, v133
	v_mov_b32_e32 v49, v133
	v_mov_b32_e32 v50, v133
	v_mov_b32_e32 v51, v133
	v_mov_b32_e32 v52, v133
	v_mov_b32_e32 v53, v133
	v_mov_b32_e32 v54, v133
	v_mov_b32_e32 v55, v133
	v_mov_b32_e32 v8, v133
	v_mov_b32_e32 v9, v133
	v_mov_b32_e32 v10, v133
	v_mov_b32_e32 v11, v133
	v_mov_b32_e32 v12, v133
	v_mov_b32_e32 v13, v133
	v_mov_b32_e32 v14, v133
	v_mov_b32_e32 v15, v133
	v_mov_b32_e32 v24, v133
	v_mov_b32_e32 v25, v133
	v_mov_b32_e32 v26, v133
	v_mov_b32_e32 v27, v133
	v_mov_b32_e32 v28, v133
	v_mov_b32_e32 v29, v133
	v_mov_b32_e32 v30, v133
	v_mov_b32_e32 v31, v133
	v_mov_b32_e32 v40, v133
	v_mov_b32_e32 v41, v133
	v_mov_b32_e32 v42, v133
	v_mov_b32_e32 v43, v133
	v_mov_b32_e32 v44, v133
	v_mov_b32_e32 v45, v133
	v_mov_b32_e32 v46, v133
	v_mov_b32_e32 v47, v133
	v_mov_b32_e32 v56, v133
	v_mov_b32_e32 v57, v133
	v_mov_b32_e32 v58, v133
	v_mov_b32_e32 v59, v133
	v_mov_b32_e32 v60, v133
	v_mov_b32_e32 v61, v133
	v_mov_b32_e32 v62, v133
	v_mov_b32_e32 v63, v133
	v_mov_b32_e32 v64, v133
	v_mov_b32_e32 v65, v133
	v_mov_b32_e32 v66, v133
	v_mov_b32_e32 v67, v133
	v_mov_b32_e32 v68, v133
	v_mov_b32_e32 v69, v133
	v_mov_b32_e32 v70, v133
	v_mov_b32_e32 v71, v133
	v_mov_b32_e32 v80, v133
	v_mov_b32_e32 v81, v133
	v_mov_b32_e32 v82, v133
	v_mov_b32_e32 v83, v133
	v_mov_b32_e32 v84, v133
	v_mov_b32_e32 v85, v133
	v_mov_b32_e32 v86, v133
	v_mov_b32_e32 v87, v133
	v_mov_b32_e32 v96, v133
	v_mov_b32_e32 v97, v133
	v_mov_b32_e32 v98, v133
	v_mov_b32_e32 v99, v133
	v_mov_b32_e32 v100, v133
	v_mov_b32_e32 v101, v133
	v_mov_b32_e32 v102, v133
	v_mov_b32_e32 v103, v133
	v_mov_b32_e32 v112, v133
	v_mov_b32_e32 v113, v133
	v_mov_b32_e32 v114, v133
	v_mov_b32_e32 v115, v133
	v_mov_b32_e32 v116, v133
	v_mov_b32_e32 v117, v133
	v_mov_b32_e32 v118, v133
	v_mov_b32_e32 v119, v133
	v_mov_b32_e32 v72, v133
	v_mov_b32_e32 v73, v133
	v_mov_b32_e32 v74, v133
	v_mov_b32_e32 v75, v133
	v_mov_b32_e32 v76, v133
	v_mov_b32_e32 v77, v133
	v_mov_b32_e32 v78, v133
	v_mov_b32_e32 v79, v133
	v_mov_b32_e32 v88, v133
	v_mov_b32_e32 v89, v133
	v_mov_b32_e32 v90, v133
	v_mov_b32_e32 v91, v133
	v_mov_b32_e32 v92, v133
	v_mov_b32_e32 v93, v133
	v_mov_b32_e32 v94, v133
	v_mov_b32_e32 v95, v133
	v_mov_b32_e32 v104, v133
	v_mov_b32_e32 v105, v133
	v_mov_b32_e32 v106, v133
	v_mov_b32_e32 v107, v133
	v_mov_b32_e32 v108, v133
	v_mov_b32_e32 v109, v133
	v_mov_b32_e32 v110, v133
	v_mov_b32_e32 v111, v133
	v_mov_b32_e32 v120, v133
	v_mov_b32_e32 v121, v133
	v_mov_b32_e32 v122, v133
	v_mov_b32_e32 v123, v133
	v_mov_b32_e32 v124, v133
	v_mov_b32_e32 v125, v133
	v_mov_b32_e32 v126, v133
	v_mov_b32_e32 v127, v133
	s_barrier
	v_readlane_b32 s98, v255, 17
	s_cmp_lg_u32 s98, 1
	s_cbranch_scc1 .Lsprio_1
	s_setprio 1
; #define PG8_STAGE(bufoff, gbase, voff) do { _Pragma("unroll") for (int _i = 0; _i < 2; ++_i) \
;         __builtin_amdgcn_global_load_lds((const unsigned*)((const char*)(gbase) + (voff)[_i]), (PG8_LAS unsigned*)(lds + (bufoff) + ldsw + _i * 8192), 16, 0, 0); } while (0)
; #define PG8_STAGEA(bufoff, gbase, voff) do { _Pragma("unroll") for (int _i = 0; _i < 2; ++_i) \
;         __builtin_amdgcn_global_load_lds((const unsigned*)((const char*)(gbase) + (voff)[_i]), (PG8_LAS unsigned*)(lds + (bufoff) + ldsw + _i * 8192), 16, 0, AUXA); } while (0)
; #define PG8_LDA(dst, b, h) do { _Pragma("unroll") for (int m = 0; m < 4; ++m) _Pragma("unroll") for (int k = 0; k < 2; ++k) dst[m][k] = *(const PG8_LAS bf16x8*)(lds + PG8_SA(b, h) + aoff + m * 2048 + k * 1024); } while (0)
; #define PG8_LDB(dst, b, h) do { _Pragma("unroll") for (int n = 0; n < 2; ++n) _Pragma("unroll") for (int k = 0; k < 2; ++k) dst[n][k] = *(const PG8_LAS bf16x8*)(lds + PG8_SB(b, h) + boff + n * 2048 + k * 1024); } while (0)
; #define PG8_MMA(ai, bj, At, Bt) do { __builtin_amdgcn_s_setprio(1); _Pragma("unroll") for (int m = 0; m < 4; ++m) _Pragma("unroll") for (int n = 0; n < 2; ++n) _Pragma("unroll") for (int k = 0; k < 2; ++k) \
;         acc[ai][bj][m][n] = __builtin_amdgcn_mfma_f32_16x16x32_bf16(Bt[n][k], At[m][k], acc[ai][bj][m][n], 0, 0, 0); __builtin_amdgcn_s_setprio(0); } while (0)
; #define PG8_WAIT_V(n) asm volatile("s_waitcnt vmcnt(" #n ")" ::: "memory")
; #define PG8_WAIT_L(n) asm volatile("s_waitcnt lgkmcnt(" #n ")" ::: "memory")
; #define PG8_BAR __builtin_amdgcn_s_barrier()
; #define PG8_SCHED __builtin_amdgcn_sched_barrier(0)
;     ...
;             PG8_LDB(B0, 0, 0); PG8_LDB(B1, 0, 1); PG8_SCHED; PG8_LDA(At, 0, 0); PG8_STAGEA(PG8_SA(1, 1), a1 + hstep, voffA);
;             PG8_WAIT_V(8); PG8_WAIT_L(0); PG8_BAR; PG8_MMA(0, 0, At, B0); PG8_MMA(0, 1, At, B1); PG8_BAR; PG8_SCHED;
;             PG8_LDA(At, 0, 1); PG8_STAGE(PG8_SB(0, 0), b2, voffB); PG8_STAGE(PG8_SB(0, 1), b2 + hstepB, voffB); PG8_STAGEA(PG8_SA(0, 0), a2, voffA);
.Lsprio_1:
.LBB0_444:
	ds_read_b128 v[148:151], v142
	ds_read_b128 v[152:155], v142 offset:1024
	ds_read_b128 v[156:159], v142 offset:2048
	ds_read_b128 v[160:163], v142 offset:3072
	ds_read_b128 v[164:167], v143
	ds_read_b128 v[168:171], v143 offset:1024
	ds_read_b128 v[176:179], v143 offset:2048
	ds_read_b128 v[180:183], v143 offset:3072
	s_add_u32 s14, s12, 0xf25c0080
	s_addc_u32 s15, s13, -1
	s_cmp_lg_u32 s22, 12
	s_cselect_b32 s14, s14, 0
	s_cselect_b32 s15, s15, 0
	s_add_u32 s16, s8, s14
	s_addc_u32 s17, s9, s15
	s_add_u32 s14, s6, s14
	s_addc_u32 s15, s7, s15
	s_mov_b32 m0, s23
	v_lshl_add_u64 v[172:173], v[136:137], 0, s[12:13]
	ds_read_b128 v[184:187], v144
	ds_read_b128 v[188:191], v144 offset:1024
	ds_read_b128 v[192:195], v144 offset:2048
	ds_read_b128 v[196:199], v144 offset:3072
	ds_read_b128 v[202:205], v144 offset:4096
	ds_read_b128 v[210:213], v144 offset:5120
	ds_read_b128 v[214:217], v144 offset:6144
	ds_read_b128 v[218:221], v144 offset:7168
	global_load_lds_dwordx4 v[172:173], off
	v_lshl_add_u64 v[172:173], v[138:139], 0, s[12:13]
	s_mov_b32 m0, s24
	s_nop 0
	global_load_lds_dwordx4 v[172:173], off
	s_waitcnt vmcnt(8)
	s_waitcnt lgkmcnt(0)
	s_barrier
	s_waitcnt lgkmcnt(0)
	v_mfma_f32_16x16x32_bf16 v[124:127], v[148:151], v[184:187], v[124:127]
	v_mfma_f32_16x16x32_bf16 v[120:123], v[156:159], v[184:187], v[120:123]
	v_mfma_f32_16x16x32_bf16 v[108:111], v[148:151], v[192:195], v[108:111]
	v_mfma_f32_16x16x32_bf16 v[104:107], v[156:159], v[192:195], v[104:107]
	v_mfma_f32_16x16x32_bf16 v[92:95], v[148:151], v[202:205], v[92:95]
	v_mfma_f32_16x16x32_bf16 v[88:91], v[156:159], v[202:205], v[88:91]
	v_mfma_f32_16x16x32_bf16 v[76:79], v[148:151], v[214:217], v[76:79]
	v_mfma_f32_16x16x32_bf16 v[72:75], v[156:159], v[214:217], v[72:75]
	v_mfma_f32_16x16x32_bf16 v[124:127], v[152:155], v[188:191], v[124:127]
	v_mfma_f32_16x16x32_bf16 v[120:123], v[160:163], v[188:191], v[120:123]
	v_mfma_f32_16x16x32_bf16 v[108:111], v[152:155], v[196:199], v[108:111]
	v_mfma_f32_16x16x32_bf16 v[104:107], v[160:163], v[196:199], v[104:107]
	v_mfma_f32_16x16x32_bf16 v[92:95], v[152:155], v[210:213], v[92:95]
	v_mfma_f32_16x16x32_bf16 v[88:91], v[160:163], v[210:213], v[88:91]
	v_mfma_f32_16x16x32_bf16 v[76:79], v[152:155], v[218:221], v[76:79]
	v_mfma_f32_16x16x32_bf16 v[72:75], v[160:163], v[218:221], v[72:75]
	v_mfma_f32_16x16x32_bf16 v[116:119], v[164:167], v[184:187], v[116:119]
	v_mfma_f32_16x16x32_bf16 v[112:115], v[176:179], v[184:187], v[112:115]
	v_mfma_f32_16x16x32_bf16 v[100:103], v[164:167], v[192:195], v[100:103]
	v_mfma_f32_16x16x32_bf16 v[96:99], v[176:179], v[192:195], v[96:99]
	v_mfma_f32_16x16x32_bf16 v[84:87], v[164:167], v[202:205], v[84:87]
	v_mfma_f32_16x16x32_bf16 v[80:83], v[176:179], v[202:205], v[80:83]
	v_mfma_f32_16x16x32_bf16 v[68:71], v[164:167], v[214:217], v[68:71]
	v_mfma_f32_16x16x32_bf16 v[64:67], v[176:179], v[214:217], v[64:67]
	v_mfma_f32_16x16x32_bf16 v[116:119], v[168:171], v[188:191], v[116:119]
	v_mfma_f32_16x16x32_bf16 v[112:115], v[180:183], v[188:191], v[112:115]
	v_mfma_f32_16x16x32_bf16 v[100:103], v[168:171], v[196:199], v[100:103]
	v_mfma_f32_16x16x32_bf16 v[96:99], v[180:183], v[196:199], v[96:99]
	v_mfma_f32_16x16x32_bf16 v[84:87], v[168:171], v[210:213], v[84:87]
	v_mfma_f32_16x16x32_bf16 v[80:83], v[180:183], v[210:213], v[80:83]
	v_mfma_f32_16x16x32_bf16 v[68:71], v[168:171], v[218:221], v[68:71]
	v_mfma_f32_16x16x32_bf16 v[64:67], v[180:183], v[218:221], v[64:67]
	s_barrier
	s_mov_b32 m0, s25
	v_lshl_add_u64 v[172:173], s[14:15], 0, v[132:133]
	s_add_u32 s36, s14, 0x10000
	ds_read_b128 v[184:187], v144 offset:16384
	ds_read_b128 v[188:191], v144 offset:17408
	ds_read_b128 v[192:195], v144 offset:18432
	ds_read_b128 v[196:199], v144 offset:19456
	ds_read_b128 v[202:205], v144 offset:20480
	ds_read_b128 v[210:213], v144 offset:21504
	ds_read_b128 v[214:217], v144 offset:22528
	ds_read_b128 v[218:221], v144 offset:23552
	global_load_lds_dwordx4 v[172:173], off
	v_lshl_add_u64 v[206:207], s[14:15], 0, v[128:129]
	s_mov_b32 m0, s26
	s_addc_u32 s37, s15, 0
	global_load_lds_dwordx4 v[206:207], off
	v_lshl_add_u64 v[222:223], s[36:37], 0, v[132:133]
	s_mov_b32 m0, s27
	v_lshl_add_u64 v[224:225], s[16:17], 0, v[130:131]
	global_load_lds_dwordx4 v[222:223], off
	v_lshl_add_u64 v[222:223], s[36:37], 0, v[128:129]
	s_mov_b32 m0, s28
	s_nop 0
	global_load_lds_dwordx4 v[222:223], off
	v_lshl_add_u64 v[222:223], s[16:17], 0, v[134:135]
	s_mov_b32 m0, s1
	s_nop 0
	global_load_lds_dwordx4 v[222:223], off
	s_mov_b32 m0, s3
	s_nop 0
	global_load_lds_dwordx4 v[224:225], off
	s_waitcnt vmcnt(8)
	s_waitcnt lgkmcnt(0)
	s_barrier
; #define PG8_STAGEA(bufoff, gbase, voff) do { _Pragma("unroll") for (int _i = 0; _i < 2; ++_i) \
;         __builtin_amdgcn_global_load_lds((const unsigned*)((const char*)(gbase) + (voff)[_i]), (PG8_LAS unsigned*)(lds + (bufoff) + ldsw + _i * 8192), 16, 0, AUXA); } while (0)
; #define PG8_LDA(dst, b, h) do { _Pragma("unroll") for (int m = 0; m < 4; ++m) _Pragma("unroll") for (int k = 0; k < 2; ++k) dst[m][k] = *(const PG8_LAS bf16x8*)(lds + PG8_SA(b, h) + aoff + m * 2048 + k * 1024); } while (0)
; #define PG8_LDB(dst, b, h) do { _Pragma("unroll") for (int n = 0; n < 2; ++n) _Pragma("unroll") for (int k = 0; k < 2; ++k) dst[n][k] = *(const PG8_LAS bf16x8*)(lds + PG8_SB(b, h) + boff + n * 2048 + k * 1024); } while (0)
; #define PG8_MMA(ai, bj, At, Bt) do { __builtin_amdgcn_s_setprio(1); _Pragma("unroll") for (int m = 0; m < 4; ++m) _Pragma("unroll") for (int n = 0; n < 2; ++n) _Pragma("unroll") for (int k = 0; k < 2; ++k) \
;         acc[ai][bj][m][n] = __builtin_amdgcn_mfma_f32_16x16x32_bf16(Bt[n][k], At[m][k], acc[ai][bj][m][n], 0, 0, 0); __builtin_amdgcn_s_setprio(0); } while (0)
; #define PG8_WAIT_V(n) asm volatile("s_waitcnt vmcnt(" #n ")" ::: "memory")
; #define PG8_WAIT_L(n) asm volatile("s_waitcnt lgkmcnt(" #n ")" ::: "memory")
; #define PG8_BAR __builtin_amdgcn_s_barrier()
; #define PG8_SCHED __builtin_amdgcn_sched_barrier(0)
;     ...
;             PG8_WAIT_V(8); PG8_WAIT_L(0); PG8_BAR; PG8_MMA(1, 0, At, B0); PG8_MMA(1, 1, At, B1); PG8_BAR; PG8_SCHED;
;             PG8_LDB(B0, 1, 0); PG8_LDB(B1, 1, 1); PG8_SCHED; PG8_LDA(At, 1, 0); PG8_STAGEA(PG8_SA(0, 1), a2 + hstep, voffA);
;             PG8_WAIT_V(8); PG8_WAIT_L(0); PG8_BAR; PG8_MMA(0, 0, At, B0); PG8_MMA(0, 1, At, B1); PG8_BAR; PG8_SCHED;
	s_waitcnt lgkmcnt(0)
	v_mfma_f32_16x16x32_bf16 v[60:63], v[148:151], v[184:187], v[60:63]
	v_mfma_f32_16x16x32_bf16 v[56:59], v[156:159], v[184:187], v[56:59]
	v_mfma_f32_16x16x32_bf16 v[44:47], v[148:151], v[192:195], v[44:47]
	v_mfma_f32_16x16x32_bf16 v[40:43], v[156:159], v[192:195], v[40:43]
	v_mfma_f32_16x16x32_bf16 v[28:31], v[148:151], v[202:205], v[28:31]
	v_mfma_f32_16x16x32_bf16 v[24:27], v[156:159], v[202:205], v[24:27]
	v_mfma_f32_16x16x32_bf16 v[12:15], v[148:151], v[214:217], v[12:15]
	v_mfma_f32_16x16x32_bf16 v[8:11], v[156:159], v[214:217], v[8:11]
	v_mfma_f32_16x16x32_bf16 v[60:63], v[152:155], v[188:191], v[60:63]
	v_mfma_f32_16x16x32_bf16 v[56:59], v[160:163], v[188:191], v[56:59]
	v_mfma_f32_16x16x32_bf16 v[44:47], v[152:155], v[196:199], v[44:47]
	v_mfma_f32_16x16x32_bf16 v[40:43], v[160:163], v[196:199], v[40:43]
	v_mfma_f32_16x16x32_bf16 v[28:31], v[152:155], v[210:213], v[28:31]
	v_mfma_f32_16x16x32_bf16 v[24:27], v[160:163], v[210:213], v[24:27]
	v_mfma_f32_16x16x32_bf16 v[12:15], v[152:155], v[218:221], v[12:15]
	v_mfma_f32_16x16x32_bf16 v[8:11], v[160:163], v[218:221], v[8:11]
	v_mfma_f32_16x16x32_bf16 v[52:55], v[164:167], v[184:187], v[52:55]
	v_mfma_f32_16x16x32_bf16 v[48:51], v[176:179], v[184:187], v[48:51]
	v_mfma_f32_16x16x32_bf16 v[36:39], v[164:167], v[192:195], v[36:39]
	v_mfma_f32_16x16x32_bf16 v[32:35], v[176:179], v[192:195], v[32:35]
	v_mfma_f32_16x16x32_bf16 v[20:23], v[164:167], v[202:205], v[20:23]
	v_mfma_f32_16x16x32_bf16 v[16:19], v[176:179], v[202:205], v[16:19]
	v_mfma_f32_16x16x32_bf16 v[4:7], v[164:167], v[214:217], v[4:7]
	v_mfma_f32_16x16x32_bf16 v[0:3], v[176:179], v[214:217], v[0:3]
	v_mfma_f32_16x16x32_bf16 v[52:55], v[168:171], v[188:191], v[52:55]
	v_mfma_f32_16x16x32_bf16 v[48:51], v[180:183], v[188:191], v[48:51]
	v_mfma_f32_16x16x32_bf16 v[36:39], v[168:171], v[196:199], v[36:39]
	v_mfma_f32_16x16x32_bf16 v[32:35], v[180:183], v[196:199], v[32:35]
	v_mfma_f32_16x16x32_bf16 v[20:23], v[168:171], v[210:213], v[20:23]
	v_mfma_f32_16x16x32_bf16 v[16:19], v[180:183], v[210:213], v[16:19]
	v_mfma_f32_16x16x32_bf16 v[4:7], v[168:171], v[218:221], v[4:7]
	v_mfma_f32_16x16x32_bf16 v[0:3], v[180:183], v[218:221], v[0:3]
	s_barrier
	ds_read_b128 v[148:151], v145
	ds_read_b128 v[152:155], v145 offset:1024
	ds_read_b128 v[156:159], v145 offset:2048
	ds_read_b128 v[160:163], v145 offset:3072
	ds_read_b128 v[164:167], v146
	ds_read_b128 v[168:171], v146 offset:1024
	ds_read_b128 v[176:179], v146 offset:2048
	ds_read_b128 v[180:183], v146 offset:3072
	s_add_u32 s16, s16, 0x40000
	s_addc_u32 s17, s17, 0
	s_mov_b32 m0, s18
	v_lshl_add_u64 v[226:227], s[16:17], 0, v[134:135]
	ds_read_b128 v[184:187], v144 offset:32768
	ds_read_b128 v[188:191], v144 offset:33792
	ds_read_b128 v[192:195], v144 offset:34816
	ds_read_b128 v[196:199], v144 offset:35840
	ds_read_b128 v[202:205], v144 offset:36864
	ds_read_b128 v[210:213], v144 offset:37888
	ds_read_b128 v[214:217], v144 offset:38912
	ds_read_b128 v[218:221], v144 offset:39936
	global_load_lds_dwordx4 v[226:227], off
	v_lshl_add_u64 v[226:227], s[16:17], 0, v[130:131]
	s_mov_b32 m0, s19
	s_nop 0
	global_load_lds_dwordx4 v[226:227], off
	s_waitcnt vmcnt(8)
	s_waitcnt lgkmcnt(0)
	s_barrier
	s_waitcnt lgkmcnt(0)
	v_mfma_f32_16x16x32_bf16 v[124:127], v[148:151], v[184:187], v[124:127]
	v_mfma_f32_16x16x32_bf16 v[120:123], v[156:159], v[184:187], v[120:123]
	v_mfma_f32_16x16x32_bf16 v[108:111], v[148:151], v[192:195], v[108:111]
	v_mfma_f32_16x16x32_bf16 v[104:107], v[156:159], v[192:195], v[104:107]
	v_mfma_f32_16x16x32_bf16 v[92:95], v[148:151], v[202:205], v[92:95]
	v_mfma_f32_16x16x32_bf16 v[88:91], v[156:159], v[202:205], v[88:91]
	v_mfma_f32_16x16x32_bf16 v[76:79], v[148:151], v[214:217], v[76:79]
	v_mfma_f32_16x16x32_bf16 v[72:75], v[156:159], v[214:217], v[72:75]
	v_mfma_f32_16x16x32_bf16 v[124:127], v[152:155], v[188:191], v[124:127]
	v_mfma_f32_16x16x32_bf16 v[120:123], v[160:163], v[188:191], v[120:123]
	v_mfma_f32_16x16x32_bf16 v[108:111], v[152:155], v[196:199], v[108:111]
	v_mfma_f32_16x16x32_bf16 v[104:107], v[160:163], v[196:199], v[104:107]
	v_mfma_f32_16x16x32_bf16 v[92:95], v[152:155], v[210:213], v[92:95]
	v_mfma_f32_16x16x32_bf16 v[88:91], v[160:163], v[210:213], v[88:91]
	v_mfma_f32_16x16x32_bf16 v[76:79], v[152:155], v[218:221], v[76:79]
	v_mfma_f32_16x16x32_bf16 v[72:75], v[160:163], v[218:221], v[72:75]
	v_mfma_f32_16x16x32_bf16 v[116:119], v[164:167], v[184:187], v[116:119]
	v_mfma_f32_16x16x32_bf16 v[112:115], v[176:179], v[184:187], v[112:115]
	v_mfma_f32_16x16x32_bf16 v[100:103], v[164:167], v[192:195], v[100:103]
	v_mfma_f32_16x16x32_bf16 v[96:99], v[176:179], v[192:195], v[96:99]
	v_mfma_f32_16x16x32_bf16 v[84:87], v[164:167], v[202:205], v[84:87]
	v_mfma_f32_16x16x32_bf16 v[80:83], v[176:179], v[202:205], v[80:83]
	v_mfma_f32_16x16x32_bf16 v[68:71], v[164:167], v[214:217], v[68:71]
	v_mfma_f32_16x16x32_bf16 v[64:67], v[176:179], v[214:217], v[64:67]
	v_mfma_f32_16x16x32_bf16 v[116:119], v[168:171], v[188:191], v[116:119]
	v_mfma_f32_16x16x32_bf16 v[112:115], v[180:183], v[188:191], v[112:115]
	v_mfma_f32_16x16x32_bf16 v[100:103], v[168:171], v[196:199], v[100:103]
	v_mfma_f32_16x16x32_bf16 v[96:99], v[180:183], v[196:199], v[96:99]
	v_mfma_f32_16x16x32_bf16 v[84:87], v[168:171], v[210:213], v[84:87]
	v_mfma_f32_16x16x32_bf16 v[80:83], v[180:183], v[210:213], v[80:83]
	v_mfma_f32_16x16x32_bf16 v[68:71], v[168:171], v[218:221], v[68:71]
	v_mfma_f32_16x16x32_bf16 v[64:67], v[180:183], v[218:221], v[64:67]
	s_barrier
; #define PG8_STAGE(bufoff, gbase, voff) do { _Pragma("unroll") for (int _i = 0; _i < 2; ++_i) \
;         __builtin_amdgcn_global_load_lds((const unsigned*)((const char*)(gbase) + (voff)[_i]), (PG8_LAS unsigned*)(lds + (bufoff) + ldsw + _i * 8192), 16, 0, 0); } while (0)
; #define PG8_STAGEA(bufoff, gbase, voff) do { _Pragma("unroll") for (int _i = 0; _i < 2; ++_i) \
;         __builtin_amdgcn_global_load_lds((const unsigned*)((const char*)(gbase) + (voff)[_i]), (PG8_LAS unsigned*)(lds + (bufoff) + ldsw + _i * 8192), 16, 0, AUXA); } while (0)
; #define PG8_LDA(dst, b, h) do { _Pragma("unroll") for (int m = 0; m < 4; ++m) _Pragma("unroll") for (int k = 0; k < 2; ++k) dst[m][k] = *(const PG8_LAS bf16x8*)(lds + PG8_SA(b, h) + aoff + m * 2048 + k * 1024); } while (0)
; #define PG8_MMA(ai, bj, At, Bt) do { __builtin_amdgcn_s_setprio(1); _Pragma("unroll") for (int m = 0; m < 4; ++m) _Pragma("unroll") for (int n = 0; n < 2; ++n) _Pragma("unroll") for (int k = 0; k < 2; ++k) \
;         acc[ai][bj][m][n] = __builtin_amdgcn_mfma_f32_16x16x32_bf16(Bt[n][k], At[m][k], acc[ai][bj][m][n], 0, 0, 0); __builtin_amdgcn_s_setprio(0); } while (0)
; #define PG8_WAIT_V(n) asm volatile("s_waitcnt vmcnt(" #n ")" ::: "memory")
; #define PG8_WAIT_L(n) asm volatile("s_waitcnt lgkmcnt(" #n ")" ::: "memory")
; #define PG8_BAR __builtin_amdgcn_s_barrier()
; #define PG8_SCHED __builtin_amdgcn_sched_barrier(0)
;     ...
;         for (int t = 0; t < nt; t += 2) {
;     ...
;             PG8_LDA(At, 1, 1); PG8_STAGE(PG8_SB(1, 0), b3, voffB); PG8_STAGE(PG8_SB(1, 1), b3 + hstepB, voffB); PG8_STAGEA(PG8_SA(1, 0), a3, voffA);
;             PG8_WAIT_V(8); PG8_WAIT_L(0); PG8_BAR; PG8_MMA(1, 0, At, B0); PG8_MMA(1, 1, At, B1); PG8_BAR; PG8_SCHED;
	s_mov_b32 m0, s29
	v_lshl_add_u64 v[172:173], v[172:173], 0, s[10:11]
	s_add_u32 s14, s14, 0x10080
	ds_read_b128 v[184:187], v144 offset:49152
	ds_read_b128 v[188:191], v144 offset:50176
	ds_read_b128 v[192:195], v144 offset:51200
	ds_read_b128 v[196:199], v144 offset:52224
	ds_read_b128 v[202:205], v144 offset:53248
	ds_read_b128 v[210:213], v144 offset:54272
	ds_read_b128 v[214:217], v144 offset:55296
	ds_read_b128 v[218:221], v144 offset:56320
	global_load_lds_dwordx4 v[172:173], off
	v_lshl_add_u64 v[172:173], v[206:207], 0, s[10:11]
	s_mov_b32 m0, s30
	s_addc_u32 s15, s15, 0
	global_load_lds_dwordx4 v[172:173], off
	v_lshl_add_u64 v[172:173], s[14:15], 0, v[132:133]
	s_mov_b32 m0, s31
	s_nop 0
	global_load_lds_dwordx4 v[172:173], off
	v_lshl_add_u64 v[172:173], s[14:15], 0, v[128:129]
	s_mov_b32 m0, s34
	s_nop 0
	global_load_lds_dwordx4 v[172:173], off
	v_lshl_add_u64 v[172:173], v[222:223], 0, s[10:11]
	s_mov_b32 m0, s20
	s_nop 0
	global_load_lds_dwordx4 v[172:173], off
	v_lshl_add_u64 v[172:173], v[224:225], 0, s[10:11]
	s_mov_b32 m0, s21
	s_nop 0
	global_load_lds_dwordx4 v[172:173], off
	s_waitcnt vmcnt(8)
	s_waitcnt lgkmcnt(0)
	s_barrier
	s_waitcnt lgkmcnt(0)
	v_mfma_f32_16x16x32_bf16 v[60:63], v[148:151], v[184:187], v[60:63]
	v_mfma_f32_16x16x32_bf16 v[56:59], v[156:159], v[184:187], v[56:59]
	v_mfma_f32_16x16x32_bf16 v[44:47], v[148:151], v[192:195], v[44:47]
	v_mfma_f32_16x16x32_bf16 v[40:43], v[156:159], v[192:195], v[40:43]
	v_mfma_f32_16x16x32_bf16 v[28:31], v[148:151], v[202:205], v[28:31]
	v_mfma_f32_16x16x32_bf16 v[24:27], v[156:159], v[202:205], v[24:27]
	v_mfma_f32_16x16x32_bf16 v[12:15], v[148:151], v[214:217], v[12:15]
	v_mfma_f32_16x16x32_bf16 v[8:11], v[156:159], v[214:217], v[8:11]
	v_mfma_f32_16x16x32_bf16 v[60:63], v[152:155], v[188:191], v[60:63]
	v_mfma_f32_16x16x32_bf16 v[56:59], v[160:163], v[188:191], v[56:59]
	v_mfma_f32_16x16x32_bf16 v[44:47], v[152:155], v[196:199], v[44:47]
	v_mfma_f32_16x16x32_bf16 v[40:43], v[160:163], v[196:199], v[40:43]
	v_mfma_f32_16x16x32_bf16 v[28:31], v[152:155], v[210:213], v[28:31]
	v_mfma_f32_16x16x32_bf16 v[24:27], v[160:163], v[210:213], v[24:27]
	v_mfma_f32_16x16x32_bf16 v[12:15], v[152:155], v[218:221], v[12:15]
	v_mfma_f32_16x16x32_bf16 v[8:11], v[160:163], v[218:221], v[8:11]
	v_mfma_f32_16x16x32_bf16 v[52:55], v[164:167], v[184:187], v[52:55]
	v_mfma_f32_16x16x32_bf16 v[48:51], v[176:179], v[184:187], v[48:51]
	v_mfma_f32_16x16x32_bf16 v[36:39], v[164:167], v[192:195], v[36:39]
	v_mfma_f32_16x16x32_bf16 v[32:35], v[176:179], v[192:195], v[32:35]
	v_mfma_f32_16x16x32_bf16 v[20:23], v[164:167], v[202:205], v[20:23]
	v_mfma_f32_16x16x32_bf16 v[16:19], v[176:179], v[202:205], v[16:19]
	v_mfma_f32_16x16x32_bf16 v[4:7], v[164:167], v[214:217], v[4:7]
	v_mfma_f32_16x16x32_bf16 v[0:3], v[176:179], v[214:217], v[0:3]
	v_mfma_f32_16x16x32_bf16 v[52:55], v[168:171], v[188:191], v[52:55]
	v_mfma_f32_16x16x32_bf16 v[48:51], v[180:183], v[188:191], v[48:51]
	v_mfma_f32_16x16x32_bf16 v[36:39], v[168:171], v[196:199], v[36:39]
	v_mfma_f32_16x16x32_bf16 v[32:35], v[180:183], v[196:199], v[32:35]
	v_mfma_f32_16x16x32_bf16 v[20:23], v[168:171], v[210:213], v[20:23]
	v_mfma_f32_16x16x32_bf16 v[16:19], v[180:183], v[210:213], v[16:19]
	v_mfma_f32_16x16x32_bf16 v[4:7], v[168:171], v[218:221], v[4:7]
	v_mfma_f32_16x16x32_bf16 v[0:3], v[180:183], v[218:221], v[0:3]
	s_barrier
	s_add_i32 s22, s22, 2
	s_add_u32 s12, s12, 0x100
	s_addc_u32 s13, s13, 0
	s_cmp_gt_u32 s22, 13
	s_cbranch_scc0 .LBB0_444
	s_setprio 0
	v_readlane_b32 s1, v255, 10
	s_cmpk_lt_u32 s1, 0x100
	s_cbranch_scc0 .LBB0_447
	s_barrier

; #define PG8_STAGE(bufoff, gbase, voff) do { _Pragma("unroll") for (int _i = 0; _i < 2; ++_i) \
;         __builtin_amdgcn_global_load_lds((const unsigned*)((const char*)(gbase) + (voff)[_i]), (PG8_LAS unsigned*)(lds + (bufoff) + ldsw + _i * 8192), 16, 0, 0); } while (0)
; #define PG8_STAGEA(bufoff, gbase, voff) do { _Pragma("unroll") for (int _i = 0; _i < 2; ++_i) \
;         __builtin_amdgcn_global_load_lds((const unsigned*)((const char*)(gbase) + (voff)[_i]), (PG8_LAS unsigned*)(lds + (bufoff) + ldsw + _i * 8192), 16, 0, AUXA); } while (0)
; #define PG8_WAIT_V(n) asm volatile("s_waitcnt vmcnt(" #n ")" ::: "memory")
; #define PG8_BAR __builtin_amdgcn_s_barrier()
;     ...
;     f32x4 acc[2][2][4][2];
; #pragma unroll
;     for (int a = 0; a < 2; ++a)
; #pragma unroll
;         for (int b = 0; b < 2; ++b)
; #pragma unroll
;             for (int m = 0; m < 4; ++m)
; #pragma unroll
;                 for (int n = 0; n < 2; ++n) acc[a][b][m][n] = (f32x4){0.f, 0.f, 0.f, 0.f};
;     bf16x8 At[4][2], B0[2][2], B1[2][2];
;     const char* cA = (const char*)g.A + (size_t)cur.pm * tstep + (size_t)cur.k0 * (BK * 2); const char* cB = (const char*)g.Bt + (size_t)cur.pn * tstep + (size_t)cur.k0 * (BK * 2);
;     S.a_ready(cur);
;     if constexpr (SP2) {
;         PG8_STAGE(PG8_SB(0, 0), cB, voffB); PG8_STAGE(PG8_SB(0, 1), cB + hstepB, voffB); PG8_STAGEA(PG8_SA(0, 0), cA, voffA); PG8_STAGEA(PG8_SA(0, 1), cA + hstep, voffA);
;         if (wr == 1) PG8_BAR;
;         PG8_WAIT_V(2); PG8_BAR;
;         PG8_STAGE(PG8_SB(1, 0), cB + kstep, voffB); PG8_STAGEA(PG8_SA(1, 0), cA + kstep, voffA); PG8_STAGE(PG8_SB(1, 1), cB + hstepB + kstep, voffB);
;         PG8_WAIT_V(6); PG8_BAR;
.LBB0_757:
	v_and_b32_e32 v15, 15, v11
	v_lshrrev_b32_e32 v16, 1, v11
	v_or_b32_e32 v129, s72, v15
	v_and_b32_e32 v16, 24, v16
	v_lshlrev_b32_e32 v17, 6, v129
	v_lshlrev_b32_e32 v128, 1, v16
	s_movk_i32 s10, 0x3c0
	v_and_or_b32 v16, v17, s10, v128
	v_lshlrev_b32_e32 v17, 2, v129
	v_and_b32_e32 v17, 32, v17
	v_readlane_b32 s10, v255, 18
	v_lshlrev_b32_e32 v11, 2, v11
	v_lshl_or_b32 v15, v15, 6, v128
	v_bitop3_b32 v16, v16, s10, v17 bitop3:0xde
	v_and_b32_e32 v11, 32, v11
	v_readlane_b32 s10, v255, 19
	s_add_i32 m0, s1, 0x18000
	s_waitcnt vmcnt(2)
	s_barrier
	v_bitop3_b32 v11, v15, s10, v11 bitop3:0xde
	s_mov_b64 s[10:11], 0x80
	v_lshl_add_u64 v[6:7], v[6:7], 0, s[10:11]
	global_load_lds_dwordx4 v[6:7], off
	v_lshl_add_u64 v[4:5], v[4:5], 0, s[10:11]
	s_add_i32 m0, s1, 0x1a000
	s_add_i32 s20, s1, 0x8000
	s_add_i32 s21, s1, 0xa000
	global_load_lds_dwordx4 v[4:5], off
	v_lshl_add_u64 v[0:1], v[0:1], 0, s[10:11]
	s_mov_b32 m0, s20
	s_add_u32 s14, s6, 0x10080
	global_load_lds_dwordx4 v[0:1], off
	v_lshl_add_u64 v[0:1], v[2:3], 0, s[10:11]
	s_mov_b32 m0, s21
	s_addc_u32 s15, s7, 0
	global_load_lds_dwordx4 v[0:1], off
	s_add_i32 m0, s1, 0x1c000
	v_lshl_add_u64 v[0:1], s[14:15], 0, v[134:135]
	global_load_lds_dwordx4 v[0:1], off
	v_lshl_add_u64 v[0:1], s[14:15], 0, v[130:131]
	s_add_i32 m0, s1, 0x1e000
	s_ashr_i32 s13, s12, 31
	global_load_lds_dwordx4 v[0:1], off
	v_lshlrev_b32_e32 v0, 14, v13
	v_and_b32_e32 v0, 0xffff8000, v0
	s_lshl_b64 s[12:13], s[12:13], 19
	v_lshl_add_u32 v0, v12, 11, v0
	v_and_b32_e32 v1, 1, v13
	v_lshl_or_b32 v0, v1, 6, v0
	s_add_u32 s12, s68, s12
	v_lshl_add_u32 v0, v14, 1, v0
	v_mov_b32_e32 v1, v135
	s_addc_u32 s13, s69, s13
	v_lshl_add_u64 v[138:139], s[12:13], 0, v[0:1]
	v_lshlrev_b32_e32 v0, 14, v8
	v_and_b32_e32 v0, 0xffff8000, v0
	v_lshl_add_u32 v0, v9, 11, v0
	v_and_b32_e32 v1, 1, v8
	s_waitcnt vmcnt(6)
	v_lshl_or_b32 v0, v1, 6, v0
	s_add_i32 s25, 0, 0x10000
	s_add_i32 s27, 0, 0x14000
	s_add_i32 s29, 0, 0x18000
	s_add_i32 s31, 0, 0x1c000
	v_lshl_add_u32 v0, v10, 1, v0
	v_mov_b32_e32 v1, v135
	v_add_u32_e32 v142, s25, v11
	v_add_u32_e32 v143, s27, v11
	s_add_i32 s25, s25, s67
	s_add_i32 s27, s27, s67
	v_add_u32_e32 v145, s29, v11
	v_add_u32_e32 v146, s31, v11
	s_add_i32 s29, s29, s67
	s_add_i32 s31, s31, s67
	v_lshl_add_u64 v[140:141], s[12:13], 0, v[0:1]
	s_mov_b32 s22, -2
	s_mov_b64 s[12:13], 0xfc40080
	v_add_u32_e32 v144, 0, v16
	s_add_i32 s23, s1, 0xc000
	s_add_i32 s24, s1, 0xe000
	s_add_i32 s26, s25, 0x2000
	s_add_i32 s28, s27, 0x2000
	s_add_i32 s30, s29, 0x2000
	s_add_i32 s34, s31, 0x2000
	v_mov_b32_e32 v0, v135
	v_mov_b32_e32 v2, v135
	v_mov_b32_e32 v3, v135
	v_mov_b32_e32 v4, v135
	v_mov_b32_e32 v5, v135
	v_mov_b32_e32 v6, v135
	v_mov_b32_e32 v7, v135
	v_mov_b32_e32 v16, v135
	v_mov_b32_e32 v17, v135
	v_mov_b32_e32 v18, v135
	v_mov_b32_e32 v19, v135
	v_mov_b32_e32 v20, v135
	v_mov_b32_e32 v21, v135
	v_mov_b32_e32 v22, v135
	v_mov_b32_e32 v23, v135
	v_mov_b32_e32 v32, v135
	v_mov_b32_e32 v33, v135
	v_mov_b32_e32 v34, v135
	v_mov_b32_e32 v35, v135
	v_mov_b32_e32 v36, v135
	v_mov_b32_e32 v37, v135
	v_mov_b32_e32 v38, v135
	v_mov_b32_e32 v39, v135
	v_mov_b32_e32 v48, v135
	v_mov_b32_e32 v49, v135
	v_mov_b32_e32 v50, v135
	v_mov_b32_e32 v51, v135
	v_mov_b32_e32 v52, v135
	v_mov_b32_e32 v53, v135
	v_mov_b32_e32 v54, v135
	v_mov_b32_e32 v55, v135
	v_mov_b32_e32 v8, v135
	v_mov_b32_e32 v9, v135
	v_mov_b32_e32 v10, v135
	v_mov_b32_e32 v11, v135
	v_mov_b32_e32 v12, v135
	v_mov_b32_e32 v13, v135
	v_mov_b32_e32 v14, v135
	v_mov_b32_e32 v15, v135
	v_mov_b32_e32 v24, v135
	v_mov_b32_e32 v25, v135
	v_mov_b32_e32 v26, v135
	v_mov_b32_e32 v27, v135
	v_mov_b32_e32 v28, v135
	v_mov_b32_e32 v29, v135
	v_mov_b32_e32 v30, v135
	v_mov_b32_e32 v31, v135
	v_mov_b32_e32 v40, v135
	v_mov_b32_e32 v41, v135
	v_mov_b32_e32 v42, v135
	v_mov_b32_e32 v43, v135
	v_mov_b32_e32 v44, v135
	v_mov_b32_e32 v45, v135
	v_mov_b32_e32 v46, v135
	v_mov_b32_e32 v47, v135
	v_mov_b32_e32 v56, v135
	v_mov_b32_e32 v57, v135
	v_mov_b32_e32 v58, v135
	v_mov_b32_e32 v59, v135
	v_mov_b32_e32 v60, v135
	v_mov_b32_e32 v61, v135
	v_mov_b32_e32 v62, v135
	v_mov_b32_e32 v63, v135
	v_mov_b32_e32 v64, v135
	v_mov_b32_e32 v65, v135
	v_mov_b32_e32 v66, v135
	v_mov_b32_e32 v67, v135
	v_mov_b32_e32 v68, v135
	v_mov_b32_e32 v69, v135
	v_mov_b32_e32 v70, v135
	v_mov_b32_e32 v71, v135
	v_mov_b32_e32 v80, v135
	v_mov_b32_e32 v81, v135
	v_mov_b32_e32 v82, v135
	v_mov_b32_e32 v83, v135
	v_mov_b32_e32 v84, v135
	v_mov_b32_e32 v85, v135
	v_mov_b32_e32 v86, v135
	v_mov_b32_e32 v87, v135
	v_mov_b32_e32 v96, v135
	v_mov_b32_e32 v97, v135
	v_mov_b32_e32 v98, v135
	v_mov_b32_e32 v99, v135
	v_mov_b32_e32 v100, v135
	v_mov_b32_e32 v101, v135
	v_mov_b32_e32 v102, v135
	v_mov_b32_e32 v103, v135
	v_mov_b32_e32 v112, v135
	v_mov_b32_e32 v113, v135
	v_mov_b32_e32 v114, v135
	v_mov_b32_e32 v115, v135
	v_mov_b32_e32 v116, v135
	v_mov_b32_e32 v117, v135
	v_mov_b32_e32 v118, v135
	v_mov_b32_e32 v119, v135
	v_mov_b32_e32 v72, v135
	v_mov_b32_e32 v73, v135
	v_mov_b32_e32 v74, v135
	v_mov_b32_e32 v75, v135
	v_mov_b32_e32 v76, v135
	v_mov_b32_e32 v77, v135
	v_mov_b32_e32 v78, v135
	v_mov_b32_e32 v79, v135
	v_mov_b32_e32 v88, v135
	v_mov_b32_e32 v89, v135
	v_mov_b32_e32 v90, v135
	v_mov_b32_e32 v91, v135
	v_mov_b32_e32 v92, v135
	v_mov_b32_e32 v93, v135
	v_mov_b32_e32 v94, v135
	v_mov_b32_e32 v95, v135
	v_mov_b32_e32 v104, v135
	v_mov_b32_e32 v105, v135
	v_mov_b32_e32 v106, v135
	v_mov_b32_e32 v107, v135
	v_mov_b32_e32 v108, v135
	v_mov_b32_e32 v109, v135
	v_mov_b32_e32 v110, v135
	v_mov_b32_e32 v111, v135
	v_mov_b32_e32 v120, v135
	v_mov_b32_e32 v121, v135
	v_mov_b32_e32 v122, v135
	v_mov_b32_e32 v123, v135
	v_mov_b32_e32 v124, v135
	v_mov_b32_e32 v125, v135
	v_mov_b32_e32 v126, v135
	v_mov_b32_e32 v127, v135
	s_barrier
	v_readlane_b32 s98, v255, 17
	s_cmp_lg_u32 s98, 1
	s_cbranch_scc1 .Lsprio_2
	s_setprio 1
; #define PG8_STAGE(bufoff, gbase, voff) do { _Pragma("unroll") for (int _i = 0; _i < 2; ++_i) \
;         __builtin_amdgcn_global_load_lds((const unsigned*)((const char*)(gbase) + (voff)[_i]), (PG8_LAS unsigned*)(lds + (bufoff) + ldsw + _i * 8192), 16, 0, 0); } while (0)
; #define PG8_STAGEA(bufoff, gbase, voff) do { _Pragma("unroll") for (int _i = 0; _i < 2; ++_i) \
;         __builtin_amdgcn_global_load_lds((const unsigned*)((const char*)(gbase) + (voff)[_i]), (PG8_LAS unsigned*)(lds + (bufoff) + ldsw + _i * 8192), 16, 0, AUXA); } while (0)
; #define PG8_LDA(dst, b, h) do { _Pragma("unroll") for (int m = 0; m < 4; ++m) _Pragma("unroll") for (int k = 0; k < 2; ++k) dst[m][k] = *(const PG8_LAS bf16x8*)(lds + PG8_SA(b, h) + aoff + m * 2048 + k * 1024); } while (0)
; #define PG8_LDB(dst, b, h) do { _Pragma("unroll") for (int n = 0; n < 2; ++n) _Pragma("unroll") for (int k = 0; k < 2; ++k) dst[n][k] = *(const PG8_LAS bf16x8*)(lds + PG8_SB(b, h) + boff + n * 2048 + k * 1024); } while (0)
; #define PG8_MMA(ai, bj, At, Bt) do { __builtin_amdgcn_s_setprio(1); _Pragma("unroll") for (int m = 0; m < 4; ++m) _Pragma("unroll") for (int n = 0; n < 2; ++n) _Pragma("unroll") for (int k = 0; k < 2; ++k) \
;         acc[ai][bj][m][n] = __builtin_amdgcn_mfma_f32_16x16x32_bf16(Bt[n][k], At[m][k], acc[ai][bj][m][n], 0, 0, 0); __builtin_amdgcn_s_setprio(0); } while (0)
; #define PG8_WAIT_V(n) asm volatile("s_waitcnt vmcnt(" #n ")" ::: "memory")
; #define PG8_WAIT_L(n) asm volatile("s_waitcnt lgkmcnt(" #n ")" ::: "memory")
; #define PG8_BAR __builtin_amdgcn_s_barrier()
; #define PG8_SCHED __builtin_amdgcn_sched_barrier(0)
;     ...
;             PG8_LDB(B0, 0, 0); PG8_LDB(B1, 0, 1); PG8_SCHED; PG8_LDA(At, 0, 0); PG8_STAGEA(PG8_SA(1, 1), a1 + hstep, voffA);
;             PG8_WAIT_V(8); PG8_WAIT_L(0); PG8_BAR; PG8_MMA(0, 0, At, B0); PG8_MMA(0, 1, At, B1); PG8_BAR; PG8_SCHED;
;             PG8_LDA(At, 0, 1); PG8_STAGE(PG8_SB(0, 0), b2, voffB); PG8_STAGE(PG8_SB(0, 1), b2 + hstepB, voffB); PG8_STAGEA(PG8_SA(0, 0), a2, voffA);
.Lsprio_2:
.LBB0_758:
	ds_read_b128 v[148:151], v142
	ds_read_b128 v[152:155], v142 offset:1024
	ds_read_b128 v[156:159], v142 offset:2048
	ds_read_b128 v[160:163], v142 offset:3072
	ds_read_b128 v[164:167], v143
	ds_read_b128 v[168:171], v143 offset:1024
	ds_read_b128 v[176:179], v143 offset:2048
	ds_read_b128 v[180:183], v143 offset:3072
	s_add_u32 s14, s12, 0xf03c0080
	s_addc_u32 s15, s13, -1
	s_cmp_lg_u32 s22, 12
	s_cselect_b32 s14, s14, 0
	s_cselect_b32 s15, s15, 0
	s_add_u32 s16, s8, s14
	s_addc_u32 s17, s9, s15
	s_add_u32 s14, s6, s14
	s_addc_u32 s15, s7, s15
	s_mov_b32 m0, s23
	v_lshl_add_u64 v[172:173], v[138:139], 0, s[12:13]
	ds_read_b128 v[184:187], v144
	ds_read_b128 v[188:191], v144 offset:1024
	ds_read_b128 v[192:195], v144 offset:2048
	ds_read_b128 v[196:199], v144 offset:3072
	ds_read_b128 v[202:205], v144 offset:4096
	ds_read_b128 v[210:213], v144 offset:5120
	ds_read_b128 v[214:217], v144 offset:6144
	ds_read_b128 v[218:221], v144 offset:7168
	global_load_lds_dwordx4 v[172:173], off
	v_lshl_add_u64 v[172:173], v[140:141], 0, s[12:13]
	s_mov_b32 m0, s24
	s_nop 0
	global_load_lds_dwordx4 v[172:173], off
	s_waitcnt vmcnt(8)
	s_waitcnt lgkmcnt(0)
	s_barrier
	s_waitcnt lgkmcnt(0)
	v_mfma_f32_16x16x32_bf16 v[124:127], v[148:151], v[184:187], v[124:127]
	v_mfma_f32_16x16x32_bf16 v[120:123], v[156:159], v[184:187], v[120:123]
	v_mfma_f32_16x16x32_bf16 v[108:111], v[148:151], v[192:195], v[108:111]
	v_mfma_f32_16x16x32_bf16 v[104:107], v[156:159], v[192:195], v[104:107]
	v_mfma_f32_16x16x32_bf16 v[92:95], v[148:151], v[202:205], v[92:95]
	v_mfma_f32_16x16x32_bf16 v[88:91], v[156:159], v[202:205], v[88:91]
	v_mfma_f32_16x16x32_bf16 v[76:79], v[148:151], v[214:217], v[76:79]
	v_mfma_f32_16x16x32_bf16 v[72:75], v[156:159], v[214:217], v[72:75]
	v_mfma_f32_16x16x32_bf16 v[124:127], v[152:155], v[188:191], v[124:127]
	v_mfma_f32_16x16x32_bf16 v[120:123], v[160:163], v[188:191], v[120:123]
	v_mfma_f32_16x16x32_bf16 v[108:111], v[152:155], v[196:199], v[108:111]
	v_mfma_f32_16x16x32_bf16 v[104:107], v[160:163], v[196:199], v[104:107]
	v_mfma_f32_16x16x32_bf16 v[92:95], v[152:155], v[210:213], v[92:95]
	v_mfma_f32_16x16x32_bf16 v[88:91], v[160:163], v[210:213], v[88:91]
	v_mfma_f32_16x16x32_bf16 v[76:79], v[152:155], v[218:221], v[76:79]
	v_mfma_f32_16x16x32_bf16 v[72:75], v[160:163], v[218:221], v[72:75]
	v_mfma_f32_16x16x32_bf16 v[116:119], v[164:167], v[184:187], v[116:119]
	v_mfma_f32_16x16x32_bf16 v[112:115], v[176:179], v[184:187], v[112:115]
	v_mfma_f32_16x16x32_bf16 v[100:103], v[164:167], v[192:195], v[100:103]
	v_mfma_f32_16x16x32_bf16 v[96:99], v[176:179], v[192:195], v[96:99]
	v_mfma_f32_16x16x32_bf16 v[84:87], v[164:167], v[202:205], v[84:87]
	v_mfma_f32_16x16x32_bf16 v[80:83], v[176:179], v[202:205], v[80:83]
	v_mfma_f32_16x16x32_bf16 v[68:71], v[164:167], v[214:217], v[68:71]
	v_mfma_f32_16x16x32_bf16 v[64:67], v[176:179], v[214:217], v[64:67]
	v_mfma_f32_16x16x32_bf16 v[116:119], v[168:171], v[188:191], v[116:119]
	v_mfma_f32_16x16x32_bf16 v[112:115], v[180:183], v[188:191], v[112:115]
	v_mfma_f32_16x16x32_bf16 v[100:103], v[168:171], v[196:199], v[100:103]
	v_mfma_f32_16x16x32_bf16 v[96:99], v[180:183], v[196:199], v[96:99]
	v_mfma_f32_16x16x32_bf16 v[84:87], v[168:171], v[210:213], v[84:87]
	v_mfma_f32_16x16x32_bf16 v[80:83], v[180:183], v[210:213], v[80:83]
	v_mfma_f32_16x16x32_bf16 v[68:71], v[168:171], v[218:221], v[68:71]
	v_mfma_f32_16x16x32_bf16 v[64:67], v[180:183], v[218:221], v[64:67]
	s_barrier
	s_mov_b32 m0, s25
	v_lshl_add_u64 v[172:173], s[14:15], 0, v[134:135]
	s_add_u32 s36, s14, 0x10000
	ds_read_b128 v[184:187], v144 offset:16384
	ds_read_b128 v[188:191], v144 offset:17408
	ds_read_b128 v[192:195], v144 offset:18432
	ds_read_b128 v[196:199], v144 offset:19456
	ds_read_b128 v[202:205], v144 offset:20480
	ds_read_b128 v[210:213], v144 offset:21504
	ds_read_b128 v[214:217], v144 offset:22528
	ds_read_b128 v[218:221], v144 offset:23552
	global_load_lds_dwordx4 v[172:173], off
	v_lshl_add_u64 v[206:207], s[14:15], 0, v[130:131]
	s_mov_b32 m0, s26
	s_addc_u32 s37, s15, 0
	global_load_lds_dwordx4 v[206:207], off
	v_lshl_add_u64 v[222:223], s[36:37], 0, v[134:135]
	s_mov_b32 m0, s27
	v_lshl_add_u64 v[224:225], s[16:17], 0, v[132:133]
	global_load_lds_dwordx4 v[222:223], off
	v_lshl_add_u64 v[222:223], s[36:37], 0, v[130:131]
	s_mov_b32 m0, s28
	s_nop 0
	global_load_lds_dwordx4 v[222:223], off
	v_lshl_add_u64 v[222:223], s[16:17], 0, v[136:137]
	s_mov_b32 m0, s1
	s_nop 0
	global_load_lds_dwordx4 v[222:223], off
	s_mov_b32 m0, s5
	s_nop 0
	global_load_lds_dwordx4 v[224:225], off
	s_waitcnt vmcnt(8)
	s_waitcnt lgkmcnt(0)
	s_barrier
; #define PG8_STAGEA(bufoff, gbase, voff) do { _Pragma("unroll") for (int _i = 0; _i < 2; ++_i) \
;         __builtin_amdgcn_global_load_lds((const unsigned*)((const char*)(gbase) + (voff)[_i]), (PG8_LAS unsigned*)(lds + (bufoff) + ldsw + _i * 8192), 16, 0, AUXA); } while (0)
; #define PG8_LDA(dst, b, h) do { _Pragma("unroll") for (int m = 0; m < 4; ++m) _Pragma("unroll") for (int k = 0; k < 2; ++k) dst[m][k] = *(const PG8_LAS bf16x8*)(lds + PG8_SA(b, h) + aoff + m * 2048 + k * 1024); } while (0)
; #define PG8_LDB(dst, b, h) do { _Pragma("unroll") for (int n = 0; n < 2; ++n) _Pragma("unroll") for (int k = 0; k < 2; ++k) dst[n][k] = *(const PG8_LAS bf16x8*)(lds + PG8_SB(b, h) + boff + n * 2048 + k * 1024); } while (0)
; #define PG8_MMA(ai, bj, At, Bt) do { __builtin_amdgcn_s_setprio(1); _Pragma("unroll") for (int m = 0; m < 4; ++m) _Pragma("unroll") for (int n = 0; n < 2; ++n) _Pragma("unroll") for (int k = 0; k < 2; ++k) \
;         acc[ai][bj][m][n] = __builtin_amdgcn_mfma_f32_16x16x32_bf16(Bt[n][k], At[m][k], acc[ai][bj][m][n], 0, 0, 0); __builtin_amdgcn_s_setprio(0); } while (0)
; #define PG8_WAIT_V(n) asm volatile("s_waitcnt vmcnt(" #n ")" ::: "memory")
; #define PG8_WAIT_L(n) asm volatile("s_waitcnt lgkmcnt(" #n ")" ::: "memory")
; #define PG8_BAR __builtin_amdgcn_s_barrier()
; #define PG8_SCHED __builtin_amdgcn_sched_barrier(0)
;     ...
;             PG8_WAIT_V(8); PG8_WAIT_L(0); PG8_BAR; PG8_MMA(1, 0, At, B0); PG8_MMA(1, 1, At, B1); PG8_BAR; PG8_SCHED;
;             PG8_LDB(B0, 1, 0); PG8_LDB(B1, 1, 1); PG8_SCHED; PG8_LDA(At, 1, 0); PG8_STAGEA(PG8_SA(0, 1), a2 + hstep, voffA);
;             PG8_WAIT_V(8); PG8_WAIT_L(0); PG8_BAR; PG8_MMA(0, 0, At, B0); PG8_MMA(0, 1, At, B1); PG8_BAR; PG8_SCHED;
	s_waitcnt lgkmcnt(0)
	v_mfma_f32_16x16x32_bf16 v[60:63], v[148:151], v[184:187], v[60:63]
	v_mfma_f32_16x16x32_bf16 v[56:59], v[156:159], v[184:187], v[56:59]
	v_mfma_f32_16x16x32_bf16 v[44:47], v[148:151], v[192:195], v[44:47]
	v_mfma_f32_16x16x32_bf16 v[40:43], v[156:159], v[192:195], v[40:43]
	v_mfma_f32_16x16x32_bf16 v[28:31], v[148:151], v[202:205], v[28:31]
	v_mfma_f32_16x16x32_bf16 v[24:27], v[156:159], v[202:205], v[24:27]
	v_mfma_f32_16x16x32_bf16 v[12:15], v[148:151], v[214:217], v[12:15]
	v_mfma_f32_16x16x32_bf16 v[8:11], v[156:159], v[214:217], v[8:11]
	v_mfma_f32_16x16x32_bf16 v[60:63], v[152:155], v[188:191], v[60:63]
	v_mfma_f32_16x16x32_bf16 v[56:59], v[160:163], v[188:191], v[56:59]
	v_mfma_f32_16x16x32_bf16 v[44:47], v[152:155], v[196:199], v[44:47]
	v_mfma_f32_16x16x32_bf16 v[40:43], v[160:163], v[196:199], v[40:43]
	v_mfma_f32_16x16x32_bf16 v[28:31], v[152:155], v[210:213], v[28:31]
	v_mfma_f32_16x16x32_bf16 v[24:27], v[160:163], v[210:213], v[24:27]
	v_mfma_f32_16x16x32_bf16 v[12:15], v[152:155], v[218:221], v[12:15]
	v_mfma_f32_16x16x32_bf16 v[8:11], v[160:163], v[218:221], v[8:11]
	v_mfma_f32_16x16x32_bf16 v[52:55], v[164:167], v[184:187], v[52:55]
	v_mfma_f32_16x16x32_bf16 v[48:51], v[176:179], v[184:187], v[48:51]
	v_mfma_f32_16x16x32_bf16 v[36:39], v[164:167], v[192:195], v[36:39]
	v_mfma_f32_16x16x32_bf16 v[32:35], v[176:179], v[192:195], v[32:35]
	v_mfma_f32_16x16x32_bf16 v[20:23], v[164:167], v[202:205], v[20:23]
	v_mfma_f32_16x16x32_bf16 v[16:19], v[176:179], v[202:205], v[16:19]
	v_mfma_f32_16x16x32_bf16 v[4:7], v[164:167], v[214:217], v[4:7]
	v_mfma_f32_16x16x32_bf16 v[0:3], v[176:179], v[214:217], v[0:3]
	v_mfma_f32_16x16x32_bf16 v[52:55], v[168:171], v[188:191], v[52:55]
	v_mfma_f32_16x16x32_bf16 v[48:51], v[180:183], v[188:191], v[48:51]
	v_mfma_f32_16x16x32_bf16 v[36:39], v[168:171], v[196:199], v[36:39]
	v_mfma_f32_16x16x32_bf16 v[32:35], v[180:183], v[196:199], v[32:35]
	v_mfma_f32_16x16x32_bf16 v[20:23], v[168:171], v[210:213], v[20:23]
	v_mfma_f32_16x16x32_bf16 v[16:19], v[180:183], v[210:213], v[16:19]
	v_mfma_f32_16x16x32_bf16 v[4:7], v[168:171], v[218:221], v[4:7]
	v_mfma_f32_16x16x32_bf16 v[0:3], v[180:183], v[218:221], v[0:3]
	s_barrier
	ds_read_b128 v[148:151], v145
	ds_read_b128 v[152:155], v145 offset:1024
	ds_read_b128 v[156:159], v145 offset:2048
	ds_read_b128 v[160:163], v145 offset:3072
	ds_read_b128 v[164:167], v146
	ds_read_b128 v[168:171], v146 offset:1024
	ds_read_b128 v[176:179], v146 offset:2048
	ds_read_b128 v[180:183], v146 offset:3072
	s_add_u32 s16, s16, 0x40000
	s_addc_u32 s17, s17, 0
	s_mov_b32 m0, s18
	v_lshl_add_u64 v[226:227], s[16:17], 0, v[136:137]
	ds_read_b128 v[184:187], v144 offset:32768
	ds_read_b128 v[188:191], v144 offset:33792
	ds_read_b128 v[192:195], v144 offset:34816
	ds_read_b128 v[196:199], v144 offset:35840
	ds_read_b128 v[202:205], v144 offset:36864
	ds_read_b128 v[210:213], v144 offset:37888
	ds_read_b128 v[214:217], v144 offset:38912
	ds_read_b128 v[218:221], v144 offset:39936
	global_load_lds_dwordx4 v[226:227], off
	v_lshl_add_u64 v[226:227], s[16:17], 0, v[132:133]
	s_mov_b32 m0, s19
	s_nop 0
	global_load_lds_dwordx4 v[226:227], off
	s_waitcnt vmcnt(8)
	s_waitcnt lgkmcnt(0)
	s_barrier
	s_waitcnt lgkmcnt(0)
	v_mfma_f32_16x16x32_bf16 v[124:127], v[148:151], v[184:187], v[124:127]
	v_mfma_f32_16x16x32_bf16 v[120:123], v[156:159], v[184:187], v[120:123]
	v_mfma_f32_16x16x32_bf16 v[108:111], v[148:151], v[192:195], v[108:111]
	v_mfma_f32_16x16x32_bf16 v[104:107], v[156:159], v[192:195], v[104:107]
	v_mfma_f32_16x16x32_bf16 v[92:95], v[148:151], v[202:205], v[92:95]
	v_mfma_f32_16x16x32_bf16 v[88:91], v[156:159], v[202:205], v[88:91]
	v_mfma_f32_16x16x32_bf16 v[76:79], v[148:151], v[214:217], v[76:79]
	v_mfma_f32_16x16x32_bf16 v[72:75], v[156:159], v[214:217], v[72:75]
	v_mfma_f32_16x16x32_bf16 v[124:127], v[152:155], v[188:191], v[124:127]
	v_mfma_f32_16x16x32_bf16 v[120:123], v[160:163], v[188:191], v[120:123]
	v_mfma_f32_16x16x32_bf16 v[108:111], v[152:155], v[196:199], v[108:111]
	v_mfma_f32_16x16x32_bf16 v[104:107], v[160:163], v[196:199], v[104:107]
	v_mfma_f32_16x16x32_bf16 v[92:95], v[152:155], v[210:213], v[92:95]
	v_mfma_f32_16x16x32_bf16 v[88:91], v[160:163], v[210:213], v[88:91]
	v_mfma_f32_16x16x32_bf16 v[76:79], v[152:155], v[218:221], v[76:79]
	v_mfma_f32_16x16x32_bf16 v[72:75], v[160:163], v[218:221], v[72:75]
	v_mfma_f32_16x16x32_bf16 v[116:119], v[164:167], v[184:187], v[116:119]
	v_mfma_f32_16x16x32_bf16 v[112:115], v[176:179], v[184:187], v[112:115]
	v_mfma_f32_16x16x32_bf16 v[100:103], v[164:167], v[192:195], v[100:103]
	v_mfma_f32_16x16x32_bf16 v[96:99], v[176:179], v[192:195], v[96:99]
	v_mfma_f32_16x16x32_bf16 v[84:87], v[164:167], v[202:205], v[84:87]
	v_mfma_f32_16x16x32_bf16 v[80:83], v[176:179], v[202:205], v[80:83]
	v_mfma_f32_16x16x32_bf16 v[68:71], v[164:167], v[214:217], v[68:71]
	v_mfma_f32_16x16x32_bf16 v[64:67], v[176:179], v[214:217], v[64:67]
	v_mfma_f32_16x16x32_bf16 v[116:119], v[168:171], v[188:191], v[116:119]
	v_mfma_f32_16x16x32_bf16 v[112:115], v[180:183], v[188:191], v[112:115]
	v_mfma_f32_16x16x32_bf16 v[100:103], v[168:171], v[196:199], v[100:103]
	v_mfma_f32_16x16x32_bf16 v[96:99], v[180:183], v[196:199], v[96:99]
	v_mfma_f32_16x16x32_bf16 v[84:87], v[168:171], v[210:213], v[84:87]
	v_mfma_f32_16x16x32_bf16 v[80:83], v[180:183], v[210:213], v[80:83]
	v_mfma_f32_16x16x32_bf16 v[68:71], v[168:171], v[218:221], v[68:71]
	v_mfma_f32_16x16x32_bf16 v[64:67], v[180:183], v[218:221], v[64:67]
	s_barrier
; #define PG8_STAGE(bufoff, gbase, voff) do { _Pragma("unroll") for (int _i = 0; _i < 2; ++_i) \
;         __builtin_amdgcn_global_load_lds((const unsigned*)((const char*)(gbase) + (voff)[_i]), (PG8_LAS unsigned*)(lds + (bufoff) + ldsw + _i * 8192), 16, 0, 0); } while (0)
; #define PG8_STAGEA(bufoff, gbase, voff) do { _Pragma("unroll") for (int _i = 0; _i < 2; ++_i) \
;         __builtin_amdgcn_global_load_lds((const unsigned*)((const char*)(gbase) + (voff)[_i]), (PG8_LAS unsigned*)(lds + (bufoff) + ldsw + _i * 8192), 16, 0, AUXA); } while (0)
; #define PG8_LDA(dst, b, h) do { _Pragma("unroll") for (int m = 0; m < 4; ++m) _Pragma("unroll") for (int k = 0; k < 2; ++k) dst[m][k] = *(const PG8_LAS bf16x8*)(lds + PG8_SA(b, h) + aoff + m * 2048 + k * 1024); } while (0)
; #define PG8_MMA(ai, bj, At, Bt) do { __builtin_amdgcn_s_setprio(1); _Pragma("unroll") for (int m = 0; m < 4; ++m) _Pragma("unroll") for (int n = 0; n < 2; ++n) _Pragma("unroll") for (int k = 0; k < 2; ++k) \
;         acc[ai][bj][m][n] = __builtin_amdgcn_mfma_f32_16x16x32_bf16(Bt[n][k], At[m][k], acc[ai][bj][m][n], 0, 0, 0); __builtin_amdgcn_s_setprio(0); } while (0)
; #define PG8_WAIT_V(n) asm volatile("s_waitcnt vmcnt(" #n ")" ::: "memory")
; #define PG8_WAIT_L(n) asm volatile("s_waitcnt lgkmcnt(" #n ")" ::: "memory")
; #define PG8_BAR __builtin_amdgcn_s_barrier()
; #define PG8_SCHED __builtin_amdgcn_sched_barrier(0)
;     ...
;         for (int t = 0; t < nt; t += 2) {
;     ...
;             PG8_LDA(At, 1, 1); PG8_STAGE(PG8_SB(1, 0), b3, voffB); PG8_STAGE(PG8_SB(1, 1), b3 + hstepB, voffB); PG8_STAGEA(PG8_SA(1, 0), a3, voffA);
;             PG8_WAIT_V(8); PG8_WAIT_L(0); PG8_BAR; PG8_MMA(1, 0, At, B0); PG8_MMA(1, 1, At, B1); PG8_BAR; PG8_SCHED;
	s_mov_b32 m0, s29
	v_lshl_add_u64 v[172:173], v[172:173], 0, s[10:11]
	s_add_u32 s14, s14, 0x10080
	ds_read_b128 v[184:187], v144 offset:49152
	ds_read_b128 v[188:191], v144 offset:50176
	ds_read_b128 v[192:195], v144 offset:51200
	ds_read_b128 v[196:199], v144 offset:52224
	ds_read_b128 v[202:205], v144 offset:53248
	ds_read_b128 v[210:213], v144 offset:54272
	ds_read_b128 v[214:217], v144 offset:55296
	ds_read_b128 v[218:221], v144 offset:56320
	global_load_lds_dwordx4 v[172:173], off
	v_lshl_add_u64 v[172:173], v[206:207], 0, s[10:11]
	s_mov_b32 m0, s30
	s_addc_u32 s15, s15, 0
	global_load_lds_dwordx4 v[172:173], off
	v_lshl_add_u64 v[172:173], s[14:15], 0, v[134:135]
	s_mov_b32 m0, s31
	s_nop 0
	global_load_lds_dwordx4 v[172:173], off
	v_lshl_add_u64 v[172:173], s[14:15], 0, v[130:131]
	s_mov_b32 m0, s34
	s_nop 0
	global_load_lds_dwordx4 v[172:173], off
	v_lshl_add_u64 v[172:173], v[222:223], 0, s[10:11]
	s_mov_b32 m0, s20
	s_nop 0
	global_load_lds_dwordx4 v[172:173], off
	v_lshl_add_u64 v[172:173], v[224:225], 0, s[10:11]
	s_mov_b32 m0, s21
	s_nop 0
	global_load_lds_dwordx4 v[172:173], off
	s_waitcnt vmcnt(8)
	s_waitcnt lgkmcnt(0)
	s_barrier
	s_waitcnt lgkmcnt(0)
	v_mfma_f32_16x16x32_bf16 v[60:63], v[148:151], v[184:187], v[60:63]
	v_mfma_f32_16x16x32_bf16 v[56:59], v[156:159], v[184:187], v[56:59]
	v_mfma_f32_16x16x32_bf16 v[44:47], v[148:151], v[192:195], v[44:47]
	v_mfma_f32_16x16x32_bf16 v[40:43], v[156:159], v[192:195], v[40:43]
	v_mfma_f32_16x16x32_bf16 v[28:31], v[148:151], v[202:205], v[28:31]
	v_mfma_f32_16x16x32_bf16 v[24:27], v[156:159], v[202:205], v[24:27]
	v_mfma_f32_16x16x32_bf16 v[12:15], v[148:151], v[214:217], v[12:15]
	v_mfma_f32_16x16x32_bf16 v[8:11], v[156:159], v[214:217], v[8:11]
	v_mfma_f32_16x16x32_bf16 v[60:63], v[152:155], v[188:191], v[60:63]
	v_mfma_f32_16x16x32_bf16 v[56:59], v[160:163], v[188:191], v[56:59]
	v_mfma_f32_16x16x32_bf16 v[44:47], v[152:155], v[196:199], v[44:47]
	v_mfma_f32_16x16x32_bf16 v[40:43], v[160:163], v[196:199], v[40:43]
	v_mfma_f32_16x16x32_bf16 v[28:31], v[152:155], v[210:213], v[28:31]
	v_mfma_f32_16x16x32_bf16 v[24:27], v[160:163], v[210:213], v[24:27]
	v_mfma_f32_16x16x32_bf16 v[12:15], v[152:155], v[218:221], v[12:15]
	v_mfma_f32_16x16x32_bf16 v[8:11], v[160:163], v[218:221], v[8:11]
	v_mfma_f32_16x16x32_bf16 v[52:55], v[164:167], v[184:187], v[52:55]
	v_mfma_f32_16x16x32_bf16 v[48:51], v[176:179], v[184:187], v[48:51]
	v_mfma_f32_16x16x32_bf16 v[36:39], v[164:167], v[192:195], v[36:39]
	v_mfma_f32_16x16x32_bf16 v[32:35], v[176:179], v[192:195], v[32:35]
	v_mfma_f32_16x16x32_bf16 v[20:23], v[164:167], v[202:205], v[20:23]
	v_mfma_f32_16x16x32_bf16 v[16:19], v[176:179], v[202:205], v[16:19]
	v_mfma_f32_16x16x32_bf16 v[4:7], v[164:167], v[214:217], v[4:7]
	v_mfma_f32_16x16x32_bf16 v[0:3], v[176:179], v[214:217], v[0:3]
	v_mfma_f32_16x16x32_bf16 v[52:55], v[168:171], v[188:191], v[52:55]
	v_mfma_f32_16x16x32_bf16 v[48:51], v[180:183], v[188:191], v[48:51]
	v_mfma_f32_16x16x32_bf16 v[36:39], v[168:171], v[196:199], v[36:39]
	v_mfma_f32_16x16x32_bf16 v[32:35], v[180:183], v[196:199], v[32:35]
	v_mfma_f32_16x16x32_bf16 v[20:23], v[168:171], v[210:213], v[20:23]
	v_mfma_f32_16x16x32_bf16 v[16:19], v[180:183], v[210:213], v[16:19]
	v_mfma_f32_16x16x32_bf16 v[4:7], v[168:171], v[218:221], v[4:7]
	v_mfma_f32_16x16x32_bf16 v[0:3], v[180:183], v[218:221], v[0:3]
	s_barrier
	s_add_i32 s22, s22, 2
	s_add_u32 s12, s12, 0x100
	s_addc_u32 s13, s13, 0
	s_cmp_gt_u32 s22, 13
	s_cbranch_scc0 .LBB0_758
	s_setprio 0
	v_readlane_b32 s1, v255, 10
	s_cmpk_lt_u32 s1, 0x100
	s_cbranch_scc0 .LBB0_761
	s_barrier

; #define PG8_STAGEA(bufoff, gbase, voff) do { _Pragma("unroll") for (int _i = 0; _i < 2; ++_i) \
;         __builtin_amdgcn_global_load_lds((const unsigned*)((const char*)(gbase) + (voff)[_i]), (PG8_LAS unsigned*)(lds + (bufoff) + ldsw + _i * 8192), 16, 0, AUXA); } while (0)
; #define PG8_LDA(dst, b, h) do { _Pragma("unroll") for (int m = 0; m < 4; ++m) _Pragma("unroll") for (int k = 0; k < 2; ++k) dst[m][k] = *(const PG8_LAS bf16x8*)(lds + PG8_SA(b, h) + aoff + m * 2048 + k * 1024); } while (0)
; #define PG8_LDB(dst, b, h) do { _Pragma("unroll") for (int n = 0; n < 2; ++n) _Pragma("unroll") for (int k = 0; k < 2; ++k) dst[n][k] = *(const PG8_LAS bf16x8*)(lds + PG8_SB(b, h) + boff + n * 2048 + k * 1024); } while (0)
; #define PG8_MMA(ai, bj, At, Bt) do { __builtin_amdgcn_s_setprio(1); _Pragma("unroll") for (int m = 0; m < 4; ++m) _Pragma("unroll") for (int n = 0; n < 2; ++n) _Pragma("unroll") for (int k = 0; k < 2; ++k) \
;         acc[ai][bj][m][n] = __builtin_amdgcn_mfma_f32_16x16x32_bf16(Bt[n][k], At[m][k], acc[ai][bj][m][n], 0, 0, 0); __builtin_amdgcn_s_setprio(0); } while (0)
; #define PG8_WAIT_V(n) asm volatile("s_waitcnt vmcnt(" #n ")" ::: "memory")
; #define PG8_WAIT_L(n) asm volatile("s_waitcnt lgkmcnt(" #n ")" ::: "memory")
; #define PG8_BAR __builtin_amdgcn_s_barrier()
; #define PG8_SCHED __builtin_amdgcn_sched_barrier(0)
;     ...
;     f32x4 acc[2][2][4][2];
; #pragma unroll
;     for (int a = 0; a < 2; ++a)
; #pragma unroll
;         for (int b = 0; b < 2; ++b)
; #pragma unroll
;             for (int m = 0; m < 4; ++m)
; #pragma unroll
;                 for (int n = 0; n < 2; ++n) acc[a][b][m][n] = (f32x4){0.f, 0.f, 0.f, 0.f};
;     bf16x8 At[4][2], B0[2][2], B1[2][2];
;     const char* cA = (const char*)g.A + (size_t)cur.pm * tstep + (size_t)cur.k0 * (BK * 2); const char* cB = (const char*)g.Bt + (size_t)cur.pn * tstep + (size_t)cur.k0 * (BK * 2);
;     ...
;             PG8_LDB(B0, 0, 0); PG8_LDB(B1, 0, 1); PG8_SCHED; PG8_LDA(At, 0, 0); PG8_STAGEA(PG8_SA(1, 1), a1 + hstep, voffA);
;             PG8_WAIT_V(8); PG8_WAIT_L(0); PG8_BAR; PG8_MMA(0, 0, At, B0); PG8_MMA(0, 1, At, B1); PG8_BAR; PG8_SCHED;
.LBB0_853:
	s_ashr_i32 s25, s24, 31
	s_lshl_b64 s[26:27], s[24:25], 19
	s_add_u32 s26, s6, s26
	s_addc_u32 s27, s7, s27
	s_and_b64 s[28:29], s[4:5], exec
	s_cselect_b32 s15, s27, s35
	s_cselect_b32 s25, s26, s34
	s_ashr_i32 s23, s22, 31
	s_lshl_b64 s[28:29], s[22:23], 19
	s_add_u32 s28, s3, s28
	s_addc_u32 s29, s42, s29
	s_and_b64 s[38:39], s[4:5], exec
	s_cselect_b32 s23, s29, s37
	s_cselect_b32 s31, s28, s36
	s_add_u32 s34, s34, 0x40080
	s_addc_u32 s35, s35, 0
	s_add_u32 s56, s36, 0x100
	v_mov_b32_e32 v0, 0
	s_addc_u32 s57, s37, 0
	s_mov_b32 s58, -2
	s_waitcnt lgkmcnt(0)
	v_mov_b32_e32 v1, v0
	v_mov_b32_e32 v2, v0
	v_mov_b32_e32 v3, v0
	v_mov_b32_e32 v4, v0
	v_mov_b32_e32 v5, v0
	v_mov_b32_e32 v6, v0
	v_mov_b32_e32 v7, v0
	v_mov_b32_e32 v16, v0
	v_mov_b32_e32 v17, v0
	v_mov_b32_e32 v18, v0
	v_mov_b32_e32 v19, v0
	v_mov_b32_e32 v20, v0
	v_mov_b32_e32 v21, v0
	v_mov_b32_e32 v22, v0
	v_mov_b32_e32 v23, v0
	v_mov_b32_e32 v32, v0
	v_mov_b32_e32 v33, v0
	v_mov_b32_e32 v34, v0
	v_mov_b32_e32 v35, v0
	v_mov_b32_e32 v36, v0
	v_mov_b32_e32 v37, v0
	v_mov_b32_e32 v38, v0
	v_mov_b32_e32 v39, v0
	v_mov_b32_e32 v48, v0
	v_mov_b32_e32 v49, v0
	v_mov_b32_e32 v50, v0
	v_mov_b32_e32 v51, v0
	v_mov_b32_e32 v52, v0
	v_mov_b32_e32 v53, v0
	v_mov_b32_e32 v54, v0
	v_mov_b32_e32 v55, v0
	v_mov_b32_e32 v8, v0
	v_mov_b32_e32 v9, v0
	v_mov_b32_e32 v10, v0
	v_mov_b32_e32 v11, v0
	v_mov_b32_e32 v12, v0
	v_mov_b32_e32 v13, v0
	v_mov_b32_e32 v14, v0
	v_mov_b32_e32 v15, v0
	v_mov_b32_e32 v24, v0
	v_mov_b32_e32 v25, v0
	v_mov_b32_e32 v26, v0
	v_mov_b32_e32 v27, v0
	v_mov_b32_e32 v28, v0
	v_mov_b32_e32 v29, v0
	v_mov_b32_e32 v30, v0
	v_mov_b32_e32 v31, v0
	v_mov_b32_e32 v40, v0
	v_mov_b32_e32 v41, v0
	v_mov_b32_e32 v42, v0
	v_mov_b32_e32 v43, v0
	v_mov_b32_e32 v44, v0
	v_mov_b32_e32 v45, v0
	v_mov_b32_e32 v46, v0
	v_mov_b32_e32 v47, v0
	v_mov_b32_e32 v56, v0
	v_mov_b32_e32 v57, v0
	v_mov_b32_e32 v58, v0
	v_mov_b32_e32 v59, v0
	v_mov_b32_e32 v60, v0
	v_mov_b32_e32 v61, v0
	v_mov_b32_e32 v62, v0
	v_mov_b32_e32 v63, v0
	v_mov_b32_e32 v64, v0
	v_mov_b32_e32 v65, v0
	v_mov_b32_e32 v66, v0
	v_mov_b32_e32 v67, v0
	v_mov_b32_e32 v68, v0
	v_mov_b32_e32 v69, v0
	v_mov_b32_e32 v70, v0
	v_mov_b32_e32 v71, v0
	v_mov_b32_e32 v80, v0
	v_mov_b32_e32 v81, v0
	v_mov_b32_e32 v82, v0
	v_mov_b32_e32 v83, v0
	v_mov_b32_e32 v84, v0
	v_mov_b32_e32 v85, v0
	v_mov_b32_e32 v86, v0
	v_mov_b32_e32 v87, v0
	v_mov_b32_e32 v96, v0
	v_mov_b32_e32 v97, v0
	v_mov_b32_e32 v98, v0
	v_mov_b32_e32 v99, v0
	v_mov_b32_e32 v100, v0
	v_mov_b32_e32 v101, v0
	v_mov_b32_e32 v102, v0
	v_mov_b32_e32 v103, v0
	v_mov_b32_e32 v112, v0
	v_mov_b32_e32 v113, v0
	v_mov_b32_e32 v114, v0
	v_mov_b32_e32 v115, v0
	v_mov_b32_e32 v116, v0
	v_mov_b32_e32 v117, v0
	v_mov_b32_e32 v118, v0
	v_mov_b32_e32 v119, v0
	v_mov_b32_e32 v72, v0
	v_mov_b32_e32 v73, v0
	v_mov_b32_e32 v74, v0
	v_mov_b32_e32 v75, v0
	v_mov_b32_e32 v76, v0
	v_mov_b32_e32 v77, v0
	v_mov_b32_e32 v78, v0
	v_mov_b32_e32 v79, v0
	v_mov_b32_e32 v88, v0
	v_mov_b32_e32 v89, v0
	v_mov_b32_e32 v90, v0
	v_mov_b32_e32 v91, v0
	v_mov_b32_e32 v92, v0
	v_mov_b32_e32 v93, v0
	v_mov_b32_e32 v94, v0
	v_mov_b32_e32 v95, v0
	v_mov_b32_e32 v104, v0
	v_mov_b32_e32 v105, v0
	v_mov_b32_e32 v106, v0
	v_mov_b32_e32 v107, v0
	v_mov_b32_e32 v108, v0
	v_mov_b32_e32 v109, v0
	v_mov_b32_e32 v110, v0
	v_mov_b32_e32 v111, v0
	v_mov_b32_e32 v120, v0
	v_mov_b32_e32 v121, v0
	v_mov_b32_e32 v122, v0
	v_mov_b32_e32 v123, v0
	v_mov_b32_e32 v124, v0
	v_mov_b32_e32 v125, v0
	v_mov_b32_e32 v126, v0
	v_mov_b32_e32 v127, v0
	v_readlane_b32 s98, v255, 17
	s_cmp_lg_u32 s98, 1
	s_cbranch_scc1 .Lsprio_3
	s_setprio 1
.Lsprio_3:
.LBB0_854:
	ds_read_b128 v[142:145], v151
	ds_read_b128 v[154:157], v151 offset:1024
	ds_read_b128 v[158:161], v151 offset:2048
	ds_read_b128 v[162:165], v151 offset:3072
	ds_read_b128 v[166:169], v152
	ds_read_b128 v[170:173], v152 offset:1024
	ds_read_b128 v[176:179], v152 offset:2048
	ds_read_b128 v[180:183], v152 offset:3072
	s_add_u32 s36, s34, 0xfffc0080
	s_addc_u32 s37, s35, -1
	s_cmp_eq_u32 s58, 12
	s_cselect_b32 s39, s15, s37
	s_cselect_b32 s38, s25, s36
	s_cselect_b32 s37, s23, s57
	s_cselect_b32 s36, s31, s56
	v_lshl_add_u64 v[206:207], s[34:35], 0, v[136:137]
	s_add_i32 m0, s40, 0xc000
	ds_read_b128 v[184:187], v153
	ds_read_b128 v[188:191], v153 offset:1024
	ds_read_b128 v[192:195], v153 offset:2048
	ds_read_b128 v[196:199], v153 offset:3072
	ds_read_b128 v[202:205], v153 offset:4096
	ds_read_b128 v[210:213], v153 offset:5120
	ds_read_b128 v[214:217], v153 offset:6144
	ds_read_b128 v[218:221], v153 offset:7168
	global_load_lds_dwordx4 v[206:207], off
	v_lshl_add_u64 v[206:207], s[34:35], 0, v[138:139]
	s_add_i32 m0, s40, 0xe000
	s_nop 0
	global_load_lds_dwordx4 v[206:207], off
	s_waitcnt vmcnt(8)
	s_waitcnt lgkmcnt(0)
	s_barrier
; #define PG8_STAGE(bufoff, gbase, voff) do { _Pragma("unroll") for (int _i = 0; _i < 2; ++_i) \
;         __builtin_amdgcn_global_load_lds((const unsigned*)((const char*)(gbase) + (voff)[_i]), (PG8_LAS unsigned*)(lds + (bufoff) + ldsw + _i * 8192), 16, 0, 0); } while (0)
; #define PG8_STAGEA(bufoff, gbase, voff) do { _Pragma("unroll") for (int _i = 0; _i < 2; ++_i) \
;         __builtin_amdgcn_global_load_lds((const unsigned*)((const char*)(gbase) + (voff)[_i]), (PG8_LAS unsigned*)(lds + (bufoff) + ldsw + _i * 8192), 16, 0, AUXA); } while (0)
; #define PG8_LDA(dst, b, h) do { _Pragma("unroll") for (int m = 0; m < 4; ++m) _Pragma("unroll") for (int k = 0; k < 2; ++k) dst[m][k] = *(const PG8_LAS bf16x8*)(lds + PG8_SA(b, h) + aoff + m * 2048 + k * 1024); } while (0)
; #define PG8_MMA(ai, bj, At, Bt) do { __builtin_amdgcn_s_setprio(1); _Pragma("unroll") for (int m = 0; m < 4; ++m) _Pragma("unroll") for (int n = 0; n < 2; ++n) _Pragma("unroll") for (int k = 0; k < 2; ++k) \
;         acc[ai][bj][m][n] = __builtin_amdgcn_mfma_f32_16x16x32_bf16(Bt[n][k], At[m][k], acc[ai][bj][m][n], 0, 0, 0); __builtin_amdgcn_s_setprio(0); } while (0)
; #define PG8_WAIT_V(n) asm volatile("s_waitcnt vmcnt(" #n ")" ::: "memory")
; #define PG8_WAIT_L(n) asm volatile("s_waitcnt lgkmcnt(" #n ")" ::: "memory")
; #define PG8_BAR __builtin_amdgcn_s_barrier()
; #define PG8_SCHED __builtin_amdgcn_sched_barrier(0)
;     ...
;             PG8_WAIT_V(8); PG8_WAIT_L(0); PG8_BAR; PG8_MMA(0, 0, At, B0); PG8_MMA(0, 1, At, B1); PG8_BAR; PG8_SCHED;
;             PG8_LDA(At, 0, 1); PG8_STAGE(PG8_SB(0, 0), b2, voffB); PG8_STAGE(PG8_SB(0, 1), b2 + hstepB, voffB); PG8_STAGEA(PG8_SA(0, 0), a2, voffA);
;             PG8_WAIT_V(8); PG8_WAIT_L(0); PG8_BAR; PG8_MMA(1, 0, At, B0); PG8_MMA(1, 1, At, B1); PG8_BAR; PG8_SCHED;
	s_waitcnt lgkmcnt(0)
	v_mfma_f32_16x16x32_bf16 v[124:127], v[142:145], v[184:187], v[124:127]
	v_mfma_f32_16x16x32_bf16 v[120:123], v[158:161], v[184:187], v[120:123]
	v_mfma_f32_16x16x32_bf16 v[108:111], v[142:145], v[192:195], v[108:111]
	v_mfma_f32_16x16x32_bf16 v[104:107], v[158:161], v[192:195], v[104:107]
	v_mfma_f32_16x16x32_bf16 v[92:95], v[142:145], v[202:205], v[92:95]
	v_mfma_f32_16x16x32_bf16 v[88:91], v[158:161], v[202:205], v[88:91]
	v_mfma_f32_16x16x32_bf16 v[76:79], v[142:145], v[214:217], v[76:79]
	v_mfma_f32_16x16x32_bf16 v[72:75], v[158:161], v[214:217], v[72:75]
	v_mfma_f32_16x16x32_bf16 v[124:127], v[154:157], v[188:191], v[124:127]
	v_mfma_f32_16x16x32_bf16 v[120:123], v[162:165], v[188:191], v[120:123]
	v_mfma_f32_16x16x32_bf16 v[108:111], v[154:157], v[196:199], v[108:111]
	v_mfma_f32_16x16x32_bf16 v[104:107], v[162:165], v[196:199], v[104:107]
	v_mfma_f32_16x16x32_bf16 v[92:95], v[154:157], v[210:213], v[92:95]
	v_mfma_f32_16x16x32_bf16 v[88:91], v[162:165], v[210:213], v[88:91]
	v_mfma_f32_16x16x32_bf16 v[76:79], v[154:157], v[218:221], v[76:79]
	v_mfma_f32_16x16x32_bf16 v[72:75], v[162:165], v[218:221], v[72:75]
	v_mfma_f32_16x16x32_bf16 v[116:119], v[166:169], v[184:187], v[116:119]
	v_mfma_f32_16x16x32_bf16 v[112:115], v[176:179], v[184:187], v[112:115]
	v_mfma_f32_16x16x32_bf16 v[100:103], v[166:169], v[192:195], v[100:103]
	v_mfma_f32_16x16x32_bf16 v[96:99], v[176:179], v[192:195], v[96:99]
	v_mfma_f32_16x16x32_bf16 v[84:87], v[166:169], v[202:205], v[84:87]
	v_mfma_f32_16x16x32_bf16 v[80:83], v[176:179], v[202:205], v[80:83]
	v_mfma_f32_16x16x32_bf16 v[68:71], v[166:169], v[214:217], v[68:71]
	v_mfma_f32_16x16x32_bf16 v[64:67], v[176:179], v[214:217], v[64:67]
	v_mfma_f32_16x16x32_bf16 v[116:119], v[170:173], v[188:191], v[116:119]
	v_mfma_f32_16x16x32_bf16 v[112:115], v[180:183], v[188:191], v[112:115]
	v_mfma_f32_16x16x32_bf16 v[100:103], v[170:173], v[196:199], v[100:103]
	v_mfma_f32_16x16x32_bf16 v[96:99], v[180:183], v[196:199], v[96:99]
	v_mfma_f32_16x16x32_bf16 v[84:87], v[170:173], v[210:213], v[84:87]
	v_mfma_f32_16x16x32_bf16 v[80:83], v[180:183], v[210:213], v[80:83]
	v_mfma_f32_16x16x32_bf16 v[68:71], v[170:173], v[218:221], v[68:71]
	v_mfma_f32_16x16x32_bf16 v[64:67], v[180:183], v[218:221], v[64:67]
	s_barrier
	s_add_i32 s59, s54, s67
	v_lshl_add_u64 v[206:207], s[36:37], 0, v[130:131]
	s_mov_b32 m0, s59
	ds_read_b128 v[184:187], v153 offset:16384
	ds_read_b128 v[188:191], v153 offset:17408
	ds_read_b128 v[192:195], v153 offset:18432
	ds_read_b128 v[196:199], v153 offset:19456
	ds_read_b128 v[202:205], v153 offset:20480
	ds_read_b128 v[210:213], v153 offset:21504
	ds_read_b128 v[214:217], v153 offset:22528
	ds_read_b128 v[218:221], v153 offset:23552
	global_load_lds_dwordx4 v[206:207], off
	s_add_i32 m0, s59, 0x2000
	s_add_u32 s70, s36, 0x10000
	v_lshl_add_u64 v[222:223], s[36:37], 0, v[134:135]
	s_addc_u32 s71, s37, 0
	s_add_i32 s59, s55, s67
	global_load_lds_dwordx4 v[222:223], off
	v_lshl_add_u64 v[224:225], s[70:71], 0, v[130:131]
	s_mov_b32 m0, s59
	v_lshl_add_u64 v[226:227], s[38:39], 0, v[132:133]
	global_load_lds_dwordx4 v[224:225], off
	v_lshl_add_u64 v[224:225], s[70:71], 0, v[134:135]
	s_add_i32 m0, s59, 0x2000
	s_nop 0
	global_load_lds_dwordx4 v[224:225], off
	v_lshl_add_u64 v[224:225], s[38:39], 0, v[128:129]
	s_mov_b32 m0, s40
	s_nop 0
	global_load_lds_dwordx4 v[224:225], off
	s_mov_b32 m0, s41
	s_nop 0
	global_load_lds_dwordx4 v[226:227], off
	s_waitcnt vmcnt(8)
	s_waitcnt lgkmcnt(0)
	s_barrier
	s_waitcnt lgkmcnt(0)
	v_mfma_f32_16x16x32_bf16 v[60:63], v[142:145], v[184:187], v[60:63]
	v_mfma_f32_16x16x32_bf16 v[56:59], v[158:161], v[184:187], v[56:59]
	v_mfma_f32_16x16x32_bf16 v[44:47], v[142:145], v[192:195], v[44:47]
	v_mfma_f32_16x16x32_bf16 v[40:43], v[158:161], v[192:195], v[40:43]
	v_mfma_f32_16x16x32_bf16 v[28:31], v[142:145], v[202:205], v[28:31]
	v_mfma_f32_16x16x32_bf16 v[24:27], v[158:161], v[202:205], v[24:27]
	v_mfma_f32_16x16x32_bf16 v[12:15], v[142:145], v[214:217], v[12:15]
	v_mfma_f32_16x16x32_bf16 v[8:11], v[158:161], v[214:217], v[8:11]
	v_mfma_f32_16x16x32_bf16 v[60:63], v[154:157], v[188:191], v[60:63]
	v_mfma_f32_16x16x32_bf16 v[56:59], v[162:165], v[188:191], v[56:59]
	v_mfma_f32_16x16x32_bf16 v[44:47], v[154:157], v[196:199], v[44:47]
	v_mfma_f32_16x16x32_bf16 v[40:43], v[162:165], v[196:199], v[40:43]
	v_mfma_f32_16x16x32_bf16 v[28:31], v[154:157], v[210:213], v[28:31]
	v_mfma_f32_16x16x32_bf16 v[24:27], v[162:165], v[210:213], v[24:27]
	v_mfma_f32_16x16x32_bf16 v[12:15], v[154:157], v[218:221], v[12:15]
	v_mfma_f32_16x16x32_bf16 v[8:11], v[162:165], v[218:221], v[8:11]
	v_mfma_f32_16x16x32_bf16 v[52:55], v[166:169], v[184:187], v[52:55]
	v_mfma_f32_16x16x32_bf16 v[48:51], v[176:179], v[184:187], v[48:51]
	v_mfma_f32_16x16x32_bf16 v[36:39], v[166:169], v[192:195], v[36:39]
	v_mfma_f32_16x16x32_bf16 v[32:35], v[176:179], v[192:195], v[32:35]
	v_mfma_f32_16x16x32_bf16 v[20:23], v[166:169], v[202:205], v[20:23]
	v_mfma_f32_16x16x32_bf16 v[16:19], v[176:179], v[202:205], v[16:19]
	v_mfma_f32_16x16x32_bf16 v[4:7], v[166:169], v[214:217], v[4:7]
	v_mfma_f32_16x16x32_bf16 v[0:3], v[176:179], v[214:217], v[0:3]
	v_mfma_f32_16x16x32_bf16 v[52:55], v[170:173], v[188:191], v[52:55]
	v_mfma_f32_16x16x32_bf16 v[48:51], v[180:183], v[188:191], v[48:51]
	v_mfma_f32_16x16x32_bf16 v[36:39], v[170:173], v[196:199], v[36:39]
	v_mfma_f32_16x16x32_bf16 v[32:35], v[180:183], v[196:199], v[32:35]
	v_mfma_f32_16x16x32_bf16 v[20:23], v[170:173], v[210:213], v[20:23]
	v_mfma_f32_16x16x32_bf16 v[16:19], v[180:183], v[210:213], v[16:19]
	v_mfma_f32_16x16x32_bf16 v[4:7], v[170:173], v[218:221], v[4:7]
	v_mfma_f32_16x16x32_bf16 v[0:3], v[180:183], v[218:221], v[0:3]
	s_barrier
; #define PG8_STAGEA(bufoff, gbase, voff) do { _Pragma("unroll") for (int _i = 0; _i < 2; ++_i) \
;         __builtin_amdgcn_global_load_lds((const unsigned*)((const char*)(gbase) + (voff)[_i]), (PG8_LAS unsigned*)(lds + (bufoff) + ldsw + _i * 8192), 16, 0, AUXA); } while (0)
; #define PG8_LDA(dst, b, h) do { _Pragma("unroll") for (int m = 0; m < 4; ++m) _Pragma("unroll") for (int k = 0; k < 2; ++k) dst[m][k] = *(const PG8_LAS bf16x8*)(lds + PG8_SA(b, h) + aoff + m * 2048 + k * 1024); } while (0)
; #define PG8_LDB(dst, b, h) do { _Pragma("unroll") for (int n = 0; n < 2; ++n) _Pragma("unroll") for (int k = 0; k < 2; ++k) dst[n][k] = *(const PG8_LAS bf16x8*)(lds + PG8_SB(b, h) + boff + n * 2048 + k * 1024); } while (0)
; #define PG8_MMA(ai, bj, At, Bt) do { __builtin_amdgcn_s_setprio(1); _Pragma("unroll") for (int m = 0; m < 4; ++m) _Pragma("unroll") for (int n = 0; n < 2; ++n) _Pragma("unroll") for (int k = 0; k < 2; ++k) \
;         acc[ai][bj][m][n] = __builtin_amdgcn_mfma_f32_16x16x32_bf16(Bt[n][k], At[m][k], acc[ai][bj][m][n], 0, 0, 0); __builtin_amdgcn_s_setprio(0); } while (0)
; #define PG8_WAIT_V(n) asm volatile("s_waitcnt vmcnt(" #n ")" ::: "memory")
; #define PG8_WAIT_L(n) asm volatile("s_waitcnt lgkmcnt(" #n ")" ::: "memory")
; #define PG8_BAR __builtin_amdgcn_s_barrier()
; #define PG8_SCHED __builtin_amdgcn_sched_barrier(0)
;     ...
;             PG8_LDB(B0, 1, 0); PG8_LDB(B1, 1, 1); PG8_SCHED; PG8_LDA(At, 1, 0); PG8_STAGEA(PG8_SA(0, 1), a2 + hstep, voffA);
;             PG8_WAIT_V(8); PG8_WAIT_L(0); PG8_BAR; PG8_MMA(0, 0, At, B0); PG8_MMA(0, 1, At, B1); PG8_BAR; PG8_SCHED;
	s_add_i32 s59, 0, 0x18000
	s_add_i32 s70, 0, 0x1c000
	v_add_u32_e32 v162, s59, v147
	v_add_u32_e32 v174, s70, v147
	ds_read_b128 v[142:145], v162
	ds_read_b128 v[154:157], v162 offset:1024
	ds_read_b128 v[158:161], v162 offset:2048
	ds_read_b128 v[162:165], v162 offset:3072
	ds_read_b128 v[166:169], v174
	ds_read_b128 v[170:173], v174 offset:1024
	ds_read_b128 v[176:179], v174 offset:2048
	ds_read_b128 v[180:183], v174 offset:3072
	s_add_u32 s38, s38, 0x40000
	s_addc_u32 s39, s39, 0
	s_mov_b32 m0, s43
	v_lshl_add_u64 v[228:229], s[38:39], 0, v[128:129]
	ds_read_b128 v[184:187], v153 offset:32768
	ds_read_b128 v[188:191], v153 offset:33792
	ds_read_b128 v[192:195], v153 offset:34816
	ds_read_b128 v[196:199], v153 offset:35840
	ds_read_b128 v[202:205], v153 offset:36864
	ds_read_b128 v[210:213], v153 offset:37888
	ds_read_b128 v[214:217], v153 offset:38912
	ds_read_b128 v[218:221], v153 offset:39936
	global_load_lds_dwordx4 v[228:229], off
	v_lshl_add_u64 v[228:229], s[38:39], 0, v[132:133]
	s_mov_b32 m0, s44
	s_nop 0
	global_load_lds_dwordx4 v[228:229], off
	s_waitcnt vmcnt(8)
	s_waitcnt lgkmcnt(0)
	s_barrier
	s_waitcnt lgkmcnt(0)
	v_mfma_f32_16x16x32_bf16 v[124:127], v[142:145], v[184:187], v[124:127]
	v_mfma_f32_16x16x32_bf16 v[120:123], v[158:161], v[184:187], v[120:123]
	v_mfma_f32_16x16x32_bf16 v[108:111], v[142:145], v[192:195], v[108:111]
	v_mfma_f32_16x16x32_bf16 v[104:107], v[158:161], v[192:195], v[104:107]
	v_mfma_f32_16x16x32_bf16 v[92:95], v[142:145], v[202:205], v[92:95]
	v_mfma_f32_16x16x32_bf16 v[88:91], v[158:161], v[202:205], v[88:91]
	v_mfma_f32_16x16x32_bf16 v[76:79], v[142:145], v[214:217], v[76:79]
	v_mfma_f32_16x16x32_bf16 v[72:75], v[158:161], v[214:217], v[72:75]
	v_mfma_f32_16x16x32_bf16 v[124:127], v[154:157], v[188:191], v[124:127]
	v_mfma_f32_16x16x32_bf16 v[120:123], v[162:165], v[188:191], v[120:123]
	v_mfma_f32_16x16x32_bf16 v[108:111], v[154:157], v[196:199], v[108:111]
	v_mfma_f32_16x16x32_bf16 v[104:107], v[162:165], v[196:199], v[104:107]
	v_mfma_f32_16x16x32_bf16 v[92:95], v[154:157], v[210:213], v[92:95]
	v_mfma_f32_16x16x32_bf16 v[88:91], v[162:165], v[210:213], v[88:91]
	v_mfma_f32_16x16x32_bf16 v[76:79], v[154:157], v[218:221], v[76:79]
	v_mfma_f32_16x16x32_bf16 v[72:75], v[162:165], v[218:221], v[72:75]
	v_mfma_f32_16x16x32_bf16 v[116:119], v[166:169], v[184:187], v[116:119]
	v_mfma_f32_16x16x32_bf16 v[112:115], v[176:179], v[184:187], v[112:115]
	v_mfma_f32_16x16x32_bf16 v[100:103], v[166:169], v[192:195], v[100:103]
	v_mfma_f32_16x16x32_bf16 v[96:99], v[176:179], v[192:195], v[96:99]
	v_mfma_f32_16x16x32_bf16 v[84:87], v[166:169], v[202:205], v[84:87]
	v_mfma_f32_16x16x32_bf16 v[80:83], v[176:179], v[202:205], v[80:83]
	v_mfma_f32_16x16x32_bf16 v[68:71], v[166:169], v[214:217], v[68:71]
	v_mfma_f32_16x16x32_bf16 v[64:67], v[176:179], v[214:217], v[64:67]
	v_mfma_f32_16x16x32_bf16 v[116:119], v[170:173], v[188:191], v[116:119]
	v_mfma_f32_16x16x32_bf16 v[112:115], v[180:183], v[188:191], v[112:115]
	v_mfma_f32_16x16x32_bf16 v[100:103], v[170:173], v[196:199], v[100:103]
	v_mfma_f32_16x16x32_bf16 v[96:99], v[180:183], v[196:199], v[96:99]
	v_mfma_f32_16x16x32_bf16 v[84:87], v[170:173], v[210:213], v[84:87]
	v_mfma_f32_16x16x32_bf16 v[80:83], v[180:183], v[210:213], v[80:83]
	v_mfma_f32_16x16x32_bf16 v[68:71], v[170:173], v[218:221], v[68:71]
	v_mfma_f32_16x16x32_bf16 v[64:67], v[180:183], v[218:221], v[64:67]
	s_barrier
; #define PG8_STAGE(bufoff, gbase, voff) do { _Pragma("unroll") for (int _i = 0; _i < 2; ++_i) \
;         __builtin_amdgcn_global_load_lds((const unsigned*)((const char*)(gbase) + (voff)[_i]), (PG8_LAS unsigned*)(lds + (bufoff) + ldsw + _i * 8192), 16, 0, 0); } while (0)
; #define PG8_STAGEA(bufoff, gbase, voff) do { _Pragma("unroll") for (int _i = 0; _i < 2; ++_i) \
;         __builtin_amdgcn_global_load_lds((const unsigned*)((const char*)(gbase) + (voff)[_i]), (PG8_LAS unsigned*)(lds + (bufoff) + ldsw + _i * 8192), 16, 0, AUXA); } while (0)
; #define PG8_LDA(dst, b, h) do { _Pragma("unroll") for (int m = 0; m < 4; ++m) _Pragma("unroll") for (int k = 0; k < 2; ++k) dst[m][k] = *(const PG8_LAS bf16x8*)(lds + PG8_SA(b, h) + aoff + m * 2048 + k * 1024); } while (0)
; #define PG8_MMA(ai, bj, At, Bt) do { __builtin_amdgcn_s_setprio(1); _Pragma("unroll") for (int m = 0; m < 4; ++m) _Pragma("unroll") for (int n = 0; n < 2; ++n) _Pragma("unroll") for (int k = 0; k < 2; ++k) \
;         acc[ai][bj][m][n] = __builtin_amdgcn_mfma_f32_16x16x32_bf16(Bt[n][k], At[m][k], acc[ai][bj][m][n], 0, 0, 0); __builtin_amdgcn_s_setprio(0); } while (0)
; #define PG8_WAIT_V(n) asm volatile("s_waitcnt vmcnt(" #n ")" ::: "memory")
; #define PG8_WAIT_L(n) asm volatile("s_waitcnt lgkmcnt(" #n ")" ::: "memory")
; #define PG8_BAR __builtin_amdgcn_s_barrier()
; #define PG8_SCHED __builtin_amdgcn_sched_barrier(0)
;     ...
;         for (int t = 0; t < nt; t += 2) {
;     ...
;             PG8_LDA(At, 1, 1); PG8_STAGE(PG8_SB(1, 0), b3, voffB); PG8_STAGE(PG8_SB(1, 1), b3 + hstepB, voffB); PG8_STAGEA(PG8_SA(1, 0), a3, voffA);
;             PG8_WAIT_V(8); PG8_WAIT_L(0); PG8_BAR; PG8_MMA(1, 0, At, B0); PG8_MMA(1, 1, At, B1); PG8_BAR; PG8_SCHED;
	s_add_i32 s38, s59, s67
	v_lshl_add_u64 v[206:207], v[206:207], 0, s[18:19]
	s_mov_b32 m0, s38
	ds_read_b128 v[184:187], v153 offset:49152
	ds_read_b128 v[188:191], v153 offset:50176
	ds_read_b128 v[192:195], v153 offset:51200
	ds_read_b128 v[196:199], v153 offset:52224
	ds_read_b128 v[202:205], v153 offset:53248
	ds_read_b128 v[210:213], v153 offset:54272
	ds_read_b128 v[214:217], v153 offset:55296
	ds_read_b128 v[218:221], v153 offset:56320
	global_load_lds_dwordx4 v[206:207], off
	s_add_i32 m0, s38, 0x2000
	s_add_u32 s36, s36, 0x10080
	v_lshl_add_u64 v[206:207], v[222:223], 0, s[18:19]
	s_addc_u32 s37, s37, 0
	s_add_i32 s38, s70, s67
	global_load_lds_dwordx4 v[206:207], off
	v_lshl_add_u64 v[206:207], s[36:37], 0, v[130:131]
	s_mov_b32 m0, s38
	s_nop 0
	global_load_lds_dwordx4 v[206:207], off
	v_lshl_add_u64 v[206:207], s[36:37], 0, v[134:135]
	s_add_i32 m0, s38, 0x2000
	s_nop 0
	global_load_lds_dwordx4 v[206:207], off
	v_lshl_add_u64 v[206:207], v[224:225], 0, s[18:19]
	s_mov_b32 m0, s45
	s_nop 0
	global_load_lds_dwordx4 v[206:207], off
	v_lshl_add_u64 v[206:207], v[226:227], 0, s[18:19]
	s_mov_b32 m0, s46
	s_nop 0
	global_load_lds_dwordx4 v[206:207], off
	s_waitcnt vmcnt(8)
	s_waitcnt lgkmcnt(0)
	s_barrier
	s_waitcnt lgkmcnt(0)
	v_mfma_f32_16x16x32_bf16 v[60:63], v[142:145], v[184:187], v[60:63]
	v_mfma_f32_16x16x32_bf16 v[56:59], v[158:161], v[184:187], v[56:59]
	v_mfma_f32_16x16x32_bf16 v[44:47], v[142:145], v[192:195], v[44:47]
	v_mfma_f32_16x16x32_bf16 v[40:43], v[158:161], v[192:195], v[40:43]
	v_mfma_f32_16x16x32_bf16 v[28:31], v[142:145], v[202:205], v[28:31]
	v_mfma_f32_16x16x32_bf16 v[24:27], v[158:161], v[202:205], v[24:27]
	v_mfma_f32_16x16x32_bf16 v[12:15], v[142:145], v[214:217], v[12:15]
	v_mfma_f32_16x16x32_bf16 v[8:11], v[158:161], v[214:217], v[8:11]
	v_mfma_f32_16x16x32_bf16 v[60:63], v[154:157], v[188:191], v[60:63]
	v_mfma_f32_16x16x32_bf16 v[56:59], v[162:165], v[188:191], v[56:59]
	v_mfma_f32_16x16x32_bf16 v[44:47], v[154:157], v[196:199], v[44:47]
	v_mfma_f32_16x16x32_bf16 v[40:43], v[162:165], v[196:199], v[40:43]
	v_mfma_f32_16x16x32_bf16 v[28:31], v[154:157], v[210:213], v[28:31]
	v_mfma_f32_16x16x32_bf16 v[24:27], v[162:165], v[210:213], v[24:27]
	v_mfma_f32_16x16x32_bf16 v[12:15], v[154:157], v[218:221], v[12:15]
	v_mfma_f32_16x16x32_bf16 v[8:11], v[162:165], v[218:221], v[8:11]
	v_mfma_f32_16x16x32_bf16 v[52:55], v[166:169], v[184:187], v[52:55]
	v_mfma_f32_16x16x32_bf16 v[48:51], v[176:179], v[184:187], v[48:51]
	v_mfma_f32_16x16x32_bf16 v[36:39], v[166:169], v[192:195], v[36:39]
	v_mfma_f32_16x16x32_bf16 v[32:35], v[176:179], v[192:195], v[32:35]
	v_mfma_f32_16x16x32_bf16 v[20:23], v[166:169], v[202:205], v[20:23]
	v_mfma_f32_16x16x32_bf16 v[16:19], v[176:179], v[202:205], v[16:19]
	v_mfma_f32_16x16x32_bf16 v[4:7], v[166:169], v[214:217], v[4:7]
	v_mfma_f32_16x16x32_bf16 v[0:3], v[176:179], v[214:217], v[0:3]
	v_mfma_f32_16x16x32_bf16 v[52:55], v[170:173], v[188:191], v[52:55]
	v_mfma_f32_16x16x32_bf16 v[48:51], v[180:183], v[188:191], v[48:51]
	v_mfma_f32_16x16x32_bf16 v[36:39], v[170:173], v[196:199], v[36:39]
	v_mfma_f32_16x16x32_bf16 v[32:35], v[180:183], v[196:199], v[32:35]
	v_mfma_f32_16x16x32_bf16 v[20:23], v[170:173], v[210:213], v[20:23]
	v_mfma_f32_16x16x32_bf16 v[16:19], v[180:183], v[210:213], v[16:19]
	v_mfma_f32_16x16x32_bf16 v[4:7], v[170:173], v[218:221], v[4:7]
	v_mfma_f32_16x16x32_bf16 v[0:3], v[180:183], v[218:221], v[0:3]
	s_barrier
	s_add_i32 s58, s58, 2
	s_add_u32 s34, s34, 0x100
	s_addc_u32 s35, s35, 0
	s_add_u32 s56, s56, 0x100
	s_addc_u32 s57, s57, 0
	s_cmp_gt_u32 s58, 13
	s_cbranch_scc0 .LBB0_854
	s_setprio 0
	s_and_b64 vcc, exec, s[20:21]
	s_cbranch_vccz .LBB0_857
	s_barrier

;     __host__ __device__ bool next(int i, Unit& u) const { return at((long)i * G + c, u); }
;     __host__ __device__ bool next(int i, Unit& u) const { if (i != 0 || c >= cnt) return false; u.pm = pm0 + c / nN; u.pn = c % nN; u.k0 = 0; u.nt = ntk; return true; }
; #define PG8_STAGE(bufoff, gbase, voff) do { _Pragma("unroll") for (int _i = 0; _i < 2; ++_i) \
;         __builtin_amdgcn_global_load_lds((const unsigned*)((const char*)(gbase) + (voff)[_i]), (PG8_LAS unsigned*)(lds + (bufoff) + ldsw + _i * 8192), 16, 0, 0); } while (0)
; #define PG8_STAGEA(bufoff, gbase, voff) do { _Pragma("unroll") for (int _i = 0; _i < 2; ++_i) \
;         __builtin_amdgcn_global_load_lds((const unsigned*)((const char*)(gbase) + (voff)[_i]), (PG8_LAS unsigned*)(lds + (bufoff) + ldsw + _i * 8192), 16, 0, AUXA); } while (0)
; #define PG8_LDA(dst, b, h) do { _Pragma("unroll") for (int m = 0; m < 4; ++m) _Pragma("unroll") for (int k = 0; k < 2; ++k) dst[m][k] = *(const PG8_LAS bf16x8*)(lds + PG8_SA(b, h) + aoff + m * 2048 + k * 1024); } while (0)
; #define PG8_WAIT_V(n) asm volatile("s_waitcnt vmcnt(" #n ")" ::: "memory")
;     ...
;         const bool has_next = S.next(ui + 1, nxt);
;         const char* nA = has_next ? (const char*)g.A + (size_t)nxt.pm * tstep + (size_t)nxt.k0 * (BK * 2) : cA; const char* nB = has_next ? (const char*)g.Bt + (size_t)nxt.pn * tstep + (size_t)nxt.k0 * (BK * 2) : cB;
;         const int nt = cur.nt;
;         for (int t = 0; t < nt; t += 2) {
;             const bool last = (t == nt - 2);
;             const char* a1 = cA + (size_t)(t + 1) * kstep;
;             const char* a2 = last ? nA : cA + (size_t)(t + 2) * kstep; const char* b2 = last ? nB : cB + (size_t)(t + 2) * kstep;
;             const char* a3 = a2 + kstep; const char* b3 = b2 + kstep;
;             if (last && has_next) S.a_ready(nxt);
;             if constexpr (SP2) {
;             PG8_LDB(B0, 0, 0); PG8_LDB(B1, 0, 1); PG8_SCHED; PG8_LDA(At, 0, 0); PG8_STAGEA(PG8_SA(1, 1), a1 + hstep, voffA);
;             PG8_WAIT_V(8); PG8_WAIT_L(0); PG8_BAR; PG8_MMA(0, 0, At, B0); PG8_MMA(0, 1, At, B1); PG8_BAR; PG8_SCHED;
;             PG8_LDA(At, 0, 1); PG8_STAGE(PG8_SB(0, 0), b2, voffB); PG8_STAGE(PG8_SB(0, 1), b2 + hstepB, voffB); PG8_STAGEA(PG8_SA(0, 0), a2, voffA);
;             PG8_WAIT_V(8); PG8_WAIT_L(0); PG8_BAR; PG8_MMA(1, 0, At, B0); PG8_MMA(1, 1, At, B1); PG8_BAR; PG8_SCHED;
.LBB0_887:
	s_add_u32 s54, s36, 0x100
	s_addc_u32 s55, s37, 0
	s_ashr_i32 s27, s26, 31
	s_lshl_b64 s[28:29], s[26:27], 19
	s_add_u32 s28, s6, s28
	s_addc_u32 s29, s7, s29
	s_and_b64 s[30:31], s[4:5], exec
	s_cselect_b32 s27, s29, s35
	s_cselect_b32 s56, s28, s34
	s_ashr_i32 s25, s24, 31
	s_lshl_b64 s[30:31], s[24:25], 19
	s_add_u32 s30, s3, s30
	s_addc_u32 s31, s42, s31
	s_and_b64 s[38:39], s[4:5], exec
	s_cselect_b32 s25, s31, s37
	s_cselect_b32 s57, s30, s36
	v_lshl_add_u64 v[142:143], s[34:35], 0, v[136:137]
	v_lshl_add_u64 v[144:145], s[34:35], 0, v[138:139]
	s_mov_b32 s58, -2
	s_mov_b64 s[36:37], 0
	v_readlane_b32 s98, v255, 17
	s_cmp_lg_u32 s98, 1
	s_cbranch_scc1 .Lsprio_4
	s_setprio 1
.Lsprio_4:
.LBB0_888:
	v_add_u32_e32 v162, s12, v148
	v_add_u32_e32 v174, s50, v148
	s_add_u32 s38, s34, s36
	ds_read_b128 v[150:153], v162
	ds_read_b128 v[154:157], v162 offset:1024
	ds_read_b128 v[158:161], v162 offset:2048
	ds_read_b128 v[162:165], v162 offset:3072
	ds_read_b128 v[166:169], v174
	ds_read_b128 v[170:173], v174 offset:1024
	ds_read_b128 v[176:179], v174 offset:2048
	ds_read_b128 v[180:183], v174 offset:3072
	s_addc_u32 s39, s35, s37
	s_add_u32 s38, s38, 0x100
	s_addc_u32 s39, s39, 0
	s_add_u32 s59, s54, s36
	s_addc_u32 s70, s55, s37
	s_cmpk_eq_i32 s36, 0x700
	s_cselect_b32 s41, s27, s39
	s_cselect_b32 s40, s56, s38
	s_cselect_b32 s39, s25, s70
	s_cselect_b32 s38, s57, s59
	v_lshl_add_u64 v[206:207], v[142:143], 0, s[36:37]
	s_add_i32 m0, s17, 0xc000
	ds_read_b128 v[184:187], v149
	ds_read_b128 v[188:191], v149 offset:1024
	ds_read_b128 v[192:195], v149 offset:2048
	ds_read_b128 v[196:199], v149 offset:3072
	ds_read_b128 v[202:205], v149 offset:4096
	ds_read_b128 v[210:213], v149 offset:5120
	ds_read_b128 v[214:217], v149 offset:6144
	ds_read_b128 v[218:221], v149 offset:7168
	global_load_lds_dwordx4 v[206:207], off
	v_lshl_add_u64 v[206:207], v[144:145], 0, s[36:37]
	s_add_i32 m0, s17, 0xe000
	s_nop 0
	global_load_lds_dwordx4 v[206:207], off
	s_waitcnt vmcnt(8)
	s_waitcnt lgkmcnt(0)
	s_barrier
	s_waitcnt lgkmcnt(0)
	v_mfma_f32_16x16x32_bf16 v[124:127], v[150:153], v[184:187], v[124:127]
	v_mfma_f32_16x16x32_bf16 v[120:123], v[158:161], v[184:187], v[120:123]
	v_mfma_f32_16x16x32_bf16 v[108:111], v[150:153], v[192:195], v[108:111]
	v_mfma_f32_16x16x32_bf16 v[104:107], v[158:161], v[192:195], v[104:107]
	v_mfma_f32_16x16x32_bf16 v[92:95], v[150:153], v[202:205], v[92:95]
	v_mfma_f32_16x16x32_bf16 v[88:91], v[158:161], v[202:205], v[88:91]
	v_mfma_f32_16x16x32_bf16 v[76:79], v[150:153], v[214:217], v[76:79]
	v_mfma_f32_16x16x32_bf16 v[72:75], v[158:161], v[214:217], v[72:75]
	v_mfma_f32_16x16x32_bf16 v[124:127], v[154:157], v[188:191], v[124:127]
	v_mfma_f32_16x16x32_bf16 v[120:123], v[162:165], v[188:191], v[120:123]
	v_mfma_f32_16x16x32_bf16 v[108:111], v[154:157], v[196:199], v[108:111]
	v_mfma_f32_16x16x32_bf16 v[104:107], v[162:165], v[196:199], v[104:107]
	v_mfma_f32_16x16x32_bf16 v[92:95], v[154:157], v[210:213], v[92:95]
	v_mfma_f32_16x16x32_bf16 v[88:91], v[162:165], v[210:213], v[88:91]
	v_mfma_f32_16x16x32_bf16 v[76:79], v[154:157], v[218:221], v[76:79]
	v_mfma_f32_16x16x32_bf16 v[72:75], v[162:165], v[218:221], v[72:75]
	v_mfma_f32_16x16x32_bf16 v[116:119], v[166:169], v[184:187], v[116:119]
	v_mfma_f32_16x16x32_bf16 v[112:115], v[176:179], v[184:187], v[112:115]
	v_mfma_f32_16x16x32_bf16 v[100:103], v[166:169], v[192:195], v[100:103]
	v_mfma_f32_16x16x32_bf16 v[96:99], v[176:179], v[192:195], v[96:99]
	v_mfma_f32_16x16x32_bf16 v[84:87], v[166:169], v[202:205], v[84:87]
	v_mfma_f32_16x16x32_bf16 v[80:83], v[176:179], v[202:205], v[80:83]
	v_mfma_f32_16x16x32_bf16 v[68:71], v[166:169], v[214:217], v[68:71]
	v_mfma_f32_16x16x32_bf16 v[64:67], v[176:179], v[214:217], v[64:67]
	v_mfma_f32_16x16x32_bf16 v[116:119], v[170:173], v[188:191], v[116:119]
	v_mfma_f32_16x16x32_bf16 v[112:115], v[180:183], v[188:191], v[112:115]
	v_mfma_f32_16x16x32_bf16 v[100:103], v[170:173], v[196:199], v[100:103]
	v_mfma_f32_16x16x32_bf16 v[96:99], v[180:183], v[196:199], v[96:99]
	v_mfma_f32_16x16x32_bf16 v[84:87], v[170:173], v[210:213], v[84:87]
	v_mfma_f32_16x16x32_bf16 v[80:83], v[180:183], v[210:213], v[80:83]
	v_mfma_f32_16x16x32_bf16 v[68:71], v[170:173], v[218:221], v[68:71]
	v_mfma_f32_16x16x32_bf16 v[64:67], v[180:183], v[218:221], v[64:67]
	s_barrier
	s_add_i32 s59, s12, s67
	v_lshl_add_u64 v[206:207], s[38:39], 0, v[132:133]
	s_mov_b32 m0, s59
	ds_read_b128 v[184:187], v149 offset:16384
	ds_read_b128 v[188:191], v149 offset:17408
	ds_read_b128 v[192:195], v149 offset:18432
	ds_read_b128 v[196:199], v149 offset:19456
	ds_read_b128 v[202:205], v149 offset:20480
	ds_read_b128 v[210:213], v149 offset:21504
	ds_read_b128 v[214:217], v149 offset:22528
	ds_read_b128 v[218:221], v149 offset:23552
	global_load_lds_dwordx4 v[206:207], off
	s_add_i32 m0, s59, 0x2000
	s_add_u32 s70, s38, 0x10000
	v_lshl_add_u64 v[222:223], s[38:39], 0, v[128:129]
	s_addc_u32 s71, s39, 0
	s_add_i32 s59, s50, s67
	global_load_lds_dwordx4 v[222:223], off
	v_lshl_add_u64 v[224:225], s[70:71], 0, v[132:133]
	s_mov_b32 m0, s59
	v_lshl_add_u64 v[226:227], s[40:41], 0, v[130:131]
	global_load_lds_dwordx4 v[224:225], off
	v_lshl_add_u64 v[224:225], s[70:71], 0, v[128:129]
	s_add_i32 m0, s59, 0x2000
	s_nop 0
	global_load_lds_dwordx4 v[224:225], off
	v_lshl_add_u64 v[224:225], s[40:41], 0, v[134:135]
	s_mov_b32 m0, s17
	s_nop 0
	global_load_lds_dwordx4 v[224:225], off
	s_mov_b32 m0, s43
	s_nop 0
	global_load_lds_dwordx4 v[226:227], off
	s_waitcnt vmcnt(8)
	s_waitcnt lgkmcnt(0)
	s_barrier
; #define PG8_STAGE(bufoff, gbase, voff) do { _Pragma("unroll") for (int _i = 0; _i < 2; ++_i) \
;         __builtin_amdgcn_global_load_lds((const unsigned*)((const char*)(gbase) + (voff)[_i]), (PG8_LAS unsigned*)(lds + (bufoff) + ldsw + _i * 8192), 16, 0, 0); } while (0)
; #define PG8_STAGEA(bufoff, gbase, voff) do { _Pragma("unroll") for (int _i = 0; _i < 2; ++_i) \
;         __builtin_amdgcn_global_load_lds((const unsigned*)((const char*)(gbase) + (voff)[_i]), (PG8_LAS unsigned*)(lds + (bufoff) + ldsw + _i * 8192), 16, 0, AUXA); } while (0)
; #define PG8_LDA(dst, b, h) do { _Pragma("unroll") for (int m = 0; m < 4; ++m) _Pragma("unroll") for (int k = 0; k < 2; ++k) dst[m][k] = *(const PG8_LAS bf16x8*)(lds + PG8_SA(b, h) + aoff + m * 2048 + k * 1024); } while (0)
; #define PG8_LDB(dst, b, h) do { _Pragma("unroll") for (int n = 0; n < 2; ++n) _Pragma("unroll") for (int k = 0; k < 2; ++k) dst[n][k] = *(const PG8_LAS bf16x8*)(lds + PG8_SB(b, h) + boff + n * 2048 + k * 1024); } while (0)
; #define PG8_MMA(ai, bj, At, Bt) do { __builtin_amdgcn_s_setprio(1); _Pragma("unroll") for (int m = 0; m < 4; ++m) _Pragma("unroll") for (int n = 0; n < 2; ++n) _Pragma("unroll") for (int k = 0; k < 2; ++k) \
;         acc[ai][bj][m][n] = __builtin_amdgcn_mfma_f32_16x16x32_bf16(Bt[n][k], At[m][k], acc[ai][bj][m][n], 0, 0, 0); __builtin_amdgcn_s_setprio(0); } while (0)
; #define PG8_WAIT_V(n) asm volatile("s_waitcnt vmcnt(" #n ")" ::: "memory")
; #define PG8_WAIT_L(n) asm volatile("s_waitcnt lgkmcnt(" #n ")" ::: "memory")
; #define PG8_BAR __builtin_amdgcn_s_barrier()
; #define PG8_SCHED __builtin_amdgcn_sched_barrier(0)
;     ...
;             PG8_WAIT_V(8); PG8_WAIT_L(0); PG8_BAR; PG8_MMA(0, 0, At, B0); PG8_MMA(0, 1, At, B1); PG8_BAR; PG8_SCHED;
;             PG8_LDA(At, 0, 1); PG8_STAGE(PG8_SB(0, 0), b2, voffB); PG8_STAGE(PG8_SB(0, 1), b2 + hstepB, voffB); PG8_STAGEA(PG8_SA(0, 0), a2, voffA);
;             PG8_WAIT_V(8); PG8_WAIT_L(0); PG8_BAR; PG8_MMA(1, 0, At, B0); PG8_MMA(1, 1, At, B1); PG8_BAR; PG8_SCHED;
;             PG8_LDB(B0, 1, 0); PG8_LDB(B1, 1, 1); PG8_SCHED; PG8_LDA(At, 1, 0); PG8_STAGEA(PG8_SA(0, 1), a2 + hstep, voffA);
;             PG8_WAIT_V(8); PG8_WAIT_L(0); PG8_BAR; PG8_MMA(0, 0, At, B0); PG8_MMA(0, 1, At, B1); PG8_BAR; PG8_SCHED;
	s_waitcnt lgkmcnt(0)
	v_mfma_f32_16x16x32_bf16 v[60:63], v[150:153], v[184:187], v[60:63]
	v_mfma_f32_16x16x32_bf16 v[56:59], v[158:161], v[184:187], v[56:59]
	v_mfma_f32_16x16x32_bf16 v[44:47], v[150:153], v[192:195], v[44:47]
	v_mfma_f32_16x16x32_bf16 v[40:43], v[158:161], v[192:195], v[40:43]
	v_mfma_f32_16x16x32_bf16 v[28:31], v[150:153], v[202:205], v[28:31]
	v_mfma_f32_16x16x32_bf16 v[24:27], v[158:161], v[202:205], v[24:27]
	v_mfma_f32_16x16x32_bf16 v[12:15], v[150:153], v[214:217], v[12:15]
	v_mfma_f32_16x16x32_bf16 v[8:11], v[158:161], v[214:217], v[8:11]
	v_mfma_f32_16x16x32_bf16 v[60:63], v[154:157], v[188:191], v[60:63]
	v_mfma_f32_16x16x32_bf16 v[56:59], v[162:165], v[188:191], v[56:59]
	v_mfma_f32_16x16x32_bf16 v[44:47], v[154:157], v[196:199], v[44:47]
	v_mfma_f32_16x16x32_bf16 v[40:43], v[162:165], v[196:199], v[40:43]
	v_mfma_f32_16x16x32_bf16 v[28:31], v[154:157], v[210:213], v[28:31]
	v_mfma_f32_16x16x32_bf16 v[24:27], v[162:165], v[210:213], v[24:27]
	v_mfma_f32_16x16x32_bf16 v[12:15], v[154:157], v[218:221], v[12:15]
	v_mfma_f32_16x16x32_bf16 v[8:11], v[162:165], v[218:221], v[8:11]
	v_mfma_f32_16x16x32_bf16 v[52:55], v[166:169], v[184:187], v[52:55]
	v_mfma_f32_16x16x32_bf16 v[48:51], v[176:179], v[184:187], v[48:51]
	v_mfma_f32_16x16x32_bf16 v[36:39], v[166:169], v[192:195], v[36:39]
	v_mfma_f32_16x16x32_bf16 v[32:35], v[176:179], v[192:195], v[32:35]
	v_mfma_f32_16x16x32_bf16 v[20:23], v[166:169], v[202:205], v[20:23]
	v_mfma_f32_16x16x32_bf16 v[16:19], v[176:179], v[202:205], v[16:19]
	v_mfma_f32_16x16x32_bf16 v[4:7], v[166:169], v[214:217], v[4:7]
	v_mfma_f32_16x16x32_bf16 v[0:3], v[176:179], v[214:217], v[0:3]
	v_mfma_f32_16x16x32_bf16 v[52:55], v[170:173], v[188:191], v[52:55]
	v_mfma_f32_16x16x32_bf16 v[48:51], v[180:183], v[188:191], v[48:51]
	v_mfma_f32_16x16x32_bf16 v[36:39], v[170:173], v[196:199], v[36:39]
	v_mfma_f32_16x16x32_bf16 v[32:35], v[180:183], v[196:199], v[32:35]
	v_mfma_f32_16x16x32_bf16 v[20:23], v[170:173], v[210:213], v[20:23]
	v_mfma_f32_16x16x32_bf16 v[16:19], v[180:183], v[210:213], v[16:19]
	v_mfma_f32_16x16x32_bf16 v[4:7], v[170:173], v[218:221], v[4:7]
	v_mfma_f32_16x16x32_bf16 v[0:3], v[180:183], v[218:221], v[0:3]
	s_barrier
	s_add_i32 s59, 0, 0x18000
	s_add_i32 s70, 0, 0x1c000
	v_add_u32_e32 v162, s59, v148
	v_add_u32_e32 v174, s70, v148
	ds_read_b128 v[150:153], v162
	ds_read_b128 v[154:157], v162 offset:1024
	ds_read_b128 v[158:161], v162 offset:2048
	ds_read_b128 v[162:165], v162 offset:3072
	ds_read_b128 v[166:169], v174
	ds_read_b128 v[170:173], v174 offset:1024
	ds_read_b128 v[176:179], v174 offset:2048
	ds_read_b128 v[180:183], v174 offset:3072
	s_add_u32 s40, s40, 0x40000
	s_addc_u32 s41, s41, 0
	s_mov_b32 m0, s44
	v_lshl_add_u64 v[228:229], s[40:41], 0, v[134:135]
	ds_read_b128 v[184:187], v149 offset:32768
	ds_read_b128 v[188:191], v149 offset:33792
	ds_read_b128 v[192:195], v149 offset:34816
	ds_read_b128 v[196:199], v149 offset:35840
	ds_read_b128 v[202:205], v149 offset:36864
	ds_read_b128 v[210:213], v149 offset:37888
	ds_read_b128 v[214:217], v149 offset:38912
	ds_read_b128 v[218:221], v149 offset:39936
	global_load_lds_dwordx4 v[228:229], off
	v_lshl_add_u64 v[228:229], s[40:41], 0, v[130:131]
	s_mov_b32 m0, s45
	s_nop 0
	global_load_lds_dwordx4 v[228:229], off
	s_waitcnt vmcnt(8)
	s_waitcnt lgkmcnt(0)
	s_barrier
	s_waitcnt lgkmcnt(0)
	v_mfma_f32_16x16x32_bf16 v[124:127], v[150:153], v[184:187], v[124:127]
	v_mfma_f32_16x16x32_bf16 v[120:123], v[158:161], v[184:187], v[120:123]
	v_mfma_f32_16x16x32_bf16 v[108:111], v[150:153], v[192:195], v[108:111]
	v_mfma_f32_16x16x32_bf16 v[104:107], v[158:161], v[192:195], v[104:107]
	v_mfma_f32_16x16x32_bf16 v[92:95], v[150:153], v[202:205], v[92:95]
	v_mfma_f32_16x16x32_bf16 v[88:91], v[158:161], v[202:205], v[88:91]
	v_mfma_f32_16x16x32_bf16 v[76:79], v[150:153], v[214:217], v[76:79]
	v_mfma_f32_16x16x32_bf16 v[72:75], v[158:161], v[214:217], v[72:75]
	v_mfma_f32_16x16x32_bf16 v[124:127], v[154:157], v[188:191], v[124:127]
	v_mfma_f32_16x16x32_bf16 v[120:123], v[162:165], v[188:191], v[120:123]
	v_mfma_f32_16x16x32_bf16 v[108:111], v[154:157], v[196:199], v[108:111]
	v_mfma_f32_16x16x32_bf16 v[104:107], v[162:165], v[196:199], v[104:107]
	v_mfma_f32_16x16x32_bf16 v[92:95], v[154:157], v[210:213], v[92:95]
	v_mfma_f32_16x16x32_bf16 v[88:91], v[162:165], v[210:213], v[88:91]
	v_mfma_f32_16x16x32_bf16 v[76:79], v[154:157], v[218:221], v[76:79]
	v_mfma_f32_16x16x32_bf16 v[72:75], v[162:165], v[218:221], v[72:75]
	v_mfma_f32_16x16x32_bf16 v[116:119], v[166:169], v[184:187], v[116:119]
	v_mfma_f32_16x16x32_bf16 v[112:115], v[176:179], v[184:187], v[112:115]
	v_mfma_f32_16x16x32_bf16 v[100:103], v[166:169], v[192:195], v[100:103]
	v_mfma_f32_16x16x32_bf16 v[96:99], v[176:179], v[192:195], v[96:99]
	v_mfma_f32_16x16x32_bf16 v[84:87], v[166:169], v[202:205], v[84:87]
	v_mfma_f32_16x16x32_bf16 v[80:83], v[176:179], v[202:205], v[80:83]
	v_mfma_f32_16x16x32_bf16 v[68:71], v[166:169], v[214:217], v[68:71]
	v_mfma_f32_16x16x32_bf16 v[64:67], v[176:179], v[214:217], v[64:67]
	v_mfma_f32_16x16x32_bf16 v[116:119], v[170:173], v[188:191], v[116:119]
	v_mfma_f32_16x16x32_bf16 v[112:115], v[180:183], v[188:191], v[112:115]
	v_mfma_f32_16x16x32_bf16 v[100:103], v[170:173], v[196:199], v[100:103]
	v_mfma_f32_16x16x32_bf16 v[96:99], v[180:183], v[196:199], v[96:99]
	v_mfma_f32_16x16x32_bf16 v[84:87], v[170:173], v[210:213], v[84:87]
	v_mfma_f32_16x16x32_bf16 v[80:83], v[180:183], v[210:213], v[80:83]
	v_mfma_f32_16x16x32_bf16 v[68:71], v[170:173], v[218:221], v[68:71]
	v_mfma_f32_16x16x32_bf16 v[64:67], v[180:183], v[218:221], v[64:67]
	s_barrier
; #define PG8_STAGE(bufoff, gbase, voff) do { _Pragma("unroll") for (int _i = 0; _i < 2; ++_i) \
;         __builtin_amdgcn_global_load_lds((const unsigned*)((const char*)(gbase) + (voff)[_i]), (PG8_LAS unsigned*)(lds + (bufoff) + ldsw + _i * 8192), 16, 0, 0); } while (0)
; #define PG8_STAGEA(bufoff, gbase, voff) do { _Pragma("unroll") for (int _i = 0; _i < 2; ++_i) \
;         __builtin_amdgcn_global_load_lds((const unsigned*)((const char*)(gbase) + (voff)[_i]), (PG8_LAS unsigned*)(lds + (bufoff) + ldsw + _i * 8192), 16, 0, AUXA); } while (0)
; #define PG8_BAR __builtin_amdgcn_s_barrier()
;     ...
;             PG8_LDA(At, 1, 1); PG8_STAGE(PG8_SB(1, 0), b3, voffB); PG8_STAGE(PG8_SB(1, 1), b3 + hstepB, voffB); PG8_STAGEA(PG8_SA(1, 0), a3, voffA);
;             PG8_WAIT_V(8); PG8_WAIT_L(0); PG8_BAR; PG8_MMA(1, 0, At, B0); PG8_MMA(1, 1, At, B1); PG8_BAR; PG8_SCHED;
;             } else {
;             PG8_LDB(B0, 0, 0); PG8_SCHED; PG8_LDA(At, 0, 0); PG8_STAGEA(PG8_SA(1, 1), a1 + hstep, voffA);
;             PG8_WAIT_L(8); PG8_BAR; PG8_WAIT_L(0); PG8_MMA(0, 0, At, B0); PG8_BAR; PG8_SCHED;
;             PG8_LDB(B1, 0, 1); PG8_STAGE(PG8_SB(0, 0), b2, voffB);
;             PG8_BAR; PG8_WAIT_L(0); PG8_MMA(0, 1, At, B1); PG8_BAR;
;             PG8_LDA(At, 0, 1); PG8_STAGEA(PG8_SA(0, 0), a2, voffA);
;             PG8_BAR; PG8_WAIT_L(0); PG8_MMA(1, 0, At, B0); PG8_BAR; PG8_SCHED;
;             PG8_STAGE(PG8_SB(0, 1), b2 + hstepB, voffB);
;             PG8_WAIT_V(6); PG8_BAR; PG8_MMA(1, 1, At, B1); PG8_BAR;
;             PG8_LDB(B0, 1, 0); PG8_SCHED; PG8_LDA(At, 1, 0); PG8_STAGEA(PG8_SA(0, 1), a2 + hstep, voffA);
;             PG8_WAIT_L(8); PG8_BAR; PG8_WAIT_L(0); PG8_MMA(0, 0, At, B0); PG8_BAR; PG8_SCHED;
;             PG8_LDB(B1, 1, 1); PG8_STAGE(PG8_SB(1, 0), b3, voffB);
;             PG8_BAR; PG8_WAIT_L(0); PG8_MMA(0, 1, At, B1); PG8_BAR;
;             PG8_LDA(At, 1, 1); PG8_STAGEA(PG8_SA(1, 0), a3, voffA);
;             PG8_BAR; PG8_WAIT_L(0); PG8_MMA(1, 0, At, B0); PG8_BAR; PG8_SCHED;
;             PG8_STAGE(PG8_SB(1, 1), b3 + hstepB, voffB);
;             PG8_WAIT_V(6); PG8_BAR; PG8_MMA(1, 1, At, B1); PG8_BAR;
;             }
;         }
;         if constexpr (ALIGN_EPI) { if (wr == 0) PG8_BAR; }
;         if constexpr (!Epi::AFTER_DRAIN) { if (!(Epi::LAST_FUSED && !has_next)) { E(acc, cur, wr, wc, fr, fq); S.done(cur); } }
;         if (!has_next) break;
	s_add_i32 s40, s59, s67
	v_lshl_add_u64 v[206:207], v[206:207], 0, s[20:21]
	s_mov_b32 m0, s40
	ds_read_b128 v[184:187], v149 offset:49152
	ds_read_b128 v[188:191], v149 offset:50176
	ds_read_b128 v[192:195], v149 offset:51200
	ds_read_b128 v[196:199], v149 offset:52224
	ds_read_b128 v[202:205], v149 offset:53248
	ds_read_b128 v[210:213], v149 offset:54272
	ds_read_b128 v[214:217], v149 offset:55296
	ds_read_b128 v[218:221], v149 offset:56320
	global_load_lds_dwordx4 v[206:207], off
	s_add_i32 m0, s40, 0x2000
	s_add_u32 s38, s38, 0x10080
	v_lshl_add_u64 v[206:207], v[222:223], 0, s[20:21]
	s_addc_u32 s39, s39, 0
	s_add_i32 s40, s70, s67
	global_load_lds_dwordx4 v[206:207], off
	v_lshl_add_u64 v[206:207], s[38:39], 0, v[132:133]
	s_mov_b32 m0, s40
	s_nop 0
	global_load_lds_dwordx4 v[206:207], off
	v_lshl_add_u64 v[206:207], s[38:39], 0, v[128:129]
	s_add_i32 m0, s40, 0x2000
	s_nop 0
	global_load_lds_dwordx4 v[206:207], off
	v_lshl_add_u64 v[206:207], v[224:225], 0, s[20:21]
	s_mov_b32 m0, s46
	s_nop 0
	global_load_lds_dwordx4 v[206:207], off
	v_lshl_add_u64 v[206:207], v[226:227], 0, s[20:21]
	s_mov_b32 m0, s47
	s_nop 0
	global_load_lds_dwordx4 v[206:207], off
	s_waitcnt vmcnt(8)
	s_waitcnt lgkmcnt(0)
	s_barrier
	s_waitcnt lgkmcnt(0)
	v_mfma_f32_16x16x32_bf16 v[60:63], v[150:153], v[184:187], v[60:63]
	v_mfma_f32_16x16x32_bf16 v[56:59], v[158:161], v[184:187], v[56:59]
	v_mfma_f32_16x16x32_bf16 v[44:47], v[150:153], v[192:195], v[44:47]
	v_mfma_f32_16x16x32_bf16 v[40:43], v[158:161], v[192:195], v[40:43]
	v_mfma_f32_16x16x32_bf16 v[28:31], v[150:153], v[202:205], v[28:31]
	v_mfma_f32_16x16x32_bf16 v[24:27], v[158:161], v[202:205], v[24:27]
	v_mfma_f32_16x16x32_bf16 v[12:15], v[150:153], v[214:217], v[12:15]
	v_mfma_f32_16x16x32_bf16 v[8:11], v[158:161], v[214:217], v[8:11]
	v_mfma_f32_16x16x32_bf16 v[60:63], v[154:157], v[188:191], v[60:63]
	v_mfma_f32_16x16x32_bf16 v[56:59], v[162:165], v[188:191], v[56:59]
	v_mfma_f32_16x16x32_bf16 v[44:47], v[154:157], v[196:199], v[44:47]
	v_mfma_f32_16x16x32_bf16 v[40:43], v[162:165], v[196:199], v[40:43]
	v_mfma_f32_16x16x32_bf16 v[28:31], v[154:157], v[210:213], v[28:31]
	v_mfma_f32_16x16x32_bf16 v[24:27], v[162:165], v[210:213], v[24:27]
	v_mfma_f32_16x16x32_bf16 v[12:15], v[154:157], v[218:221], v[12:15]
	v_mfma_f32_16x16x32_bf16 v[8:11], v[162:165], v[218:221], v[8:11]
	v_mfma_f32_16x16x32_bf16 v[52:55], v[166:169], v[184:187], v[52:55]
	v_mfma_f32_16x16x32_bf16 v[48:51], v[176:179], v[184:187], v[48:51]
	v_mfma_f32_16x16x32_bf16 v[36:39], v[166:169], v[192:195], v[36:39]
	v_mfma_f32_16x16x32_bf16 v[32:35], v[176:179], v[192:195], v[32:35]
	v_mfma_f32_16x16x32_bf16 v[20:23], v[166:169], v[202:205], v[20:23]
	v_mfma_f32_16x16x32_bf16 v[16:19], v[176:179], v[202:205], v[16:19]
	v_mfma_f32_16x16x32_bf16 v[4:7], v[166:169], v[214:217], v[4:7]
	v_mfma_f32_16x16x32_bf16 v[0:3], v[176:179], v[214:217], v[0:3]
	v_mfma_f32_16x16x32_bf16 v[52:55], v[170:173], v[188:191], v[52:55]
	v_mfma_f32_16x16x32_bf16 v[48:51], v[180:183], v[188:191], v[48:51]
	v_mfma_f32_16x16x32_bf16 v[36:39], v[170:173], v[196:199], v[36:39]
	v_mfma_f32_16x16x32_bf16 v[32:35], v[180:183], v[196:199], v[32:35]
	v_mfma_f32_16x16x32_bf16 v[20:23], v[170:173], v[210:213], v[20:23]
	v_mfma_f32_16x16x32_bf16 v[16:19], v[180:183], v[210:213], v[16:19]
	v_mfma_f32_16x16x32_bf16 v[4:7], v[170:173], v[218:221], v[4:7]
	v_mfma_f32_16x16x32_bf16 v[0:3], v[180:183], v[218:221], v[0:3]
	s_barrier
	s_add_i32 s58, s58, 2
	s_add_u32 s36, s36, 0x100
	s_addc_u32 s37, s37, 0
	s_cmp_gt_u32 s58, 13
	s_cbranch_scc0 .LBB0_888
	s_setprio 0
	s_and_b64 vcc, exec, s[22:23]
	s_cbranch_vccz .LBB0_891
	s_barrier

;     __host__ __device__ bool next(int i, Unit& u) const { return at((long)i * G + c, u); }
;     __host__ __device__ bool next(int i, Unit& u) const { if (i != 0 || c >= cnt) return false; u.pm = pm0 + c / nN; u.pn = c % nN; u.k0 = 0; u.nt = ntk; return true; }
; #define PG8_STAGEA(bufoff, gbase, voff) do { _Pragma("unroll") for (int _i = 0; _i < 2; ++_i) \
;         __builtin_amdgcn_global_load_lds((const unsigned*)((const char*)(gbase) + (voff)[_i]), (PG8_LAS unsigned*)(lds + (bufoff) + ldsw + _i * 8192), 16, 0, AUXA); } while (0)
; #define PG8_LDA(dst, b, h) do { _Pragma("unroll") for (int m = 0; m < 4; ++m) _Pragma("unroll") for (int k = 0; k < 2; ++k) dst[m][k] = *(const PG8_LAS bf16x8*)(lds + PG8_SA(b, h) + aoff + m * 2048 + k * 1024); } while (0)
; #define PG8_LDB(dst, b, h) do { _Pragma("unroll") for (int n = 0; n < 2; ++n) _Pragma("unroll") for (int k = 0; k < 2; ++k) dst[n][k] = *(const PG8_LAS bf16x8*)(lds + PG8_SB(b, h) + boff + n * 2048 + k * 1024); } while (0)
; #define PG8_WAIT_V(n) asm volatile("s_waitcnt vmcnt(" #n ")" ::: "memory")
; #define PG8_BAR __builtin_amdgcn_s_barrier()
;     ...
;         const bool has_next = S.next(ui + 1, nxt);
;         const char* nA = has_next ? (const char*)g.A + (size_t)nxt.pm * tstep + (size_t)nxt.k0 * (BK * 2) : cA; const char* nB = has_next ? (const char*)g.Bt + (size_t)nxt.pn * tstep + (size_t)nxt.k0 * (BK * 2) : cB;
;         const int nt = cur.nt;
;         for (int t = 0; t < nt; t += 2) {
;             const bool last = (t == nt - 2);
;             const char* a1 = cA + (size_t)(t + 1) * kstep;
;             const char* a2 = last ? nA : cA + (size_t)(t + 2) * kstep; const char* b2 = last ? nB : cB + (size_t)(t + 2) * kstep;
;             const char* a3 = a2 + kstep; const char* b3 = b2 + kstep;
;             if (last && has_next) S.a_ready(nxt);
;             if constexpr (SP2) {
;             PG8_LDB(B0, 0, 0); PG8_LDB(B1, 0, 1); PG8_SCHED; PG8_LDA(At, 0, 0); PG8_STAGEA(PG8_SA(1, 1), a1 + hstep, voffA);
;             PG8_WAIT_V(8); PG8_WAIT_L(0); PG8_BAR; PG8_MMA(0, 0, At, B0); PG8_MMA(0, 1, At, B1); PG8_BAR; PG8_SCHED;
;     ...
; #pragma unroll
;         for (int a = 0; a < 2; ++a)
; #pragma unroll
;             for (int b = 0; b < 2; ++b)
; #pragma unroll
;                 for (int m = 0; m < 4; ++m)
; #pragma unroll
;                     for (int n = 0; n < 2; ++n) acc[a][b][m][n] = (f32x4){0.f, 0.f, 0.f, 0.f};
.LBB0_976:
	s_ashr_i32 s27, s26, 31
	s_lshl_b64 s[28:29], s[26:27], 19
	s_add_u32 s28, s8, s28
	s_addc_u32 s29, s9, s29
	s_and_b64 s[30:31], s[0:1], exec
	s_cselect_b32 s27, s29, s39
	s_cselect_b32 s35, s28, s38
	s_ashr_i32 s25, s24, 31
	s_lshl_b64 s[30:31], s[24:25], 19
	s_add_u32 s30, s3, s30
	s_addc_u32 s31, s21, s31
	s_and_b64 s[42:43], s[0:1], exec
	s_cselect_b32 s25, s31, s41
	s_cselect_b32 s58, s30, s40
	s_add_u32 s38, s38, 0x40080
	s_addc_u32 s39, s39, 0
	s_add_u32 s59, s40, 0x100
	v_mov_b32_e32 v0, 0
	s_addc_u32 s70, s41, 0
	s_mov_b32 s71, -2
	v_mov_b32_e32 v1, v0
	v_mov_b32_e32 v2, v0
	v_mov_b32_e32 v3, v0
	v_mov_b32_e32 v4, v0
	v_mov_b32_e32 v5, v0
	v_mov_b32_e32 v6, v0
	v_mov_b32_e32 v7, v0
	v_mov_b32_e32 v16, v0
	v_mov_b32_e32 v17, v0
	v_mov_b32_e32 v18, v0
	v_mov_b32_e32 v19, v0
	v_mov_b32_e32 v20, v0
	v_mov_b32_e32 v21, v0
	v_mov_b32_e32 v22, v0
	v_mov_b32_e32 v23, v0
	v_mov_b32_e32 v32, v0
	v_mov_b32_e32 v33, v0
	v_mov_b32_e32 v34, v0
	v_mov_b32_e32 v35, v0
	v_mov_b32_e32 v36, v0
	v_mov_b32_e32 v37, v0
	v_mov_b32_e32 v38, v0
	v_mov_b32_e32 v39, v0
	v_mov_b32_e32 v48, v0
	v_mov_b32_e32 v49, v0
	v_mov_b32_e32 v50, v0
	v_mov_b32_e32 v51, v0
	v_mov_b32_e32 v52, v0
	v_mov_b32_e32 v53, v0
	v_mov_b32_e32 v54, v0
	v_mov_b32_e32 v55, v0
	v_mov_b32_e32 v8, v0
	v_mov_b32_e32 v9, v0
	v_mov_b32_e32 v10, v0
	v_mov_b32_e32 v11, v0
	v_mov_b32_e32 v12, v0
	v_mov_b32_e32 v13, v0
	v_mov_b32_e32 v14, v0
	v_mov_b32_e32 v15, v0
	v_mov_b32_e32 v24, v0
	v_mov_b32_e32 v25, v0
	v_mov_b32_e32 v26, v0
	v_mov_b32_e32 v27, v0
	v_mov_b32_e32 v28, v0
	v_mov_b32_e32 v29, v0
	v_mov_b32_e32 v30, v0
	v_mov_b32_e32 v31, v0
	v_mov_b32_e32 v40, v0
	v_mov_b32_e32 v41, v0
	v_mov_b32_e32 v42, v0
	v_mov_b32_e32 v43, v0
	v_mov_b32_e32 v44, v0
	v_mov_b32_e32 v45, v0
	v_mov_b32_e32 v46, v0
	v_mov_b32_e32 v47, v0
	v_mov_b32_e32 v56, v0
	v_mov_b32_e32 v57, v0
	v_mov_b32_e32 v58, v0
	v_mov_b32_e32 v59, v0
	v_mov_b32_e32 v60, v0
	v_mov_b32_e32 v61, v0
	v_mov_b32_e32 v62, v0
	v_mov_b32_e32 v63, v0
	v_mov_b32_e32 v64, v0
	v_mov_b32_e32 v65, v0
	v_mov_b32_e32 v66, v0
	v_mov_b32_e32 v67, v0
	v_mov_b32_e32 v68, v0
	v_mov_b32_e32 v69, v0
	v_mov_b32_e32 v70, v0
	v_mov_b32_e32 v71, v0
	v_mov_b32_e32 v80, v0
	v_mov_b32_e32 v81, v0
	v_mov_b32_e32 v82, v0
	v_mov_b32_e32 v83, v0
	v_mov_b32_e32 v84, v0
	v_mov_b32_e32 v85, v0
	v_mov_b32_e32 v86, v0
	v_mov_b32_e32 v87, v0
	v_mov_b32_e32 v96, v0
	v_mov_b32_e32 v97, v0
	v_mov_b32_e32 v98, v0
	v_mov_b32_e32 v99, v0
	v_mov_b32_e32 v100, v0
	v_mov_b32_e32 v101, v0
	v_mov_b32_e32 v102, v0
	v_mov_b32_e32 v103, v0
	v_mov_b32_e32 v112, v0
	v_mov_b32_e32 v113, v0
	v_mov_b32_e32 v114, v0
	v_mov_b32_e32 v115, v0
	v_mov_b32_e32 v116, v0
	v_mov_b32_e32 v117, v0
	v_mov_b32_e32 v118, v0
	v_mov_b32_e32 v119, v0
	v_mov_b32_e32 v72, v0
	v_mov_b32_e32 v73, v0
	v_mov_b32_e32 v74, v0
	v_mov_b32_e32 v75, v0
	v_mov_b32_e32 v76, v0
	v_mov_b32_e32 v77, v0
	v_mov_b32_e32 v78, v0
	v_mov_b32_e32 v79, v0
	v_mov_b32_e32 v88, v0
	v_mov_b32_e32 v89, v0
	v_mov_b32_e32 v90, v0
	v_mov_b32_e32 v91, v0
	v_mov_b32_e32 v92, v0
	v_mov_b32_e32 v93, v0
	v_mov_b32_e32 v94, v0
	v_mov_b32_e32 v95, v0
	v_mov_b32_e32 v104, v0
	v_mov_b32_e32 v105, v0
	v_mov_b32_e32 v106, v0
	v_mov_b32_e32 v107, v0
	v_mov_b32_e32 v108, v0
	v_mov_b32_e32 v109, v0
	v_mov_b32_e32 v110, v0
	v_mov_b32_e32 v111, v0
	v_mov_b32_e32 v120, v0
	v_mov_b32_e32 v121, v0
	v_mov_b32_e32 v122, v0
	v_mov_b32_e32 v123, v0
	v_mov_b32_e32 v124, v0
	v_mov_b32_e32 v125, v0
	v_mov_b32_e32 v126, v0
	v_mov_b32_e32 v127, v0
	v_readlane_b32 s98, v255, 17
	s_cmp_lg_u32 s98, 1
	s_cbranch_scc1 .Lsprio_5
	s_setprio 1
.Lsprio_5:
.LBB0_977:
	ds_read_b128 v[144:147], v170
	ds_read_b128 v[148:151], v170 offset:1024
	ds_read_b128 v[152:155], v170 offset:2048
	ds_read_b128 v[156:159], v170 offset:3072
	ds_read_b128 v[160:163], v171
	ds_read_b128 v[164:167], v171 offset:1024
	ds_read_b128 v[176:179], v171 offset:2048
	ds_read_b128 v[180:183], v171 offset:3072
	s_add_u32 s40, s38, 0xfffc0080
	s_addc_u32 s41, s39, -1
	s_cmp_eq_u32 s71, 12
	s_cselect_b32 s43, s27, s41
	s_cselect_b32 s42, s35, s40
	s_cselect_b32 s41, s25, s70
	s_cselect_b32 s40, s58, s59
	v_lshl_add_u64 v[206:207], s[38:39], 0, v[138:139]
	s_add_i32 m0, s37, 0xc000
	ds_read_b128 v[184:187], v172
	ds_read_b128 v[188:191], v172 offset:1024
	ds_read_b128 v[192:195], v172 offset:2048
	ds_read_b128 v[196:199], v172 offset:3072
	ds_read_b128 v[202:205], v172 offset:4096
	ds_read_b128 v[210:213], v172 offset:5120
	ds_read_b128 v[214:217], v172 offset:6144
	ds_read_b128 v[218:221], v172 offset:7168
	global_load_lds_dwordx4 v[206:207], off
	v_lshl_add_u64 v[206:207], s[38:39], 0, v[140:141]
	s_add_i32 m0, s37, 0xe000
	s_nop 0
	global_load_lds_dwordx4 v[206:207], off
	s_waitcnt vmcnt(8)
	s_waitcnt lgkmcnt(0)
	s_barrier
; #define PG8_STAGE(bufoff, gbase, voff) do { _Pragma("unroll") for (int _i = 0; _i < 2; ++_i) \
;         __builtin_amdgcn_global_load_lds((const unsigned*)((const char*)(gbase) + (voff)[_i]), (PG8_LAS unsigned*)(lds + (bufoff) + ldsw + _i * 8192), 16, 0, 0); } while (0)
; #define PG8_STAGEA(bufoff, gbase, voff) do { _Pragma("unroll") for (int _i = 0; _i < 2; ++_i) \
;         __builtin_amdgcn_global_load_lds((const unsigned*)((const char*)(gbase) + (voff)[_i]), (PG8_LAS unsigned*)(lds + (bufoff) + ldsw + _i * 8192), 16, 0, AUXA); } while (0)
; #define PG8_LDA(dst, b, h) do { _Pragma("unroll") for (int m = 0; m < 4; ++m) _Pragma("unroll") for (int k = 0; k < 2; ++k) dst[m][k] = *(const PG8_LAS bf16x8*)(lds + PG8_SA(b, h) + aoff + m * 2048 + k * 1024); } while (0)
; #define PG8_LDB(dst, b, h) do { _Pragma("unroll") for (int n = 0; n < 2; ++n) _Pragma("unroll") for (int k = 0; k < 2; ++k) dst[n][k] = *(const PG8_LAS bf16x8*)(lds + PG8_SB(b, h) + boff + n * 2048 + k * 1024); } while (0)
; #define PG8_MMA(ai, bj, At, Bt) do { __builtin_amdgcn_s_setprio(1); _Pragma("unroll") for (int m = 0; m < 4; ++m) _Pragma("unroll") for (int n = 0; n < 2; ++n) _Pragma("unroll") for (int k = 0; k < 2; ++k) \
;         acc[ai][bj][m][n] = __builtin_amdgcn_mfma_f32_16x16x32_bf16(Bt[n][k], At[m][k], acc[ai][bj][m][n], 0, 0, 0); __builtin_amdgcn_s_setprio(0); } while (0)
; #define PG8_WAIT_V(n) asm volatile("s_waitcnt vmcnt(" #n ")" ::: "memory")
; #define PG8_WAIT_L(n) asm volatile("s_waitcnt lgkmcnt(" #n ")" ::: "memory")
; #define PG8_BAR __builtin_amdgcn_s_barrier()
; #define PG8_SCHED __builtin_amdgcn_sched_barrier(0)
;     ...
;             PG8_WAIT_V(8); PG8_WAIT_L(0); PG8_BAR; PG8_MMA(0, 0, At, B0); PG8_MMA(0, 1, At, B1); PG8_BAR; PG8_SCHED;
;             PG8_LDA(At, 0, 1); PG8_STAGE(PG8_SB(0, 0), b2, voffB); PG8_STAGE(PG8_SB(0, 1), b2 + hstepB, voffB); PG8_STAGEA(PG8_SA(0, 0), a2, voffA);
;             PG8_WAIT_V(8); PG8_WAIT_L(0); PG8_BAR; PG8_MMA(1, 0, At, B0); PG8_MMA(1, 1, At, B1); PG8_BAR; PG8_SCHED;
;             PG8_LDB(B0, 1, 0); PG8_LDB(B1, 1, 1); PG8_SCHED; PG8_LDA(At, 1, 0); PG8_STAGEA(PG8_SA(0, 1), a2 + hstep, voffA);
;             PG8_WAIT_V(8); PG8_WAIT_L(0); PG8_BAR; PG8_MMA(0, 0, At, B0); PG8_MMA(0, 1, At, B1); PG8_BAR; PG8_SCHED;
	s_waitcnt lgkmcnt(0)
	v_mfma_f32_16x16x32_bf16 v[124:127], v[144:147], v[184:187], v[124:127]
	v_mfma_f32_16x16x32_bf16 v[120:123], v[152:155], v[184:187], v[120:123]
	v_mfma_f32_16x16x32_bf16 v[108:111], v[144:147], v[192:195], v[108:111]
	v_mfma_f32_16x16x32_bf16 v[104:107], v[152:155], v[192:195], v[104:107]
	v_mfma_f32_16x16x32_bf16 v[92:95], v[144:147], v[202:205], v[92:95]
	v_mfma_f32_16x16x32_bf16 v[88:91], v[152:155], v[202:205], v[88:91]
	v_mfma_f32_16x16x32_bf16 v[76:79], v[144:147], v[214:217], v[76:79]
	v_mfma_f32_16x16x32_bf16 v[72:75], v[152:155], v[214:217], v[72:75]
	v_mfma_f32_16x16x32_bf16 v[124:127], v[148:151], v[188:191], v[124:127]
	v_mfma_f32_16x16x32_bf16 v[120:123], v[156:159], v[188:191], v[120:123]
	v_mfma_f32_16x16x32_bf16 v[108:111], v[148:151], v[196:199], v[108:111]
	v_mfma_f32_16x16x32_bf16 v[104:107], v[156:159], v[196:199], v[104:107]
	v_mfma_f32_16x16x32_bf16 v[92:95], v[148:151], v[210:213], v[92:95]
	v_mfma_f32_16x16x32_bf16 v[88:91], v[156:159], v[210:213], v[88:91]
	v_mfma_f32_16x16x32_bf16 v[76:79], v[148:151], v[218:221], v[76:79]
	v_mfma_f32_16x16x32_bf16 v[72:75], v[156:159], v[218:221], v[72:75]
	v_mfma_f32_16x16x32_bf16 v[116:119], v[160:163], v[184:187], v[116:119]
	v_mfma_f32_16x16x32_bf16 v[112:115], v[176:179], v[184:187], v[112:115]
	v_mfma_f32_16x16x32_bf16 v[100:103], v[160:163], v[192:195], v[100:103]
	v_mfma_f32_16x16x32_bf16 v[96:99], v[176:179], v[192:195], v[96:99]
	v_mfma_f32_16x16x32_bf16 v[84:87], v[160:163], v[202:205], v[84:87]
	v_mfma_f32_16x16x32_bf16 v[80:83], v[176:179], v[202:205], v[80:83]
	v_mfma_f32_16x16x32_bf16 v[68:71], v[160:163], v[214:217], v[68:71]
	v_mfma_f32_16x16x32_bf16 v[64:67], v[176:179], v[214:217], v[64:67]
	v_mfma_f32_16x16x32_bf16 v[116:119], v[164:167], v[188:191], v[116:119]
	v_mfma_f32_16x16x32_bf16 v[112:115], v[180:183], v[188:191], v[112:115]
	v_mfma_f32_16x16x32_bf16 v[100:103], v[164:167], v[196:199], v[100:103]
	v_mfma_f32_16x16x32_bf16 v[96:99], v[180:183], v[196:199], v[96:99]
	v_mfma_f32_16x16x32_bf16 v[84:87], v[164:167], v[210:213], v[84:87]
	v_mfma_f32_16x16x32_bf16 v[80:83], v[180:183], v[210:213], v[80:83]
	v_mfma_f32_16x16x32_bf16 v[68:71], v[164:167], v[218:221], v[68:71]
	v_mfma_f32_16x16x32_bf16 v[64:67], v[180:183], v[218:221], v[64:67]
	s_barrier
	s_add_i32 s73, s54, s67
	v_lshl_add_u64 v[206:207], s[40:41], 0, v[132:133]
	s_mov_b32 m0, s73
	ds_read_b128 v[184:187], v172 offset:16384
	ds_read_b128 v[188:191], v172 offset:17408
	ds_read_b128 v[192:195], v172 offset:18432
	ds_read_b128 v[196:199], v172 offset:19456
	ds_read_b128 v[202:205], v172 offset:20480
	ds_read_b128 v[210:213], v172 offset:21504
	ds_read_b128 v[214:217], v172 offset:22528
	ds_read_b128 v[218:221], v172 offset:23552
	global_load_lds_dwordx4 v[206:207], off
	s_add_i32 m0, s73, 0x2000
	s_add_u32 s74, s40, 0x10000
	v_lshl_add_u64 v[222:223], s[40:41], 0, v[128:129]
	s_addc_u32 s75, s41, 0
	s_add_i32 s73, s55, s67
	global_load_lds_dwordx4 v[222:223], off
	v_lshl_add_u64 v[224:225], s[74:75], 0, v[132:133]
	s_mov_b32 m0, s73
	v_lshl_add_u64 v[226:227], s[42:43], 0, v[130:131]
	global_load_lds_dwordx4 v[224:225], off
	v_lshl_add_u64 v[224:225], s[74:75], 0, v[128:129]
	s_add_i32 m0, s73, 0x2000
	s_nop 0
	global_load_lds_dwordx4 v[224:225], off
	v_lshl_add_u64 v[224:225], s[42:43], 0, v[134:135]
	s_mov_b32 m0, s37
	s_nop 0
	global_load_lds_dwordx4 v[224:225], off
	s_mov_b32 m0, s46
	s_nop 0
	global_load_lds_dwordx4 v[226:227], off
	s_waitcnt vmcnt(8)
	s_waitcnt lgkmcnt(0)
	s_barrier
	s_waitcnt lgkmcnt(0)
	v_mfma_f32_16x16x32_bf16 v[60:63], v[144:147], v[184:187], v[60:63]
	v_mfma_f32_16x16x32_bf16 v[56:59], v[152:155], v[184:187], v[56:59]
	v_mfma_f32_16x16x32_bf16 v[44:47], v[144:147], v[192:195], v[44:47]
	v_mfma_f32_16x16x32_bf16 v[40:43], v[152:155], v[192:195], v[40:43]
	v_mfma_f32_16x16x32_bf16 v[28:31], v[144:147], v[202:205], v[28:31]
	v_mfma_f32_16x16x32_bf16 v[24:27], v[152:155], v[202:205], v[24:27]
	v_mfma_f32_16x16x32_bf16 v[12:15], v[144:147], v[214:217], v[12:15]
	v_mfma_f32_16x16x32_bf16 v[8:11], v[152:155], v[214:217], v[8:11]
	v_mfma_f32_16x16x32_bf16 v[60:63], v[148:151], v[188:191], v[60:63]
	v_mfma_f32_16x16x32_bf16 v[56:59], v[156:159], v[188:191], v[56:59]
	v_mfma_f32_16x16x32_bf16 v[44:47], v[148:151], v[196:199], v[44:47]
	v_mfma_f32_16x16x32_bf16 v[40:43], v[156:159], v[196:199], v[40:43]
	v_mfma_f32_16x16x32_bf16 v[28:31], v[148:151], v[210:213], v[28:31]
	v_mfma_f32_16x16x32_bf16 v[24:27], v[156:159], v[210:213], v[24:27]
	v_mfma_f32_16x16x32_bf16 v[12:15], v[148:151], v[218:221], v[12:15]
	v_mfma_f32_16x16x32_bf16 v[8:11], v[156:159], v[218:221], v[8:11]
	v_mfma_f32_16x16x32_bf16 v[52:55], v[160:163], v[184:187], v[52:55]
	v_mfma_f32_16x16x32_bf16 v[48:51], v[176:179], v[184:187], v[48:51]
	v_mfma_f32_16x16x32_bf16 v[36:39], v[160:163], v[192:195], v[36:39]
	v_mfma_f32_16x16x32_bf16 v[32:35], v[176:179], v[192:195], v[32:35]
	v_mfma_f32_16x16x32_bf16 v[20:23], v[160:163], v[202:205], v[20:23]
	v_mfma_f32_16x16x32_bf16 v[16:19], v[176:179], v[202:205], v[16:19]
	v_mfma_f32_16x16x32_bf16 v[4:7], v[160:163], v[214:217], v[4:7]
	v_mfma_f32_16x16x32_bf16 v[0:3], v[176:179], v[214:217], v[0:3]
	v_mfma_f32_16x16x32_bf16 v[52:55], v[164:167], v[188:191], v[52:55]
	v_mfma_f32_16x16x32_bf16 v[48:51], v[180:183], v[188:191], v[48:51]
	v_mfma_f32_16x16x32_bf16 v[36:39], v[164:167], v[196:199], v[36:39]
	v_mfma_f32_16x16x32_bf16 v[32:35], v[180:183], v[196:199], v[32:35]
	v_mfma_f32_16x16x32_bf16 v[20:23], v[164:167], v[210:213], v[20:23]
	v_mfma_f32_16x16x32_bf16 v[16:19], v[180:183], v[210:213], v[16:19]
	v_mfma_f32_16x16x32_bf16 v[4:7], v[164:167], v[218:221], v[4:7]
	v_mfma_f32_16x16x32_bf16 v[0:3], v[180:183], v[218:221], v[0:3]
	s_barrier
; #define PG8_STAGEA(bufoff, gbase, voff) do { _Pragma("unroll") for (int _i = 0; _i < 2; ++_i) \
;         __builtin_amdgcn_global_load_lds((const unsigned*)((const char*)(gbase) + (voff)[_i]), (PG8_LAS unsigned*)(lds + (bufoff) + ldsw + _i * 8192), 16, 0, AUXA); } while (0)
; #define PG8_LDA(dst, b, h) do { _Pragma("unroll") for (int m = 0; m < 4; ++m) _Pragma("unroll") for (int k = 0; k < 2; ++k) dst[m][k] = *(const PG8_LAS bf16x8*)(lds + PG8_SA(b, h) + aoff + m * 2048 + k * 1024); } while (0)
; #define PG8_LDB(dst, b, h) do { _Pragma("unroll") for (int n = 0; n < 2; ++n) _Pragma("unroll") for (int k = 0; k < 2; ++k) dst[n][k] = *(const PG8_LAS bf16x8*)(lds + PG8_SB(b, h) + boff + n * 2048 + k * 1024); } while (0)
; #define PG8_MMA(ai, bj, At, Bt) do { __builtin_amdgcn_s_setprio(1); _Pragma("unroll") for (int m = 0; m < 4; ++m) _Pragma("unroll") for (int n = 0; n < 2; ++n) _Pragma("unroll") for (int k = 0; k < 2; ++k) \
;         acc[ai][bj][m][n] = __builtin_amdgcn_mfma_f32_16x16x32_bf16(Bt[n][k], At[m][k], acc[ai][bj][m][n], 0, 0, 0); __builtin_amdgcn_s_setprio(0); } while (0)
; #define PG8_WAIT_V(n) asm volatile("s_waitcnt vmcnt(" #n ")" ::: "memory")
; #define PG8_WAIT_L(n) asm volatile("s_waitcnt lgkmcnt(" #n ")" ::: "memory")
; #define PG8_BAR __builtin_amdgcn_s_barrier()
; #define PG8_SCHED __builtin_amdgcn_sched_barrier(0)
;     ...
;             PG8_LDB(B0, 1, 0); PG8_LDB(B1, 1, 1); PG8_SCHED; PG8_LDA(At, 1, 0); PG8_STAGEA(PG8_SA(0, 1), a2 + hstep, voffA);
;             PG8_WAIT_V(8); PG8_WAIT_L(0); PG8_BAR; PG8_MMA(0, 0, At, B0); PG8_MMA(0, 1, At, B1); PG8_BAR; PG8_SCHED;
	s_add_i32 s73, 0, 0x18000
	s_add_i32 s74, 0, 0x1c000
	v_add_u32_e32 v156, s73, v169
	v_add_u32_e32 v173, s74, v169
	ds_read_b128 v[144:147], v156
	ds_read_b128 v[148:151], v156 offset:1024
	ds_read_b128 v[152:155], v156 offset:2048
	ds_read_b128 v[156:159], v156 offset:3072
	ds_read_b128 v[160:163], v173
	ds_read_b128 v[164:167], v173 offset:1024
	ds_read_b128 v[176:179], v173 offset:2048
	ds_read_b128 v[180:183], v173 offset:3072
	s_add_u32 s42, s42, 0x40000
	s_addc_u32 s43, s43, 0
	s_mov_b32 m0, s47
	v_lshl_add_u64 v[228:229], s[42:43], 0, v[134:135]
	ds_read_b128 v[184:187], v172 offset:32768
	ds_read_b128 v[188:191], v172 offset:33792
	ds_read_b128 v[192:195], v172 offset:34816
	ds_read_b128 v[196:199], v172 offset:35840
	ds_read_b128 v[202:205], v172 offset:36864
	ds_read_b128 v[210:213], v172 offset:37888
	ds_read_b128 v[214:217], v172 offset:38912
	ds_read_b128 v[218:221], v172 offset:39936
	global_load_lds_dwordx4 v[228:229], off
	v_lshl_add_u64 v[228:229], s[42:43], 0, v[130:131]
	s_mov_b32 m0, s50
	s_nop 0
	global_load_lds_dwordx4 v[228:229], off
	s_waitcnt vmcnt(8)
	s_waitcnt lgkmcnt(0)
	s_barrier
	s_waitcnt lgkmcnt(0)
	v_mfma_f32_16x16x32_bf16 v[124:127], v[144:147], v[184:187], v[124:127]
	v_mfma_f32_16x16x32_bf16 v[120:123], v[152:155], v[184:187], v[120:123]
	v_mfma_f32_16x16x32_bf16 v[108:111], v[144:147], v[192:195], v[108:111]
	v_mfma_f32_16x16x32_bf16 v[104:107], v[152:155], v[192:195], v[104:107]
	v_mfma_f32_16x16x32_bf16 v[92:95], v[144:147], v[202:205], v[92:95]
	v_mfma_f32_16x16x32_bf16 v[88:91], v[152:155], v[202:205], v[88:91]
	v_mfma_f32_16x16x32_bf16 v[76:79], v[144:147], v[214:217], v[76:79]
	v_mfma_f32_16x16x32_bf16 v[72:75], v[152:155], v[214:217], v[72:75]
	v_mfma_f32_16x16x32_bf16 v[124:127], v[148:151], v[188:191], v[124:127]
	v_mfma_f32_16x16x32_bf16 v[120:123], v[156:159], v[188:191], v[120:123]
	v_mfma_f32_16x16x32_bf16 v[108:111], v[148:151], v[196:199], v[108:111]
	v_mfma_f32_16x16x32_bf16 v[104:107], v[156:159], v[196:199], v[104:107]
	v_mfma_f32_16x16x32_bf16 v[92:95], v[148:151], v[210:213], v[92:95]
	v_mfma_f32_16x16x32_bf16 v[88:91], v[156:159], v[210:213], v[88:91]
	v_mfma_f32_16x16x32_bf16 v[76:79], v[148:151], v[218:221], v[76:79]
	v_mfma_f32_16x16x32_bf16 v[72:75], v[156:159], v[218:221], v[72:75]
	v_mfma_f32_16x16x32_bf16 v[116:119], v[160:163], v[184:187], v[116:119]
	v_mfma_f32_16x16x32_bf16 v[112:115], v[176:179], v[184:187], v[112:115]
	v_mfma_f32_16x16x32_bf16 v[100:103], v[160:163], v[192:195], v[100:103]
	v_mfma_f32_16x16x32_bf16 v[96:99], v[176:179], v[192:195], v[96:99]
	v_mfma_f32_16x16x32_bf16 v[84:87], v[160:163], v[202:205], v[84:87]
	v_mfma_f32_16x16x32_bf16 v[80:83], v[176:179], v[202:205], v[80:83]
	v_mfma_f32_16x16x32_bf16 v[68:71], v[160:163], v[214:217], v[68:71]
	v_mfma_f32_16x16x32_bf16 v[64:67], v[176:179], v[214:217], v[64:67]
	v_mfma_f32_16x16x32_bf16 v[116:119], v[164:167], v[188:191], v[116:119]
	v_mfma_f32_16x16x32_bf16 v[112:115], v[180:183], v[188:191], v[112:115]
	v_mfma_f32_16x16x32_bf16 v[100:103], v[164:167], v[196:199], v[100:103]
	v_mfma_f32_16x16x32_bf16 v[96:99], v[180:183], v[196:199], v[96:99]
	v_mfma_f32_16x16x32_bf16 v[84:87], v[164:167], v[210:213], v[84:87]
	v_mfma_f32_16x16x32_bf16 v[80:83], v[180:183], v[210:213], v[80:83]
	v_mfma_f32_16x16x32_bf16 v[68:71], v[164:167], v[218:221], v[68:71]
	v_mfma_f32_16x16x32_bf16 v[64:67], v[180:183], v[218:221], v[64:67]
	s_barrier
; #define PG8_STAGE(bufoff, gbase, voff) do { _Pragma("unroll") for (int _i = 0; _i < 2; ++_i) \
;         __builtin_amdgcn_global_load_lds((const unsigned*)((const char*)(gbase) + (voff)[_i]), (PG8_LAS unsigned*)(lds + (bufoff) + ldsw + _i * 8192), 16, 0, 0); } while (0)
; #define PG8_STAGEA(bufoff, gbase, voff) do { _Pragma("unroll") for (int _i = 0; _i < 2; ++_i) \
;         __builtin_amdgcn_global_load_lds((const unsigned*)((const char*)(gbase) + (voff)[_i]), (PG8_LAS unsigned*)(lds + (bufoff) + ldsw + _i * 8192), 16, 0, AUXA); } while (0)
; #define PG8_BAR __builtin_amdgcn_s_barrier()
;     ...
;             PG8_LDA(At, 1, 1); PG8_STAGE(PG8_SB(1, 0), b3, voffB); PG8_STAGE(PG8_SB(1, 1), b3 + hstepB, voffB); PG8_STAGEA(PG8_SA(1, 0), a3, voffA);
;             PG8_WAIT_V(8); PG8_WAIT_L(0); PG8_BAR; PG8_MMA(1, 0, At, B0); PG8_MMA(1, 1, At, B1); PG8_BAR; PG8_SCHED;
;             } else {
;             PG8_LDB(B0, 0, 0); PG8_SCHED; PG8_LDA(At, 0, 0); PG8_STAGEA(PG8_SA(1, 1), a1 + hstep, voffA);
;             PG8_WAIT_L(8); PG8_BAR; PG8_WAIT_L(0); PG8_MMA(0, 0, At, B0); PG8_BAR; PG8_SCHED;
;             PG8_LDB(B1, 0, 1); PG8_STAGE(PG8_SB(0, 0), b2, voffB);
;             PG8_BAR; PG8_WAIT_L(0); PG8_MMA(0, 1, At, B1); PG8_BAR;
;             PG8_LDA(At, 0, 1); PG8_STAGEA(PG8_SA(0, 0), a2, voffA);
;             PG8_BAR; PG8_WAIT_L(0); PG8_MMA(1, 0, At, B0); PG8_BAR; PG8_SCHED;
;             PG8_STAGE(PG8_SB(0, 1), b2 + hstepB, voffB);
;             PG8_WAIT_V(6); PG8_BAR; PG8_MMA(1, 1, At, B1); PG8_BAR;
;             PG8_LDB(B0, 1, 0); PG8_SCHED; PG8_LDA(At, 1, 0); PG8_STAGEA(PG8_SA(0, 1), a2 + hstep, voffA);
;             PG8_WAIT_L(8); PG8_BAR; PG8_WAIT_L(0); PG8_MMA(0, 0, At, B0); PG8_BAR; PG8_SCHED;
;             PG8_LDB(B1, 1, 1); PG8_STAGE(PG8_SB(1, 0), b3, voffB);
;             PG8_BAR; PG8_WAIT_L(0); PG8_MMA(0, 1, At, B1); PG8_BAR;
;             PG8_LDA(At, 1, 1); PG8_STAGEA(PG8_SA(1, 0), a3, voffA);
;             PG8_BAR; PG8_WAIT_L(0); PG8_MMA(1, 0, At, B0); PG8_BAR; PG8_SCHED;
;             PG8_STAGE(PG8_SB(1, 1), b3 + hstepB, voffB);
;             PG8_WAIT_V(6); PG8_BAR; PG8_MMA(1, 1, At, B1); PG8_BAR;
;             }
;         }
;         if constexpr (ALIGN_EPI) { if (wr == 0) PG8_BAR; }
;         if constexpr (!Epi::AFTER_DRAIN) { if (!(Epi::LAST_FUSED && !has_next)) { E(acc, cur, wr, wc, fr, fq); S.done(cur); } }
;         if (!has_next) break;
	s_add_i32 s42, s73, s67
	v_lshl_add_u64 v[206:207], v[206:207], 0, s[16:17]
	s_mov_b32 m0, s42
	ds_read_b128 v[184:187], v172 offset:49152
	ds_read_b128 v[188:191], v172 offset:50176
	ds_read_b128 v[192:195], v172 offset:51200
	ds_read_b128 v[196:199], v172 offset:52224
	ds_read_b128 v[202:205], v172 offset:53248
	ds_read_b128 v[210:213], v172 offset:54272
	ds_read_b128 v[214:217], v172 offset:55296
	ds_read_b128 v[218:221], v172 offset:56320
	global_load_lds_dwordx4 v[206:207], off
	s_add_i32 m0, s42, 0x2000
	s_add_u32 s40, s40, 0x10080
	v_lshl_add_u64 v[206:207], v[222:223], 0, s[16:17]
	s_addc_u32 s41, s41, 0
	s_add_i32 s42, s74, s67
	global_load_lds_dwordx4 v[206:207], off
	v_lshl_add_u64 v[206:207], s[40:41], 0, v[132:133]
	s_mov_b32 m0, s42
	s_nop 0
	global_load_lds_dwordx4 v[206:207], off
	v_lshl_add_u64 v[206:207], s[40:41], 0, v[128:129]
	s_add_i32 m0, s42, 0x2000
	s_nop 0
	global_load_lds_dwordx4 v[206:207], off
	v_lshl_add_u64 v[206:207], v[224:225], 0, s[16:17]
	s_mov_b32 m0, s51
	s_nop 0
	global_load_lds_dwordx4 v[206:207], off
	v_lshl_add_u64 v[206:207], v[226:227], 0, s[16:17]
	s_mov_b32 m0, s52
	s_nop 0
	global_load_lds_dwordx4 v[206:207], off
	s_waitcnt vmcnt(8)
	s_waitcnt lgkmcnt(0)
	s_barrier
	s_waitcnt lgkmcnt(0)
	v_mfma_f32_16x16x32_bf16 v[60:63], v[144:147], v[184:187], v[60:63]
	v_mfma_f32_16x16x32_bf16 v[56:59], v[152:155], v[184:187], v[56:59]
	v_mfma_f32_16x16x32_bf16 v[44:47], v[144:147], v[192:195], v[44:47]
	v_mfma_f32_16x16x32_bf16 v[40:43], v[152:155], v[192:195], v[40:43]
	v_mfma_f32_16x16x32_bf16 v[28:31], v[144:147], v[202:205], v[28:31]
	v_mfma_f32_16x16x32_bf16 v[24:27], v[152:155], v[202:205], v[24:27]
	v_mfma_f32_16x16x32_bf16 v[12:15], v[144:147], v[214:217], v[12:15]
	v_mfma_f32_16x16x32_bf16 v[8:11], v[152:155], v[214:217], v[8:11]
	v_mfma_f32_16x16x32_bf16 v[60:63], v[148:151], v[188:191], v[60:63]
	v_mfma_f32_16x16x32_bf16 v[56:59], v[156:159], v[188:191], v[56:59]
	v_mfma_f32_16x16x32_bf16 v[44:47], v[148:151], v[196:199], v[44:47]
	v_mfma_f32_16x16x32_bf16 v[40:43], v[156:159], v[196:199], v[40:43]
	v_mfma_f32_16x16x32_bf16 v[28:31], v[148:151], v[210:213], v[28:31]
	v_mfma_f32_16x16x32_bf16 v[24:27], v[156:159], v[210:213], v[24:27]
	v_mfma_f32_16x16x32_bf16 v[12:15], v[148:151], v[218:221], v[12:15]
	v_mfma_f32_16x16x32_bf16 v[8:11], v[156:159], v[218:221], v[8:11]
	v_mfma_f32_16x16x32_bf16 v[52:55], v[160:163], v[184:187], v[52:55]
	v_mfma_f32_16x16x32_bf16 v[48:51], v[176:179], v[184:187], v[48:51]
	v_mfma_f32_16x16x32_bf16 v[36:39], v[160:163], v[192:195], v[36:39]
	v_mfma_f32_16x16x32_bf16 v[32:35], v[176:179], v[192:195], v[32:35]
	v_mfma_f32_16x16x32_bf16 v[20:23], v[160:163], v[202:205], v[20:23]
	v_mfma_f32_16x16x32_bf16 v[16:19], v[176:179], v[202:205], v[16:19]
	v_mfma_f32_16x16x32_bf16 v[4:7], v[160:163], v[214:217], v[4:7]
	v_mfma_f32_16x16x32_bf16 v[0:3], v[176:179], v[214:217], v[0:3]
	v_mfma_f32_16x16x32_bf16 v[52:55], v[164:167], v[188:191], v[52:55]
	v_mfma_f32_16x16x32_bf16 v[48:51], v[180:183], v[188:191], v[48:51]
	v_mfma_f32_16x16x32_bf16 v[36:39], v[164:167], v[196:199], v[36:39]
	v_mfma_f32_16x16x32_bf16 v[32:35], v[180:183], v[196:199], v[32:35]
	v_mfma_f32_16x16x32_bf16 v[20:23], v[164:167], v[210:213], v[20:23]
	v_mfma_f32_16x16x32_bf16 v[16:19], v[180:183], v[210:213], v[16:19]
	v_mfma_f32_16x16x32_bf16 v[4:7], v[164:167], v[218:221], v[4:7]
	v_mfma_f32_16x16x32_bf16 v[0:3], v[180:183], v[218:221], v[0:3]
	s_barrier
	s_add_i32 s71, s71, 2
	s_add_u32 s38, s38, 0x100
	s_addc_u32 s39, s39, 0
	s_add_u32 s59, s59, 0x100
	s_addc_u32 s70, s70, 0
	s_cmp_gt_u32 s71, 13
	s_cbranch_scc0 .LBB0_977
	s_setprio 0
	s_and_b64 vcc, exec, s[18:19]
	s_cbranch_vccz .LBB0_980
	s_barrier

;     __host__ __device__ bool next(int i, Unit& u) const { return at((long)i * G + c, u); }
;     __host__ __device__ bool next(int i, Unit& u) const { if (i != 0 || c >= cnt) return false; u.pm = pm0 + c / nN; u.pn = c % nN; u.k0 = 0; u.nt = ntk; return true; }
; #define PG8_STAGEA(bufoff, gbase, voff) do { _Pragma("unroll") for (int _i = 0; _i < 2; ++_i) \
;         __builtin_amdgcn_global_load_lds((const unsigned*)((const char*)(gbase) + (voff)[_i]), (PG8_LAS unsigned*)(lds + (bufoff) + ldsw + _i * 8192), 16, 0, AUXA); } while (0)
; #define PG8_LDA(dst, b, h) do { _Pragma("unroll") for (int m = 0; m < 4; ++m) _Pragma("unroll") for (int k = 0; k < 2; ++k) dst[m][k] = *(const PG8_LAS bf16x8*)(lds + PG8_SA(b, h) + aoff + m * 2048 + k * 1024); } while (0)
; #define PG8_LDB(dst, b, h) do { _Pragma("unroll") for (int n = 0; n < 2; ++n) _Pragma("unroll") for (int k = 0; k < 2; ++k) dst[n][k] = *(const PG8_LAS bf16x8*)(lds + PG8_SB(b, h) + boff + n * 2048 + k * 1024); } while (0)
; #define PG8_MMA(ai, bj, At, Bt) do { __builtin_amdgcn_s_setprio(1); _Pragma("unroll") for (int m = 0; m < 4; ++m) _Pragma("unroll") for (int n = 0; n < 2; ++n) _Pragma("unroll") for (int k = 0; k < 2; ++k) \
;         acc[ai][bj][m][n] = __builtin_amdgcn_mfma_f32_16x16x32_bf16(Bt[n][k], At[m][k], acc[ai][bj][m][n], 0, 0, 0); __builtin_amdgcn_s_setprio(0); } while (0)
;     ...
;         const bool has_next = S.next(ui + 1, nxt);
;         const char* nA = has_next ? (const char*)g.A + (size_t)nxt.pm * tstep + (size_t)nxt.k0 * (BK * 2) : cA; const char* nB = has_next ? (const char*)g.Bt + (size_t)nxt.pn * tstep + (size_t)nxt.k0 * (BK * 2) : cB;
;         const int nt = cur.nt;
;         for (int t = 0; t < nt; t += 2) {
;             const bool last = (t == nt - 2);
;             const char* a1 = cA + (size_t)(t + 1) * kstep;
;             const char* a2 = last ? nA : cA + (size_t)(t + 2) * kstep; const char* b2 = last ? nB : cB + (size_t)(t + 2) * kstep;
;             const char* a3 = a2 + kstep; const char* b3 = b2 + kstep;
;             if (last && has_next) S.a_ready(nxt);
;             if constexpr (SP2) {
;             PG8_LDB(B0, 0, 0); PG8_LDB(B1, 0, 1); PG8_SCHED; PG8_LDA(At, 0, 0); PG8_STAGEA(PG8_SA(1, 1), a1 + hstep, voffA);
;             PG8_WAIT_V(8); PG8_WAIT_L(0); PG8_BAR; PG8_MMA(0, 0, At, B0); PG8_MMA(0, 1, At, B1); PG8_BAR; PG8_SCHED;
.LBB0_1053:
	s_ashr_i32 s23, s22, 31
	s_xor_b64 s[28:29], s[40:41], -1
	s_lshl_b64 s[30:31], s[22:23], 21
	s_add_u32 s13, s4, s30
	s_addc_u32 s23, s5, s31
	s_ashr_i32 s27, s26, 31
	s_lshl_b64 s[34:35], s[26:27], 7
	s_add_u32 s30, s13, s34
	s_addc_u32 s31, s23, s35
	s_and_b64 s[42:43], s[40:41], exec
	s_cselect_b32 s13, s31, s39
	s_cselect_b32 s23, s30, s38
	s_ashr_i32 s25, s24, 31
	s_lshl_b64 s[42:43], s[24:25], 21
	s_add_u32 s25, s3, s42
	s_addc_u32 s27, s47, s43
	s_add_u32 s34, s25, s34
	s_addc_u32 s35, s27, s35
	s_and_b64 s[42:43], s[40:41], exec
	s_cselect_b32 s25, s35, s37
	s_cselect_b32 s27, s34, s36
	s_mov_b32 s73, 2
	s_mov_b64 s[42:43], 0x100
	v_mov_b64_e32 v[130:131], v[144:145]
	v_mov_b64_e32 v[150:151], v[142:143]
	v_readlane_b32 s98, v255, 17
	s_cmp_lg_u32 s98, 1
	s_cbranch_scc1 .Lsprio_6
	s_setprio 1
.Lsprio_6:
.LBB0_1054:
	v_add_u32_e32 v128, s59, v163
	ds_read_b128 v[166:169], v128
	ds_read_b128 v[170:173], v128 offset:1024
	ds_read_b128 v[176:179], v128 offset:2048
	ds_read_b128 v[180:183], v128 offset:3072
	v_add_u32_e32 v128, s70, v163
	ds_read_b128 v[184:187], v128
	ds_read_b128 v[188:191], v128 offset:1024
	ds_read_b128 v[192:195], v128 offset:2048
	ds_read_b128 v[196:199], v128 offset:3072
	s_add_u32 s44, s38, s42
	s_addc_u32 s45, s39, s43
	s_add_u32 s74, s36, s42
	s_addc_u32 s75, s37, s43
	s_cmp_eq_u32 s57, s73
	s_cselect_b32 s51, s13, s45
	s_cselect_b32 s50, s23, s44
	s_cselect_b32 s45, s25, s75
	s_cselect_b32 s44, s27, s74
	v_lshl_add_u64 v[206:207], s[38:39], 0, v[150:151]
	s_add_i32 m0, s49, 0xc000
	ds_read_b128 v[202:205], v164
	ds_read_b128 v[210:213], v164 offset:1024
	ds_read_b128 v[214:217], v164 offset:2048
	ds_read_b128 v[218:221], v164 offset:3072
	ds_read_b128 v[222:225], v164 offset:4096
	ds_read_b128 v[226:229], v164 offset:5120
	ds_read_b128 v[230:233], v164 offset:6144
	ds_read_b128 v[234:237], v164 offset:7168
	global_load_lds_dwordx4 v[206:207], off
	v_lshl_add_u64 v[206:207], s[38:39], 0, v[130:131]
	s_add_i32 m0, s49, 0xe000
	s_nop 0
	global_load_lds_dwordx4 v[206:207], off
	s_waitcnt vmcnt(8)
	s_waitcnt lgkmcnt(0)
	s_barrier
	s_waitcnt lgkmcnt(0)
	v_mfma_f32_16x16x32_bf16 v[124:127], v[166:169], v[202:205], v[124:127]
	v_mfma_f32_16x16x32_bf16 v[120:123], v[176:179], v[202:205], v[120:123]
	v_mfma_f32_16x16x32_bf16 v[108:111], v[166:169], v[214:217], v[108:111]
	v_mfma_f32_16x16x32_bf16 v[104:107], v[176:179], v[214:217], v[104:107]
	v_mfma_f32_16x16x32_bf16 v[92:95], v[166:169], v[222:225], v[92:95]
	v_mfma_f32_16x16x32_bf16 v[88:91], v[176:179], v[222:225], v[88:91]
	v_mfma_f32_16x16x32_bf16 v[76:79], v[166:169], v[230:233], v[76:79]
	v_mfma_f32_16x16x32_bf16 v[72:75], v[176:179], v[230:233], v[72:75]
	v_mfma_f32_16x16x32_bf16 v[124:127], v[170:173], v[210:213], v[124:127]
	v_mfma_f32_16x16x32_bf16 v[120:123], v[180:183], v[210:213], v[120:123]
	v_mfma_f32_16x16x32_bf16 v[108:111], v[170:173], v[218:221], v[108:111]
	v_mfma_f32_16x16x32_bf16 v[104:107], v[180:183], v[218:221], v[104:107]
	v_mfma_f32_16x16x32_bf16 v[92:95], v[170:173], v[226:229], v[92:95]
	v_mfma_f32_16x16x32_bf16 v[88:91], v[180:183], v[226:229], v[88:91]
	v_mfma_f32_16x16x32_bf16 v[76:79], v[170:173], v[234:237], v[76:79]
	v_mfma_f32_16x16x32_bf16 v[72:75], v[180:183], v[234:237], v[72:75]
	v_mfma_f32_16x16x32_bf16 v[116:119], v[184:187], v[202:205], v[116:119]
	v_mfma_f32_16x16x32_bf16 v[112:115], v[192:195], v[202:205], v[112:115]
	v_mfma_f32_16x16x32_bf16 v[100:103], v[184:187], v[214:217], v[100:103]
	v_mfma_f32_16x16x32_bf16 v[96:99], v[192:195], v[214:217], v[96:99]
	v_mfma_f32_16x16x32_bf16 v[84:87], v[184:187], v[222:225], v[84:87]
	v_mfma_f32_16x16x32_bf16 v[80:83], v[192:195], v[222:225], v[80:83]
	v_mfma_f32_16x16x32_bf16 v[68:71], v[184:187], v[230:233], v[68:71]
	v_mfma_f32_16x16x32_bf16 v[64:67], v[192:195], v[230:233], v[64:67]
	v_mfma_f32_16x16x32_bf16 v[116:119], v[188:191], v[210:213], v[116:119]
	v_mfma_f32_16x16x32_bf16 v[112:115], v[196:199], v[210:213], v[112:115]
	v_mfma_f32_16x16x32_bf16 v[100:103], v[188:191], v[218:221], v[100:103]
	v_mfma_f32_16x16x32_bf16 v[96:99], v[196:199], v[218:221], v[96:99]
	v_mfma_f32_16x16x32_bf16 v[84:87], v[188:191], v[226:229], v[84:87]
	v_mfma_f32_16x16x32_bf16 v[80:83], v[196:199], v[226:229], v[80:83]
	v_mfma_f32_16x16x32_bf16 v[68:71], v[188:191], v[234:237], v[68:71]
	v_mfma_f32_16x16x32_bf16 v[64:67], v[196:199], v[234:237], v[64:67]
	s_barrier
	s_add_i32 s74, s59, s67
	v_lshl_add_u64 v[206:207], s[44:45], 0, v[136:137]
	s_mov_b32 m0, s74
	ds_read_b128 v[202:205], v164 offset:16384
	ds_read_b128 v[210:213], v164 offset:17408
	ds_read_b128 v[214:217], v164 offset:18432
	ds_read_b128 v[218:221], v164 offset:19456
	ds_read_b128 v[222:225], v164 offset:20480
	ds_read_b128 v[226:229], v164 offset:21504
	ds_read_b128 v[230:233], v164 offset:22528
	ds_read_b128 v[234:237], v164 offset:23552
	global_load_lds_dwordx4 v[206:207], off
	s_add_i32 m0, s74, 0x2000
	s_add_u32 s74, s44, 0x40000
	v_lshl_add_u64 v[238:239], s[44:45], 0, v[140:141]
	s_addc_u32 s75, s45, 0
	s_add_i32 s76, s70, s67
	global_load_lds_dwordx4 v[238:239], off
	v_lshl_add_u64 v[240:241], s[74:75], 0, v[136:137]
	s_mov_b32 m0, s76
	v_lshl_add_u64 v[242:243], s[50:51], 0, v[138:139]
	global_load_lds_dwordx4 v[240:241], off
	v_lshl_add_u64 v[240:241], s[74:75], 0, v[140:141]
	s_add_i32 m0, s76, 0x2000
	s_nop 0
	global_load_lds_dwordx4 v[240:241], off
	v_lshl_add_u64 v[240:241], s[50:51], 0, v[134:135]
	s_mov_b32 m0, s49
	s_nop 0
	global_load_lds_dwordx4 v[240:241], off
	s_mov_b32 m0, s52
	s_nop 0
	global_load_lds_dwordx4 v[242:243], off
	s_waitcnt vmcnt(8)
	s_waitcnt lgkmcnt(0)
	s_barrier
; #define PG8_STAGE(bufoff, gbase, voff) do { _Pragma("unroll") for (int _i = 0; _i < 2; ++_i) \
;         __builtin_amdgcn_global_load_lds((const unsigned*)((const char*)(gbase) + (voff)[_i]), (PG8_LAS unsigned*)(lds + (bufoff) + ldsw + _i * 8192), 16, 0, 0); } while (0)
; #define PG8_STAGEA(bufoff, gbase, voff) do { _Pragma("unroll") for (int _i = 0; _i < 2; ++_i) \
;         __builtin_amdgcn_global_load_lds((const unsigned*)((const char*)(gbase) + (voff)[_i]), (PG8_LAS unsigned*)(lds + (bufoff) + ldsw + _i * 8192), 16, 0, AUXA); } while (0)
; #define PG8_LDA(dst, b, h) do { _Pragma("unroll") for (int m = 0; m < 4; ++m) _Pragma("unroll") for (int k = 0; k < 2; ++k) dst[m][k] = *(const PG8_LAS bf16x8*)(lds + PG8_SA(b, h) + aoff + m * 2048 + k * 1024); } while (0)
; #define PG8_LDB(dst, b, h) do { _Pragma("unroll") for (int n = 0; n < 2; ++n) _Pragma("unroll") for (int k = 0; k < 2; ++k) dst[n][k] = *(const PG8_LAS bf16x8*)(lds + PG8_SB(b, h) + boff + n * 2048 + k * 1024); } while (0)
; #define PG8_MMA(ai, bj, At, Bt) do { __builtin_amdgcn_s_setprio(1); _Pragma("unroll") for (int m = 0; m < 4; ++m) _Pragma("unroll") for (int n = 0; n < 2; ++n) _Pragma("unroll") for (int k = 0; k < 2; ++k) \
;         acc[ai][bj][m][n] = __builtin_amdgcn_mfma_f32_16x16x32_bf16(Bt[n][k], At[m][k], acc[ai][bj][m][n], 0, 0, 0); __builtin_amdgcn_s_setprio(0); } while (0)
; #define PG8_WAIT_V(n) asm volatile("s_waitcnt vmcnt(" #n ")" ::: "memory")
; #define PG8_WAIT_L(n) asm volatile("s_waitcnt lgkmcnt(" #n ")" ::: "memory")
; #define PG8_BAR __builtin_amdgcn_s_barrier()
; #define PG8_SCHED __builtin_amdgcn_sched_barrier(0)
;     ...
;             PG8_WAIT_V(8); PG8_WAIT_L(0); PG8_BAR; PG8_MMA(0, 0, At, B0); PG8_MMA(0, 1, At, B1); PG8_BAR; PG8_SCHED;
;             PG8_LDA(At, 0, 1); PG8_STAGE(PG8_SB(0, 0), b2, voffB); PG8_STAGE(PG8_SB(0, 1), b2 + hstepB, voffB); PG8_STAGEA(PG8_SA(0, 0), a2, voffA);
;             PG8_WAIT_V(8); PG8_WAIT_L(0); PG8_BAR; PG8_MMA(1, 0, At, B0); PG8_MMA(1, 1, At, B1); PG8_BAR; PG8_SCHED;
;             PG8_LDB(B0, 1, 0); PG8_LDB(B1, 1, 1); PG8_SCHED; PG8_LDA(At, 1, 0); PG8_STAGEA(PG8_SA(0, 1), a2 + hstep, voffA);
;             PG8_WAIT_V(8); PG8_WAIT_L(0); PG8_BAR; PG8_MMA(0, 0, At, B0); PG8_MMA(0, 1, At, B1); PG8_BAR; PG8_SCHED;
	s_waitcnt lgkmcnt(0)
	v_mfma_f32_16x16x32_bf16 v[60:63], v[166:169], v[202:205], v[60:63]
	v_mfma_f32_16x16x32_bf16 v[56:59], v[176:179], v[202:205], v[56:59]
	v_mfma_f32_16x16x32_bf16 v[44:47], v[166:169], v[214:217], v[44:47]
	v_mfma_f32_16x16x32_bf16 v[40:43], v[176:179], v[214:217], v[40:43]
	v_mfma_f32_16x16x32_bf16 v[28:31], v[166:169], v[222:225], v[28:31]
	v_mfma_f32_16x16x32_bf16 v[24:27], v[176:179], v[222:225], v[24:27]
	v_mfma_f32_16x16x32_bf16 v[12:15], v[166:169], v[230:233], v[12:15]
	v_mfma_f32_16x16x32_bf16 v[8:11], v[176:179], v[230:233], v[8:11]
	v_mfma_f32_16x16x32_bf16 v[60:63], v[170:173], v[210:213], v[60:63]
	v_mfma_f32_16x16x32_bf16 v[56:59], v[180:183], v[210:213], v[56:59]
	v_mfma_f32_16x16x32_bf16 v[44:47], v[170:173], v[218:221], v[44:47]
	v_mfma_f32_16x16x32_bf16 v[40:43], v[180:183], v[218:221], v[40:43]
	v_mfma_f32_16x16x32_bf16 v[28:31], v[170:173], v[226:229], v[28:31]
	v_mfma_f32_16x16x32_bf16 v[24:27], v[180:183], v[226:229], v[24:27]
	v_mfma_f32_16x16x32_bf16 v[12:15], v[170:173], v[234:237], v[12:15]
	v_mfma_f32_16x16x32_bf16 v[8:11], v[180:183], v[234:237], v[8:11]
	v_mfma_f32_16x16x32_bf16 v[52:55], v[184:187], v[202:205], v[52:55]
	v_mfma_f32_16x16x32_bf16 v[48:51], v[192:195], v[202:205], v[48:51]
	v_mfma_f32_16x16x32_bf16 v[36:39], v[184:187], v[214:217], v[36:39]
	v_mfma_f32_16x16x32_bf16 v[32:35], v[192:195], v[214:217], v[32:35]
	v_mfma_f32_16x16x32_bf16 v[20:23], v[184:187], v[222:225], v[20:23]
	v_mfma_f32_16x16x32_bf16 v[16:19], v[192:195], v[222:225], v[16:19]
	v_mfma_f32_16x16x32_bf16 v[4:7], v[184:187], v[230:233], v[4:7]
	v_mfma_f32_16x16x32_bf16 v[0:3], v[192:195], v[230:233], v[0:3]
	v_mfma_f32_16x16x32_bf16 v[52:55], v[188:191], v[210:213], v[52:55]
	v_mfma_f32_16x16x32_bf16 v[48:51], v[196:199], v[210:213], v[48:51]
	v_mfma_f32_16x16x32_bf16 v[36:39], v[188:191], v[218:221], v[36:39]
	v_mfma_f32_16x16x32_bf16 v[32:35], v[196:199], v[218:221], v[32:35]
	v_mfma_f32_16x16x32_bf16 v[20:23], v[188:191], v[226:229], v[20:23]
	v_mfma_f32_16x16x32_bf16 v[16:19], v[196:199], v[226:229], v[16:19]
	v_mfma_f32_16x16x32_bf16 v[4:7], v[188:191], v[234:237], v[4:7]
	v_mfma_f32_16x16x32_bf16 v[0:3], v[196:199], v[234:237], v[0:3]
	s_barrier
	s_add_i32 s74, 0, 0x18000
	v_add_u32_e32 v128, s74, v163
	s_add_i32 s75, 0, 0x1c000
	ds_read_b128 v[166:169], v128
	ds_read_b128 v[170:173], v128 offset:1024
	ds_read_b128 v[176:179], v128 offset:2048
	ds_read_b128 v[180:183], v128 offset:3072
	v_add_u32_e32 v128, s75, v163
	ds_read_b128 v[184:187], v128
	ds_read_b128 v[188:191], v128 offset:1024
	ds_read_b128 v[192:195], v128 offset:2048
	ds_read_b128 v[196:199], v128 offset:3072
	s_add_u32 s50, s50, 0x100000
	s_addc_u32 s51, s51, 0
	s_mov_b32 m0, s53
	v_lshl_add_u64 v[244:245], s[50:51], 0, v[134:135]
	ds_read_b128 v[202:205], v164 offset:32768
	ds_read_b128 v[210:213], v164 offset:33792
	ds_read_b128 v[214:217], v164 offset:34816
	ds_read_b128 v[218:221], v164 offset:35840
	ds_read_b128 v[222:225], v164 offset:36864
	ds_read_b128 v[226:229], v164 offset:37888
	ds_read_b128 v[230:233], v164 offset:38912
	ds_read_b128 v[234:237], v164 offset:39936
	global_load_lds_dwordx4 v[244:245], off
	v_lshl_add_u64 v[244:245], s[50:51], 0, v[138:139]
	s_mov_b32 m0, s54
	s_nop 0
	global_load_lds_dwordx4 v[244:245], off
	s_waitcnt vmcnt(8)
	s_waitcnt lgkmcnt(0)
	s_barrier
	s_waitcnt lgkmcnt(0)
	v_mfma_f32_16x16x32_bf16 v[124:127], v[166:169], v[202:205], v[124:127]
	v_mfma_f32_16x16x32_bf16 v[120:123], v[176:179], v[202:205], v[120:123]
	v_mfma_f32_16x16x32_bf16 v[108:111], v[166:169], v[214:217], v[108:111]
	v_mfma_f32_16x16x32_bf16 v[104:107], v[176:179], v[214:217], v[104:107]
	v_mfma_f32_16x16x32_bf16 v[92:95], v[166:169], v[222:225], v[92:95]
	v_mfma_f32_16x16x32_bf16 v[88:91], v[176:179], v[222:225], v[88:91]
	v_mfma_f32_16x16x32_bf16 v[76:79], v[166:169], v[230:233], v[76:79]
	v_mfma_f32_16x16x32_bf16 v[72:75], v[176:179], v[230:233], v[72:75]
	v_mfma_f32_16x16x32_bf16 v[124:127], v[170:173], v[210:213], v[124:127]
	v_mfma_f32_16x16x32_bf16 v[120:123], v[180:183], v[210:213], v[120:123]
	v_mfma_f32_16x16x32_bf16 v[108:111], v[170:173], v[218:221], v[108:111]
	v_mfma_f32_16x16x32_bf16 v[104:107], v[180:183], v[218:221], v[104:107]
	v_mfma_f32_16x16x32_bf16 v[92:95], v[170:173], v[226:229], v[92:95]
	v_mfma_f32_16x16x32_bf16 v[88:91], v[180:183], v[226:229], v[88:91]
	v_mfma_f32_16x16x32_bf16 v[76:79], v[170:173], v[234:237], v[76:79]
	v_mfma_f32_16x16x32_bf16 v[72:75], v[180:183], v[234:237], v[72:75]
	v_mfma_f32_16x16x32_bf16 v[116:119], v[184:187], v[202:205], v[116:119]
	v_mfma_f32_16x16x32_bf16 v[112:115], v[192:195], v[202:205], v[112:115]
	v_mfma_f32_16x16x32_bf16 v[100:103], v[184:187], v[214:217], v[100:103]
	v_mfma_f32_16x16x32_bf16 v[96:99], v[192:195], v[214:217], v[96:99]
	v_mfma_f32_16x16x32_bf16 v[84:87], v[184:187], v[222:225], v[84:87]
	v_mfma_f32_16x16x32_bf16 v[80:83], v[192:195], v[222:225], v[80:83]
	v_mfma_f32_16x16x32_bf16 v[68:71], v[184:187], v[230:233], v[68:71]
	v_mfma_f32_16x16x32_bf16 v[64:67], v[192:195], v[230:233], v[64:67]
	v_mfma_f32_16x16x32_bf16 v[116:119], v[188:191], v[210:213], v[116:119]
	v_mfma_f32_16x16x32_bf16 v[112:115], v[196:199], v[210:213], v[112:115]
	v_mfma_f32_16x16x32_bf16 v[100:103], v[188:191], v[218:221], v[100:103]
	v_mfma_f32_16x16x32_bf16 v[96:99], v[196:199], v[218:221], v[96:99]
	v_mfma_f32_16x16x32_bf16 v[84:87], v[188:191], v[226:229], v[84:87]
	v_mfma_f32_16x16x32_bf16 v[80:83], v[196:199], v[226:229], v[80:83]
	v_mfma_f32_16x16x32_bf16 v[68:71], v[188:191], v[234:237], v[68:71]
	v_mfma_f32_16x16x32_bf16 v[64:67], v[196:199], v[234:237], v[64:67]
	s_barrier
; #define PG8_STAGE(bufoff, gbase, voff) do { _Pragma("unroll") for (int _i = 0; _i < 2; ++_i) \
;         __builtin_amdgcn_global_load_lds((const unsigned*)((const char*)(gbase) + (voff)[_i]), (PG8_LAS unsigned*)(lds + (bufoff) + ldsw + _i * 8192), 16, 0, 0); } while (0)
; #define PG8_STAGEA(bufoff, gbase, voff) do { _Pragma("unroll") for (int _i = 0; _i < 2; ++_i) \
;         __builtin_amdgcn_global_load_lds((const unsigned*)((const char*)(gbase) + (voff)[_i]), (PG8_LAS unsigned*)(lds + (bufoff) + ldsw + _i * 8192), 16, 0, AUXA); } while (0)
; #define PG8_BAR __builtin_amdgcn_s_barrier()
;     ...
;             PG8_LDA(At, 1, 1); PG8_STAGE(PG8_SB(1, 0), b3, voffB); PG8_STAGE(PG8_SB(1, 1), b3 + hstepB, voffB); PG8_STAGEA(PG8_SA(1, 0), a3, voffA);
;             PG8_WAIT_V(8); PG8_WAIT_L(0); PG8_BAR; PG8_MMA(1, 0, At, B0); PG8_MMA(1, 1, At, B1); PG8_BAR; PG8_SCHED;
;             } else {
;             PG8_LDB(B0, 0, 0); PG8_SCHED; PG8_LDA(At, 0, 0); PG8_STAGEA(PG8_SA(1, 1), a1 + hstep, voffA);
;             PG8_WAIT_L(8); PG8_BAR; PG8_WAIT_L(0); PG8_MMA(0, 0, At, B0); PG8_BAR; PG8_SCHED;
;             PG8_LDB(B1, 0, 1); PG8_STAGE(PG8_SB(0, 0), b2, voffB);
;             PG8_BAR; PG8_WAIT_L(0); PG8_MMA(0, 1, At, B1); PG8_BAR;
;             PG8_LDA(At, 0, 1); PG8_STAGEA(PG8_SA(0, 0), a2, voffA);
;             PG8_BAR; PG8_WAIT_L(0); PG8_MMA(1, 0, At, B0); PG8_BAR; PG8_SCHED;
;             PG8_STAGE(PG8_SB(0, 1), b2 + hstepB, voffB);
;             PG8_WAIT_V(6); PG8_BAR; PG8_MMA(1, 1, At, B1); PG8_BAR;
;             PG8_LDB(B0, 1, 0); PG8_SCHED; PG8_LDA(At, 1, 0); PG8_STAGEA(PG8_SA(0, 1), a2 + hstep, voffA);
;             PG8_WAIT_L(8); PG8_BAR; PG8_WAIT_L(0); PG8_MMA(0, 0, At, B0); PG8_BAR; PG8_SCHED;
;             PG8_LDB(B1, 1, 1); PG8_STAGE(PG8_SB(1, 0), b3, voffB);
;             PG8_BAR; PG8_WAIT_L(0); PG8_MMA(0, 1, At, B1); PG8_BAR;
;             PG8_LDA(At, 1, 1); PG8_STAGEA(PG8_SA(1, 0), a3, voffA);
;             PG8_BAR; PG8_WAIT_L(0); PG8_MMA(1, 0, At, B0); PG8_BAR; PG8_SCHED;
;             PG8_STAGE(PG8_SB(1, 1), b3 + hstepB, voffB);
;             PG8_WAIT_V(6); PG8_BAR; PG8_MMA(1, 1, At, B1); PG8_BAR;
;             }
;         }
;         if constexpr (ALIGN_EPI) { if (wr == 0) PG8_BAR; }
;         if constexpr (!Epi::AFTER_DRAIN) { if (!(Epi::LAST_FUSED && !has_next)) { E(acc, cur, wr, wc, fr, fq); S.done(cur); } }
;         if (!has_next) break;
	s_add_i32 s50, s74, s67
	v_lshl_add_u64 v[206:207], v[206:207], 0, s[16:17]
	s_mov_b32 m0, s50
	ds_read_b128 v[202:205], v164 offset:49152
	ds_read_b128 v[210:213], v164 offset:50176
	ds_read_b128 v[214:217], v164 offset:51200
	ds_read_b128 v[218:221], v164 offset:52224
	ds_read_b128 v[222:225], v164 offset:53248
	ds_read_b128 v[226:229], v164 offset:54272
	ds_read_b128 v[230:233], v164 offset:55296
	ds_read_b128 v[234:237], v164 offset:56320
	global_load_lds_dwordx4 v[206:207], off
	s_add_i32 m0, s50, 0x2000
	s_add_u32 s44, s44, 0x40080
	v_lshl_add_u64 v[206:207], v[238:239], 0, s[16:17]
	s_addc_u32 s45, s45, 0
	s_add_i32 s50, s75, s67
	global_load_lds_dwordx4 v[206:207], off
	v_lshl_add_u64 v[206:207], s[44:45], 0, v[136:137]
	s_mov_b32 m0, s50
	s_nop 0
	global_load_lds_dwordx4 v[206:207], off
	v_lshl_add_u64 v[206:207], s[44:45], 0, v[140:141]
	s_add_i32 m0, s50, 0x2000
	s_nop 0
	global_load_lds_dwordx4 v[206:207], off
	v_lshl_add_u64 v[206:207], v[240:241], 0, s[16:17]
	s_mov_b32 m0, s55
	s_nop 0
	global_load_lds_dwordx4 v[206:207], off
	v_lshl_add_u64 v[206:207], v[242:243], 0, s[16:17]
	s_mov_b32 m0, s56
	s_nop 0
	global_load_lds_dwordx4 v[206:207], off
	s_waitcnt vmcnt(8)
	s_waitcnt lgkmcnt(0)
	s_barrier
	s_waitcnt lgkmcnt(0)
	v_mfma_f32_16x16x32_bf16 v[60:63], v[166:169], v[202:205], v[60:63]
	v_mfma_f32_16x16x32_bf16 v[56:59], v[176:179], v[202:205], v[56:59]
	v_mfma_f32_16x16x32_bf16 v[44:47], v[166:169], v[214:217], v[44:47]
	v_mfma_f32_16x16x32_bf16 v[40:43], v[176:179], v[214:217], v[40:43]
	v_mfma_f32_16x16x32_bf16 v[28:31], v[166:169], v[222:225], v[28:31]
	v_mfma_f32_16x16x32_bf16 v[24:27], v[176:179], v[222:225], v[24:27]
	v_mfma_f32_16x16x32_bf16 v[12:15], v[166:169], v[230:233], v[12:15]
	v_mfma_f32_16x16x32_bf16 v[8:11], v[176:179], v[230:233], v[8:11]
	v_mfma_f32_16x16x32_bf16 v[60:63], v[170:173], v[210:213], v[60:63]
	v_mfma_f32_16x16x32_bf16 v[56:59], v[180:183], v[210:213], v[56:59]
	v_mfma_f32_16x16x32_bf16 v[44:47], v[170:173], v[218:221], v[44:47]
	v_mfma_f32_16x16x32_bf16 v[40:43], v[180:183], v[218:221], v[40:43]
	v_mfma_f32_16x16x32_bf16 v[28:31], v[170:173], v[226:229], v[28:31]
	v_mfma_f32_16x16x32_bf16 v[24:27], v[180:183], v[226:229], v[24:27]
	v_mfma_f32_16x16x32_bf16 v[12:15], v[170:173], v[234:237], v[12:15]
	v_mfma_f32_16x16x32_bf16 v[8:11], v[180:183], v[234:237], v[8:11]
	v_mfma_f32_16x16x32_bf16 v[52:55], v[184:187], v[202:205], v[52:55]
	v_mfma_f32_16x16x32_bf16 v[48:51], v[192:195], v[202:205], v[48:51]
	v_mfma_f32_16x16x32_bf16 v[36:39], v[184:187], v[214:217], v[36:39]
	v_mfma_f32_16x16x32_bf16 v[32:35], v[192:195], v[214:217], v[32:35]
	v_mfma_f32_16x16x32_bf16 v[20:23], v[184:187], v[222:225], v[20:23]
	v_mfma_f32_16x16x32_bf16 v[16:19], v[192:195], v[222:225], v[16:19]
	v_mfma_f32_16x16x32_bf16 v[4:7], v[184:187], v[230:233], v[4:7]
	v_mfma_f32_16x16x32_bf16 v[0:3], v[192:195], v[230:233], v[0:3]
	v_mfma_f32_16x16x32_bf16 v[52:55], v[188:191], v[210:213], v[52:55]
	v_mfma_f32_16x16x32_bf16 v[48:51], v[196:199], v[210:213], v[48:51]
	v_mfma_f32_16x16x32_bf16 v[36:39], v[188:191], v[218:221], v[36:39]
	v_mfma_f32_16x16x32_bf16 v[32:35], v[196:199], v[218:221], v[32:35]
	v_mfma_f32_16x16x32_bf16 v[20:23], v[188:191], v[226:229], v[20:23]
	v_mfma_f32_16x16x32_bf16 v[16:19], v[196:199], v[226:229], v[16:19]
	v_mfma_f32_16x16x32_bf16 v[4:7], v[188:191], v[234:237], v[4:7]
	v_mfma_f32_16x16x32_bf16 v[0:3], v[196:199], v[234:237], v[0:3]
	s_barrier
	s_add_i32 s44, s73, 2
	s_add_u32 s42, s42, 0x100
	s_addc_u32 s43, s43, 0
	v_lshl_add_u64 v[150:151], v[150:151], 0, s[20:21]
	v_lshl_add_u64 v[130:131], v[130:131], 0, s[20:21]
	s_cmp_ge_i32 s73, s57
	s_mov_b32 s73, s44
	s_cbranch_scc0 .LBB0_1054
	s_setprio 0
	s_and_b64 vcc, exec, s[18:19]
	s_cbranch_vccz .LBB0_1057
	s_barrier

; __global__ void __launch_bounds__(512, 2) fwd_megakernel(Params P) {
	.amdhsa_kernel _Z14fwd_megakernel6Params
		.amdhsa_group_segment_fixed_size 0
		.amdhsa_private_segment_fixed_size 0
		.amdhsa_kernarg_size 376
		.amdhsa_user_sgpr_count 2
		.amdhsa_user_sgpr_dispatch_ptr 0
		.amdhsa_user_sgpr_queue_ptr 0
		.amdhsa_user_sgpr_kernarg_segment_ptr 1
		.amdhsa_user_sgpr_dispatch_id 0
		.amdhsa_user_sgpr_kernarg_preload_length 0
		.amdhsa_user_sgpr_kernarg_preload_offset 0
		.amdhsa_user_sgpr_private_segment_size 0
		.amdhsa_uses_dynamic_stack 0
		.amdhsa_enable_private_segment 0
		.amdhsa_system_sgpr_workgroup_id_x 1
		.amdhsa_system_sgpr_workgroup_id_y 0
		.amdhsa_system_sgpr_workgroup_id_z 0
		.amdhsa_system_sgpr_workgroup_info 0
		.amdhsa_system_vgpr_workitem_id 0
		.amdhsa_next_free_vgpr 256
		.amdhsa_next_free_sgpr 102
		.amdhsa_accum_offset 256
		.amdhsa_reserve_vcc 1
		.amdhsa_float_round_mode_32 0
		.amdhsa_float_round_mode_16_64 0
		.amdhsa_float_denorm_mode_32 3
		.amdhsa_float_denorm_mode_16_64 3
		.amdhsa_dx10_clamp 1
		.amdhsa_ieee_mode 1
		.amdhsa_fp16_overflow 0
		.amdhsa_tg_split 0
		.amdhsa_exception_fp_ieee_invalid_op 0
		.amdhsa_exception_fp_denorm_src 0
		.amdhsa_exception_fp_ieee_div_zero 0
		.amdhsa_exception_fp_ieee_overflow 0
		.amdhsa_exception_fp_ieee_underflow 0
		.amdhsa_exception_fp_ieee_inexact 0
		.amdhsa_exception_int_div_zero 0
	.end_amdhsa_kernel

amdhsa.kernels:
  - .agpr_count:     0
    .args:
      - .offset:         0
        .size:           120
        .value_kind:     by_value
      - .offset:         120
        .size:           4
        .value_kind:     hidden_block_count_x
      - .offset:         124
        .size:           4
        .value_kind:     hidden_block_count_y
      - .offset:         128
        .size:           4
        .value_kind:     hidden_block_count_z
      - .offset:         132
        .size:           2
        .value_kind:     hidden_group_size_x
      - .offset:         134
        .size:           2
        .value_kind:     hidden_group_size_y
      - .offset:         136
        .size:           2
        .value_kind:     hidden_group_size_z
      - .offset:         138
        .size:           2
        .value_kind:     hidden_remainder_x
      - .offset:         140
        .size:           2
        .value_kind:     hidden_remainder_y
      - .offset:         142
        .size:           2
        .value_kind:     hidden_remainder_z
      - .offset:         160
        .size:           8
        .value_kind:     hidden_global_offset_x
      - .offset:         168
        .size:           8
        .value_kind:     hidden_global_offset_y
      - .offset:         176
        .size:           8
        .value_kind:     hidden_global_offset_z
      - .offset:         184
        .size:           2
        .value_kind:     hidden_grid_dims
      - .offset:         240
        .size:           4
        .value_kind:     hidden_dynamic_lds_size
    .group_segment_fixed_size: 0
    .kernarg_segment_align: 8
    .kernarg_segment_size: 376
    .language:       OpenCL C
    .language_version:
      - 2
      - 0
    .max_flat_workgroup_size: 512
    .name:           _Z14fwd_megakernel6Params
    .private_segment_fixed_size: 0
    .sgpr_count:     108
    .sgpr_spill_count: 22
    .symbol:         _Z14fwd_megakernel6Params.kd
    .uniform_work_group_size: 1
    .uses_dynamic_stack: false
    .vgpr_count:     256
    .vgpr_spill_count: 0
    .wavefront_size: 64
